# K-loop load segments: the LDS-DMA pair issued right after the first ds_read of the segment, remaining ds_reads after the pair (DMA-first ordering), on top of v053
# speedup vs baseline: 1.0057x; 1.0057x over previous
; #define PG8_STAGE(bufoff, gbase, voff) do { _Pragma("unroll") for (int _i = 0; _i < 2; ++_i) \
;         __builtin_amdgcn_global_load_lds((const unsigned*)((const char*)(gbase) + (voff)[_i]), (LAS unsigned*)(lds + (bufoff) + ldsw + _i * 8192), 16, 0, 0); } while (0)
; #define PG8_LDA(dst, b, h) do { _Pragma("unroll") for (int m = 0; m < 4; ++m) _Pragma("unroll") for (int k = 0; k < 2; ++k) dst[m][k] = *(const LAS bf16x8*)(lds + PG8_SA(b, h) + aoff + m * 2048 + k * 1024); } while (0)
; #define PG8_LDB(dst, b, h) do { _Pragma("unroll") for (int n = 0; n < 2; ++n) _Pragma("unroll") for (int k = 0; k < 2; ++k) dst[n][k] = *(const LAS bf16x8*)(lds + PG8_SB(b, h) + boff + n * 2048 + k * 1024); } while (0)
; #define PG8_MMA(ai, bj, At, Bt) do { __builtin_amdgcn_s_setprio(1); _Pragma("unroll") for (int m = 0; m < 4; ++m) _Pragma("unroll") for (int n = 0; n < 2; ++n) _Pragma("unroll") for (int k = 0; k < 2; ++k) \
;         acc[ai][bj][m][n] = __builtin_amdgcn_mfma_f32_16x16x32_bf16(Bt[n][k], At[m][k], acc[ai][bj][m][n], 0, 0, 0); __builtin_amdgcn_s_setprio(0); } while (0)
; #define PG8_WAIT_V(n) asm volatile("s_waitcnt vmcnt(" #n ")" ::: "memory")
; #define PG8_WAIT_L(n) asm volatile("s_waitcnt lgkmcnt(" #n ")" ::: "memory")
; #define PG8_BAR __builtin_amdgcn_s_barrier()
; #define PG8_SCHED __builtin_amdgcn_sched_barrier(0)
; template <int MODE, class EpiT, class Sched>
; __device__ __forceinline__ void gemm_phase(LAS unsigned char* lds, const Gemm g, const Sched& S, const EpiT& E) {
;     ...
;             PG8_LDB(B0, 0, 0); PG8_SCHED; PG8_LDA(At, 0, 0); PG8_STAGE(PG8_SA(1, 1), a1 + hstep, voffA);
;             PG8_WAIT_L(8); PG8_BAR; PG8_WAIT_L(0); PG8_MMA(0, 0, At, B0); PG8_BAR; PG8_SCHED;
;             PG8_LDB(B1, 0, 1); PG8_STAGE(PG8_SB(0, 0), b2, voffB);
;             PG8_BAR; PG8_WAIT_L(0); PG8_MMA(0, 1, At, B1); PG8_BAR;
;             PG8_LDA(At, 0, 1); PG8_STAGE(PG8_SA(0, 0), a2, voffA);
;             PG8_BAR; PG8_WAIT_L(0); PG8_MMA(1, 0, At, B0); PG8_BAR; PG8_SCHED;
;             PG8_STAGE(PG8_SB(0, 1), b2 + hstep, voffB);
;             PG8_WAIT_V(6); PG8_BAR; PG8_MMA(1, 1, At, B1); PG8_BAR;
.LBB0_115:
	s_add_i32 s58, s52, 2
	s_add_u32 s59, s44, 0x80
	s_addc_u32 s53, s45, 0
	s_add_u32 s100, s44, s78
	s_addc_u32 s101, s45, 0
	s_add_i32 s91, 0, 0x10000
	ds_read_b128 v[70:73], v249
	ds_read_b128 v[74:77], v249 offset:1024
	ds_read_b128 v[82:85], v249 offset:2048
	ds_read_b128 v[86:89], v249 offset:3072
	s_cmp_eq_u32 s57, s52
	s_cselect_b32 s52, s4, s59
	s_cselect_b32 s53, s5, s53
	s_cselect_b32 s75, s47, vcc_hi
	s_cselect_b32 s74, s46, vcc_lo
	s_add_i32 m0, s20, 0xc000
	ds_read_b128 v[138:141], v194
	global_load_lds_dwordx4 v0, s[100:101]
	s_add_i32 m0, s20, 0xe000
	ds_read_b128 v[184:187], v194 offset:7168
	global_load_lds_dwordx4 v174, s[100:101]
	ds_read_b128 v[142:145], v194 offset:1024
	ds_read_b128 v[146:149], v194 offset:2048
	ds_read_b128 v[154:157], v194 offset:3072
	ds_read_b128 v[162:165], v194 offset:4096
	ds_read_b128 v[166:169], v194 offset:5120
	ds_read_b128 v[170:173], v194 offset:6144
	s_waitcnt lgkmcnt(8)
	s_barrier
	s_waitcnt lgkmcnt(0)
	v_mfma_f32_16x16x32_bf16 v[158:161], v[70:73], v[138:141], v[158:161]
	v_mfma_f32_16x16x32_bf16 v[150:153], v[82:85], v[138:141], v[150:153]
	v_mfma_f32_16x16x32_bf16 v[126:129], v[70:73], v[146:149], v[126:129]
	v_mfma_f32_16x16x32_bf16 v[122:125], v[82:85], v[146:149], v[122:125]
	v_mfma_f32_16x16x32_bf16 v[110:113], v[70:73], v[162:165], v[110:113]
	v_mfma_f32_16x16x32_bf16 v[106:109], v[82:85], v[162:165], v[106:109]
	v_mfma_f32_16x16x32_bf16 v[94:97], v[70:73], v[170:173], v[94:97]
	v_mfma_f32_16x16x32_bf16 v[90:93], v[82:85], v[170:173], v[90:93]
	v_mfma_f32_16x16x32_bf16 v[158:161], v[74:77], v[142:145], v[158:161]
	v_mfma_f32_16x16x32_bf16 v[150:153], v[86:89], v[142:145], v[150:153]
	v_mfma_f32_16x16x32_bf16 v[126:129], v[74:77], v[154:157], v[126:129]
	v_mfma_f32_16x16x32_bf16 v[122:125], v[86:89], v[154:157], v[122:125]
	v_mfma_f32_16x16x32_bf16 v[110:113], v[74:77], v[166:169], v[110:113]
	v_mfma_f32_16x16x32_bf16 v[106:109], v[86:89], v[166:169], v[106:109]
	v_mfma_f32_16x16x32_bf16 v[94:97], v[74:77], v[184:187], v[94:97]
	v_mfma_f32_16x16x32_bf16 v[90:93], v[86:89], v[184:187], v[90:93]
	s_barrier
	s_add_i32 s59, 0, 0x14000
	s_add_i32 s91, s91, s9
	s_add_u32 s98, s74, 0x80
	s_addc_u32 s99, s75, 0
	s_mov_b32 m0, s91
	ds_read_b128 v[188:191], v249 offset:16384
	global_load_lds_dwordx4 v0, s[74:75]
	s_add_i32 m0, s91, 0x2000
	ds_read_b128 v[224:227], v249 offset:19456
	global_load_lds_dwordx4 v174, s[74:75]
	ds_read_b128 v[196:199], v249 offset:17408
	ds_read_b128 v[220:223], v249 offset:18432
	s_barrier
	s_waitcnt lgkmcnt(0)
	v_mfma_f32_16x16x32_bf16 v[134:137], v[188:191], v[138:141], v[134:137]
	v_mfma_f32_16x16x32_bf16 v[130:133], v[220:223], v[138:141], v[130:133]
	v_mfma_f32_16x16x32_bf16 v[118:121], v[188:191], v[146:149], v[118:121]
	v_mfma_f32_16x16x32_bf16 v[114:117], v[220:223], v[146:149], v[114:117]
	v_mfma_f32_16x16x32_bf16 v[102:105], v[188:191], v[162:165], v[102:105]
	v_mfma_f32_16x16x32_bf16 v[98:101], v[220:223], v[162:165], v[98:101]
	v_mfma_f32_16x16x32_bf16 v[78:81], v[188:191], v[170:173], v[78:81]
	v_mfma_f32_16x16x32_bf16 v[66:69], v[220:223], v[170:173], v[66:69]
	v_mfma_f32_16x16x32_bf16 v[134:137], v[196:199], v[142:145], v[134:137]
	v_mfma_f32_16x16x32_bf16 v[130:133], v[224:227], v[142:145], v[130:133]
	v_mfma_f32_16x16x32_bf16 v[118:121], v[196:199], v[154:157], v[118:121]
	v_mfma_f32_16x16x32_bf16 v[114:117], v[224:227], v[154:157], v[114:117]
	v_mfma_f32_16x16x32_bf16 v[102:105], v[196:199], v[166:169], v[102:105]
	v_mfma_f32_16x16x32_bf16 v[98:101], v[224:227], v[166:169], v[98:101]
	v_mfma_f32_16x16x32_bf16 v[78:81], v[196:199], v[184:187], v[78:81]
	v_mfma_f32_16x16x32_bf16 v[66:69], v[224:227], v[184:187], v[66:69]
	s_barrier
	s_mov_b32 m0, s20
	s_add_u32 s100, s52, 0x80
	s_addc_u32 s101, s53, 0
	ds_read_b128 v[138:141], v194 offset:16384
	global_load_lds_dwordx4 v0, s[52:53]
	s_mov_b32 m0, s21
	ds_read_b128 v[184:187], v194 offset:23552
	global_load_lds_dwordx4 v174, s[52:53]
	ds_read_b128 v[142:145], v194 offset:17408
	ds_read_b128 v[146:149], v194 offset:18432
	ds_read_b128 v[154:157], v194 offset:19456
	ds_read_b128 v[162:165], v194 offset:20480
	ds_read_b128 v[166:169], v194 offset:21504
	ds_read_b128 v[170:173], v194 offset:22528
	s_barrier
	s_waitcnt lgkmcnt(0)
	v_mfma_f32_16x16x32_bf16 v[62:65], v[70:73], v[138:141], v[62:65]
	v_mfma_f32_16x16x32_bf16 v[58:61], v[82:85], v[138:141], v[58:61]
	v_mfma_f32_16x16x32_bf16 v[46:49], v[70:73], v[146:149], v[46:49]
	v_mfma_f32_16x16x32_bf16 v[42:45], v[82:85], v[146:149], v[42:45]
	v_mfma_f32_16x16x32_bf16 v[30:33], v[70:73], v[162:165], v[30:33]
	v_mfma_f32_16x16x32_bf16 v[26:29], v[82:85], v[162:165], v[26:29]
	v_mfma_f32_16x16x32_bf16 v[14:17], v[70:73], v[170:173], v[14:17]
	v_mfma_f32_16x16x32_bf16 v[10:13], v[82:85], v[170:173], v[10:13]
	v_mfma_f32_16x16x32_bf16 v[62:65], v[74:77], v[142:145], v[62:65]
	v_mfma_f32_16x16x32_bf16 v[58:61], v[86:89], v[142:145], v[58:61]
	v_mfma_f32_16x16x32_bf16 v[46:49], v[74:77], v[154:157], v[46:49]
	v_mfma_f32_16x16x32_bf16 v[42:45], v[86:89], v[154:157], v[42:45]
	v_mfma_f32_16x16x32_bf16 v[30:33], v[74:77], v[166:169], v[30:33]
	v_mfma_f32_16x16x32_bf16 v[26:29], v[86:89], v[166:169], v[26:29]
	v_mfma_f32_16x16x32_bf16 v[14:17], v[74:77], v[184:187], v[14:17]
	v_mfma_f32_16x16x32_bf16 v[10:13], v[86:89], v[184:187], v[10:13]
	s_barrier
	s_add_u32 s74, s74, s78
	s_addc_u32 s75, s75, 0
	s_add_i32 s59, s59, s9
	s_mov_b32 m0, s59
	s_nop 0
	global_load_lds_dwordx4 v0, s[74:75]
	s_add_i32 m0, s59, 0x2000
	s_nop 0
	global_load_lds_dwordx4 v174, s[74:75]
	s_waitcnt vmcnt(6)
	s_barrier
; #define PG8_STAGE(bufoff, gbase, voff) do { _Pragma("unroll") for (int _i = 0; _i < 2; ++_i) \
;         __builtin_amdgcn_global_load_lds((const unsigned*)((const char*)(gbase) + (voff)[_i]), (LAS unsigned*)(lds + (bufoff) + ldsw + _i * 8192), 16, 0, 0); } while (0)
; #define PG8_LDA(dst, b, h) do { _Pragma("unroll") for (int m = 0; m < 4; ++m) _Pragma("unroll") for (int k = 0; k < 2; ++k) dst[m][k] = *(const LAS bf16x8*)(lds + PG8_SA(b, h) + aoff + m * 2048 + k * 1024); } while (0)
; #define PG8_LDB(dst, b, h) do { _Pragma("unroll") for (int n = 0; n < 2; ++n) _Pragma("unroll") for (int k = 0; k < 2; ++k) dst[n][k] = *(const LAS bf16x8*)(lds + PG8_SB(b, h) + boff + n * 2048 + k * 1024); } while (0)
; #define PG8_MMA(ai, bj, At, Bt) do { __builtin_amdgcn_s_setprio(1); _Pragma("unroll") for (int m = 0; m < 4; ++m) _Pragma("unroll") for (int n = 0; n < 2; ++n) _Pragma("unroll") for (int k = 0; k < 2; ++k) \
;         acc[ai][bj][m][n] = __builtin_amdgcn_mfma_f32_16x16x32_bf16(Bt[n][k], At[m][k], acc[ai][bj][m][n], 0, 0, 0); __builtin_amdgcn_s_setprio(0); } while (0)
; #define PG8_WAIT_V(n) asm volatile("s_waitcnt vmcnt(" #n ")" ::: "memory")
; #define PG8_WAIT_L(n) asm volatile("s_waitcnt lgkmcnt(" #n ")" ::: "memory")
; #define PG8_BAR __builtin_amdgcn_s_barrier()
; #define PG8_SCHED __builtin_amdgcn_sched_barrier(0)
; template <int MODE, class EpiT, class Sched>
; __device__ __forceinline__ void gemm_phase(LAS unsigned char* lds, const Gemm g, const Sched& S, const EpiT& E) {
;     ...
;             PG8_WAIT_V(6); PG8_BAR; PG8_MMA(1, 1, At, B1); PG8_BAR;
;             PG8_LDB(B0, 1, 0); PG8_SCHED; PG8_LDA(At, 1, 0); PG8_STAGE(PG8_SA(0, 1), a2 + hstep, voffA);
;             PG8_WAIT_L(8); PG8_BAR; PG8_WAIT_L(0); PG8_MMA(0, 0, At, B0); PG8_BAR; PG8_SCHED;
;             PG8_LDB(B1, 1, 1); PG8_STAGE(PG8_SB(1, 0), b3, voffB);
;             PG8_BAR; PG8_WAIT_L(0); PG8_MMA(0, 1, At, B1); PG8_BAR;
;             PG8_LDA(At, 1, 1); PG8_STAGE(PG8_SA(1, 0), a3, voffA);
;             PG8_BAR; PG8_WAIT_L(0); PG8_MMA(1, 0, At, B0); PG8_BAR; PG8_SCHED;
	v_mfma_f32_16x16x32_bf16 v[54:57], v[188:191], v[138:141], v[54:57]
	v_mfma_f32_16x16x32_bf16 v[50:53], v[220:223], v[138:141], v[50:53]
	v_mfma_f32_16x16x32_bf16 v[38:41], v[188:191], v[146:149], v[38:41]
	v_mfma_f32_16x16x32_bf16 v[34:37], v[220:223], v[146:149], v[34:37]
	v_mfma_f32_16x16x32_bf16 v[22:25], v[188:191], v[162:165], v[22:25]
	v_mfma_f32_16x16x32_bf16 v[18:21], v[220:223], v[162:165], v[18:21]
	v_mfma_f32_16x16x32_bf16 v[6:9], v[188:191], v[170:173], v[6:9]
	v_mfma_f32_16x16x32_bf16 v[2:5], v[220:223], v[170:173], v[2:5]
	v_mfma_f32_16x16x32_bf16 v[54:57], v[196:199], v[142:145], v[54:57]
	v_mfma_f32_16x16x32_bf16 v[50:53], v[224:227], v[142:145], v[50:53]
	v_mfma_f32_16x16x32_bf16 v[38:41], v[196:199], v[154:157], v[38:41]
	v_mfma_f32_16x16x32_bf16 v[34:37], v[224:227], v[154:157], v[34:37]
	v_mfma_f32_16x16x32_bf16 v[22:25], v[196:199], v[166:169], v[22:25]
	v_mfma_f32_16x16x32_bf16 v[18:21], v[224:227], v[166:169], v[18:21]
	v_mfma_f32_16x16x32_bf16 v[6:9], v[196:199], v[184:187], v[6:9]
	v_mfma_f32_16x16x32_bf16 v[2:5], v[224:227], v[184:187], v[2:5]
	s_barrier
	s_add_i32 s59, 0, 0x18000
	ds_read_b128 v[70:73], v249 offset:32768
	ds_read_b128 v[74:77], v249 offset:33792
	ds_read_b128 v[82:85], v249 offset:34816
	ds_read_b128 v[86:89], v249 offset:35840
	s_add_u32 s52, s52, s78
	s_addc_u32 s53, s53, 0
	s_mov_b32 m0, s22
	ds_read_b128 v[138:141], v194 offset:32768
	global_load_lds_dwordx4 v0, s[52:53]
	s_mov_b32 m0, s23
	ds_read_b128 v[184:187], v194 offset:39936
	global_load_lds_dwordx4 v174, s[52:53]
	ds_read_b128 v[142:145], v194 offset:33792
	ds_read_b128 v[146:149], v194 offset:34816
	ds_read_b128 v[154:157], v194 offset:35840
	ds_read_b128 v[162:165], v194 offset:36864
	ds_read_b128 v[166:169], v194 offset:37888
	ds_read_b128 v[170:173], v194 offset:38912
	s_waitcnt lgkmcnt(8)
	s_barrier
	s_waitcnt lgkmcnt(0)
	v_mfma_f32_16x16x32_bf16 v[158:161], v[70:73], v[138:141], v[158:161]
	v_mfma_f32_16x16x32_bf16 v[150:153], v[82:85], v[138:141], v[150:153]
	v_mfma_f32_16x16x32_bf16 v[126:129], v[70:73], v[146:149], v[126:129]
	v_mfma_f32_16x16x32_bf16 v[122:125], v[82:85], v[146:149], v[122:125]
	v_mfma_f32_16x16x32_bf16 v[110:113], v[70:73], v[162:165], v[110:113]
	v_mfma_f32_16x16x32_bf16 v[106:109], v[82:85], v[162:165], v[106:109]
	v_mfma_f32_16x16x32_bf16 v[94:97], v[70:73], v[170:173], v[94:97]
	v_mfma_f32_16x16x32_bf16 v[90:93], v[82:85], v[170:173], v[90:93]
	v_mfma_f32_16x16x32_bf16 v[158:161], v[74:77], v[142:145], v[158:161]
	v_mfma_f32_16x16x32_bf16 v[150:153], v[86:89], v[142:145], v[150:153]
	v_mfma_f32_16x16x32_bf16 v[126:129], v[74:77], v[154:157], v[126:129]
	v_mfma_f32_16x16x32_bf16 v[122:125], v[86:89], v[154:157], v[122:125]
	v_mfma_f32_16x16x32_bf16 v[110:113], v[74:77], v[166:169], v[110:113]
	v_mfma_f32_16x16x32_bf16 v[106:109], v[86:89], v[166:169], v[106:109]
	v_mfma_f32_16x16x32_bf16 v[94:97], v[74:77], v[184:187], v[94:97]
	v_mfma_f32_16x16x32_bf16 v[90:93], v[86:89], v[184:187], v[90:93]
	s_barrier
	s_add_i32 s52, 0, 0x1c000
	s_add_i32 s53, s59, s9
	s_mov_b32 m0, s53
	ds_read_b128 v[188:191], v249 offset:49152
	global_load_lds_dwordx4 v0, s[98:99]
	s_add_i32 m0, s53, 0x2000
	ds_read_b128 v[224:227], v249 offset:52224
	global_load_lds_dwordx4 v174, s[98:99]
	ds_read_b128 v[196:199], v249 offset:50176
	ds_read_b128 v[220:223], v249 offset:51200
	s_barrier
	s_waitcnt lgkmcnt(0)
	v_mfma_f32_16x16x32_bf16 v[134:137], v[188:191], v[138:141], v[134:137]
	v_mfma_f32_16x16x32_bf16 v[130:133], v[220:223], v[138:141], v[130:133]
	v_mfma_f32_16x16x32_bf16 v[118:121], v[188:191], v[146:149], v[118:121]
	v_mfma_f32_16x16x32_bf16 v[114:117], v[220:223], v[146:149], v[114:117]
	v_mfma_f32_16x16x32_bf16 v[102:105], v[188:191], v[162:165], v[102:105]
	v_mfma_f32_16x16x32_bf16 v[98:101], v[220:223], v[162:165], v[98:101]
	v_mfma_f32_16x16x32_bf16 v[78:81], v[188:191], v[170:173], v[78:81]
	v_mfma_f32_16x16x32_bf16 v[66:69], v[220:223], v[170:173], v[66:69]
	v_mfma_f32_16x16x32_bf16 v[134:137], v[196:199], v[142:145], v[134:137]
	v_mfma_f32_16x16x32_bf16 v[130:133], v[224:227], v[142:145], v[130:133]
	v_mfma_f32_16x16x32_bf16 v[118:121], v[196:199], v[154:157], v[118:121]
	v_mfma_f32_16x16x32_bf16 v[114:117], v[224:227], v[154:157], v[114:117]
	v_mfma_f32_16x16x32_bf16 v[102:105], v[196:199], v[166:169], v[102:105]
	v_mfma_f32_16x16x32_bf16 v[98:101], v[224:227], v[166:169], v[98:101]
	v_mfma_f32_16x16x32_bf16 v[78:81], v[196:199], v[184:187], v[78:81]
	v_mfma_f32_16x16x32_bf16 v[66:69], v[224:227], v[184:187], v[66:69]
	s_barrier
; #define PG8_STAGE(bufoff, gbase, voff) do { _Pragma("unroll") for (int _i = 0; _i < 2; ++_i) \
;         __builtin_amdgcn_global_load_lds((const unsigned*)((const char*)(gbase) + (voff)[_i]), (LAS unsigned*)(lds + (bufoff) + ldsw + _i * 8192), 16, 0, 0); } while (0)
; #define PG8_LDA(dst, b, h) do { _Pragma("unroll") for (int m = 0; m < 4; ++m) _Pragma("unroll") for (int k = 0; k < 2; ++k) dst[m][k] = *(const LAS bf16x8*)(lds + PG8_SA(b, h) + aoff + m * 2048 + k * 1024); } while (0)
; #define PG8_LDB(dst, b, h) do { _Pragma("unroll") for (int n = 0; n < 2; ++n) _Pragma("unroll") for (int k = 0; k < 2; ++k) dst[n][k] = *(const LAS bf16x8*)(lds + PG8_SB(b, h) + boff + n * 2048 + k * 1024); } while (0)
; #define PG8_MMA(ai, bj, At, Bt) do { __builtin_amdgcn_s_setprio(1); _Pragma("unroll") for (int m = 0; m < 4; ++m) _Pragma("unroll") for (int n = 0; n < 2; ++n) _Pragma("unroll") for (int k = 0; k < 2; ++k) \
;         acc[ai][bj][m][n] = __builtin_amdgcn_mfma_f32_16x16x32_bf16(Bt[n][k], At[m][k], acc[ai][bj][m][n], 0, 0, 0); __builtin_amdgcn_s_setprio(0); } while (0)
; #define PG8_WAIT_V(n) asm volatile("s_waitcnt vmcnt(" #n ")" ::: "memory")
; #define PG8_WAIT_L(n) asm volatile("s_waitcnt lgkmcnt(" #n ")" ::: "memory")
; #define PG8_BAR __builtin_amdgcn_s_barrier()
; #define PG8_SCHED __builtin_amdgcn_sched_barrier(0)
; template <int MODE, class EpiT, class Sched>
; __device__ __forceinline__ void gemm_phase(LAS unsigned char* lds, const Gemm g, const Sched& S, const EpiT& E) {
;     ...
;             PG8_LDB(B1, 1, 1); PG8_STAGE(PG8_SB(1, 0), b3, voffB);
;             PG8_BAR; PG8_WAIT_L(0); PG8_MMA(0, 1, At, B1); PG8_BAR;
;             PG8_LDA(At, 1, 1); PG8_STAGE(PG8_SA(1, 0), a3, voffA);
;             PG8_BAR; PG8_WAIT_L(0); PG8_MMA(1, 0, At, B0); PG8_BAR; PG8_SCHED;
;             PG8_STAGE(PG8_SB(1, 1), b3 + hstep, voffB);
;             PG8_WAIT_V(6); PG8_BAR; PG8_MMA(1, 1, At, B1); PG8_BAR;
;         }
;         E.template run<MODE>(acc, cur, wr, wc, fr, fq, SC + ui * 256);
;         if (!has_next) break;
	s_mov_b32 m0, s51
	ds_read_b128 v[138:141], v194 offset:49152
	global_load_lds_dwordx4 v0, s[100:101]
	s_mov_b32 m0, s56
	ds_read_b128 v[184:187], v194 offset:56320
	global_load_lds_dwordx4 v174, s[100:101]
	ds_read_b128 v[142:145], v194 offset:50176
	ds_read_b128 v[146:149], v194 offset:51200
	ds_read_b128 v[154:157], v194 offset:52224
	ds_read_b128 v[162:165], v194 offset:53248
	ds_read_b128 v[166:169], v194 offset:54272
	ds_read_b128 v[170:173], v194 offset:55296
	s_barrier
	s_waitcnt lgkmcnt(0)
	v_mfma_f32_16x16x32_bf16 v[62:65], v[70:73], v[138:141], v[62:65]
	v_mfma_f32_16x16x32_bf16 v[58:61], v[82:85], v[138:141], v[58:61]
	v_mfma_f32_16x16x32_bf16 v[46:49], v[70:73], v[146:149], v[46:49]
	v_mfma_f32_16x16x32_bf16 v[42:45], v[82:85], v[146:149], v[42:45]
	v_mfma_f32_16x16x32_bf16 v[30:33], v[70:73], v[162:165], v[30:33]
	v_mfma_f32_16x16x32_bf16 v[26:29], v[82:85], v[162:165], v[26:29]
	v_mfma_f32_16x16x32_bf16 v[14:17], v[70:73], v[170:173], v[14:17]
	v_mfma_f32_16x16x32_bf16 v[10:13], v[82:85], v[170:173], v[10:13]
	v_mfma_f32_16x16x32_bf16 v[62:65], v[74:77], v[142:145], v[62:65]
	v_mfma_f32_16x16x32_bf16 v[58:61], v[86:89], v[142:145], v[58:61]
	v_mfma_f32_16x16x32_bf16 v[46:49], v[74:77], v[154:157], v[46:49]
	v_mfma_f32_16x16x32_bf16 v[42:45], v[86:89], v[154:157], v[42:45]
	v_mfma_f32_16x16x32_bf16 v[30:33], v[74:77], v[166:169], v[30:33]
	v_mfma_f32_16x16x32_bf16 v[26:29], v[86:89], v[166:169], v[26:29]
	v_mfma_f32_16x16x32_bf16 v[14:17], v[74:77], v[184:187], v[14:17]
	v_mfma_f32_16x16x32_bf16 v[10:13], v[86:89], v[184:187], v[10:13]
	s_barrier
	s_add_i32 s52, s52, s9
	s_add_u32 s98, s98, s78
	s_addc_u32 s99, s99, 0
	s_mov_b32 m0, s52
	s_nop 0
	global_load_lds_dwordx4 v0, s[98:99]
	s_add_i32 m0, s52, 0x2000
	s_nop 0
	global_load_lds_dwordx4 v174, s[98:99]
	s_waitcnt vmcnt(6)
	s_barrier
	v_mfma_f32_16x16x32_bf16 v[54:57], v[188:191], v[138:141], v[54:57]
	v_mfma_f32_16x16x32_bf16 v[50:53], v[220:223], v[138:141], v[50:53]
	v_mfma_f32_16x16x32_bf16 v[38:41], v[188:191], v[146:149], v[38:41]
	v_mfma_f32_16x16x32_bf16 v[34:37], v[220:223], v[146:149], v[34:37]
	v_mfma_f32_16x16x32_bf16 v[22:25], v[188:191], v[162:165], v[22:25]
	v_mfma_f32_16x16x32_bf16 v[18:21], v[220:223], v[162:165], v[18:21]
	v_mfma_f32_16x16x32_bf16 v[6:9], v[188:191], v[170:173], v[6:9]
	v_mfma_f32_16x16x32_bf16 v[2:5], v[220:223], v[170:173], v[2:5]
	v_mfma_f32_16x16x32_bf16 v[54:57], v[196:199], v[142:145], v[54:57]
	v_mfma_f32_16x16x32_bf16 v[50:53], v[224:227], v[142:145], v[50:53]
	v_mfma_f32_16x16x32_bf16 v[38:41], v[196:199], v[154:157], v[38:41]
	v_mfma_f32_16x16x32_bf16 v[34:37], v[224:227], v[154:157], v[34:37]
	v_mfma_f32_16x16x32_bf16 v[22:25], v[196:199], v[166:169], v[22:25]
	v_mfma_f32_16x16x32_bf16 v[18:21], v[224:227], v[166:169], v[18:21]
	v_mfma_f32_16x16x32_bf16 v[6:9], v[196:199], v[184:187], v[6:9]
	v_mfma_f32_16x16x32_bf16 v[2:5], v[224:227], v[184:187], v[2:5]
	s_barrier
	s_add_u32 s44, s44, 0x100
	s_addc_u32 s45, s45, 0
	s_add_u32 vcc_lo, vcc_lo, 0x100
	s_addc_u32 vcc_hi, vcc_hi, 0
	s_cmp_ge_u32 s58, s50
	s_mov_b32 s52, s58
	s_cbranch_scc0 .LBB0_115
	v_lshl_or_b32 v184, s24, 8, v193
	v_ashrrev_i32_e32 v185, 31, v184
	v_mov_b32_e32 v74, 0
	v_cndmask_b32_e64 v70, 0, 1, s[68:69]
	v_lshl_add_u64 v[138:139], v[184:185], 2, s[12:13]
	v_cmp_ne_u32_e64 s[44:45], 1, v70
	s_andn2_b64 vcc, exec, s[68:69]
	v_mov_b32_e32 v86, 0
	v_mov_b32_e32 v87, v74
	v_mov_b32_e32 v186, 0
	v_mov_b32_e32 v187, v74
	s_cbranch_vccnz .LBB0_118
	global_load_dwordx4 v[86:89], v[138:139], off
	s_waitcnt vmcnt(0)
	v_mov_b32_e32 v186, v88
	v_mov_b32_e32 v187, v89

; #define PG8_STAGE(bufoff, gbase, voff) do { _Pragma("unroll") for (int _i = 0; _i < 2; ++_i) \
;         __builtin_amdgcn_global_load_lds((const unsigned*)((const char*)(gbase) + (voff)[_i]), (LAS unsigned*)(lds + (bufoff) + ldsw + _i * 8192), 16, 0, 0); } while (0)
; #define PG8_LDA(dst, b, h) do { _Pragma("unroll") for (int m = 0; m < 4; ++m) _Pragma("unroll") for (int k = 0; k < 2; ++k) dst[m][k] = *(const LAS bf16x8*)(lds + PG8_SA(b, h) + aoff + m * 2048 + k * 1024); } while (0)
; #define PG8_LDB(dst, b, h) do { _Pragma("unroll") for (int n = 0; n < 2; ++n) _Pragma("unroll") for (int k = 0; k < 2; ++k) dst[n][k] = *(const LAS bf16x8*)(lds + PG8_SB(b, h) + boff + n * 2048 + k * 1024); } while (0)
; #define PG8_MMA(ai, bj, At, Bt) do { __builtin_amdgcn_s_setprio(1); _Pragma("unroll") for (int m = 0; m < 4; ++m) _Pragma("unroll") for (int n = 0; n < 2; ++n) _Pragma("unroll") for (int k = 0; k < 2; ++k) \
;         acc[ai][bj][m][n] = __builtin_amdgcn_mfma_f32_16x16x32_bf16(Bt[n][k], At[m][k], acc[ai][bj][m][n], 0, 0, 0); __builtin_amdgcn_s_setprio(0); } while (0)
; #define PG8_WAIT_V(n) asm volatile("s_waitcnt vmcnt(" #n ")" ::: "memory")
; #define PG8_WAIT_L(n) asm volatile("s_waitcnt lgkmcnt(" #n ")" ::: "memory")
; #define PG8_BAR __builtin_amdgcn_s_barrier()
; #define PG8_SCHED __builtin_amdgcn_sched_barrier(0)
; template <int MODE, class EpiT, class Sched>
; __device__ __forceinline__ void gemm_phase(LAS unsigned char* lds, const Gemm g, const Sched& S, const EpiT& E) {
;     ...
;             PG8_LDB(B0, 0, 0); PG8_SCHED; PG8_LDA(At, 0, 0); PG8_STAGE(PG8_SA(1, 1), a1 + hstep, voffA);
;             PG8_WAIT_L(8); PG8_BAR; PG8_WAIT_L(0); PG8_MMA(0, 0, At, B0); PG8_BAR; PG8_SCHED;
;             PG8_LDB(B1, 0, 1); PG8_STAGE(PG8_SB(0, 0), b2, voffB);
;             PG8_BAR; PG8_WAIT_L(0); PG8_MMA(0, 1, At, B1); PG8_BAR;
;             PG8_LDA(At, 0, 1); PG8_STAGE(PG8_SA(0, 0), a2, voffA);
;             PG8_BAR; PG8_WAIT_L(0); PG8_MMA(1, 0, At, B0); PG8_BAR; PG8_SCHED;
;             PG8_STAGE(PG8_SB(0, 1), b2 + hstep, voffB);
;             PG8_WAIT_V(6); PG8_BAR; PG8_MMA(1, 1, At, B1); PG8_BAR;
.LBB0_159:
	s_add_i32 s89, s30, 2
	s_add_u32 s44, s4, 0x80
	s_addc_u32 s45, s5, 0
	s_add_u32 s100, s4, s38
	s_addc_u32 s101, s5, 0
	s_add_i32 s58, 0, 0x10000
	ds_read_b128 v[130:133], v251
	ds_read_b128 v[134:137], v251 offset:1024
	ds_read_b128 v[138:141], v251 offset:2048
	ds_read_b128 v[142:145], v251 offset:3072
	s_cmp_eq_u32 s61, s30
	s_cselect_b32 s45, s79, s45
	s_cselect_b32 s44, s78, s44
	s_cselect_b32 s53, s47, s24
	s_cselect_b32 s52, s46, s23
	s_add_i32 m0, s69, 0xc000
	ds_read_b128 v[146:149], v223
	global_load_lds_dwordx4 v0, s[100:101]
	s_add_i32 m0, s69, 0xe000
	ds_read_b128 v[174:177], v223 offset:7168
	global_load_lds_dwordx4 v182, s[100:101]
	ds_read_b128 v[150:153], v223 offset:1024
	ds_read_b128 v[154:157], v223 offset:2048
	ds_read_b128 v[158:161], v223 offset:3072
	ds_read_b128 v[162:165], v223 offset:4096
	ds_read_b128 v[166:169], v223 offset:5120
	ds_read_b128 v[170:173], v223 offset:6144
	s_waitcnt lgkmcnt(8)
	s_barrier
	s_waitcnt lgkmcnt(0)
	v_mfma_f32_16x16x32_bf16 v[126:129], v[130:133], v[146:149], v[126:129]
	v_mfma_f32_16x16x32_bf16 v[122:125], v[138:141], v[146:149], v[122:125]
	v_mfma_f32_16x16x32_bf16 v[110:113], v[130:133], v[154:157], v[110:113]
	v_mfma_f32_16x16x32_bf16 v[106:109], v[138:141], v[154:157], v[106:109]
	v_mfma_f32_16x16x32_bf16 v[94:97], v[130:133], v[162:165], v[94:97]
	v_mfma_f32_16x16x32_bf16 v[90:93], v[138:141], v[162:165], v[90:93]
	v_mfma_f32_16x16x32_bf16 v[78:81], v[130:133], v[170:173], v[78:81]
	v_mfma_f32_16x16x32_bf16 v[74:77], v[138:141], v[170:173], v[74:77]
	v_mfma_f32_16x16x32_bf16 v[126:129], v[134:137], v[150:153], v[126:129]
	v_mfma_f32_16x16x32_bf16 v[122:125], v[142:145], v[150:153], v[122:125]
	v_mfma_f32_16x16x32_bf16 v[110:113], v[134:137], v[158:161], v[110:113]
	v_mfma_f32_16x16x32_bf16 v[106:109], v[142:145], v[158:161], v[106:109]
	v_mfma_f32_16x16x32_bf16 v[94:97], v[134:137], v[166:169], v[94:97]
	v_mfma_f32_16x16x32_bf16 v[90:93], v[142:145], v[166:169], v[90:93]
	v_mfma_f32_16x16x32_bf16 v[78:81], v[134:137], v[174:177], v[78:81]
	v_mfma_f32_16x16x32_bf16 v[74:77], v[142:145], v[174:177], v[74:77]
	s_barrier
	s_add_i32 s30, 0, 0x14000
	s_add_i32 s58, s58, s68
	s_add_u32 s98, s52, 0x80
	s_addc_u32 s99, s53, 0
	s_mov_b32 m0, s58
	ds_read_b128 v[188:191], v251 offset:16384
	global_load_lds_dwordx4 v0, s[52:53]
	s_add_i32 m0, s58, 0x2000
	ds_read_b128 v[224:227], v251 offset:19456
	global_load_lds_dwordx4 v182, s[52:53]
	ds_read_b128 v[192:195], v251 offset:17408
	ds_read_b128 v[196:199], v251 offset:18432
	s_barrier
	s_waitcnt lgkmcnt(0)
	v_mfma_f32_16x16x32_bf16 v[118:121], v[188:191], v[146:149], v[118:121]
	v_mfma_f32_16x16x32_bf16 v[114:117], v[196:199], v[146:149], v[114:117]
	v_mfma_f32_16x16x32_bf16 v[102:105], v[188:191], v[154:157], v[102:105]
	v_mfma_f32_16x16x32_bf16 v[98:101], v[196:199], v[154:157], v[98:101]
	v_mfma_f32_16x16x32_bf16 v[86:89], v[188:191], v[162:165], v[86:89]
	v_mfma_f32_16x16x32_bf16 v[82:85], v[196:199], v[162:165], v[82:85]
	v_mfma_f32_16x16x32_bf16 v[70:73], v[188:191], v[170:173], v[70:73]
	v_mfma_f32_16x16x32_bf16 v[66:69], v[196:199], v[170:173], v[66:69]
	v_mfma_f32_16x16x32_bf16 v[118:121], v[192:195], v[150:153], v[118:121]
	v_mfma_f32_16x16x32_bf16 v[114:117], v[224:227], v[150:153], v[114:117]
	v_mfma_f32_16x16x32_bf16 v[102:105], v[192:195], v[158:161], v[102:105]
	v_mfma_f32_16x16x32_bf16 v[98:101], v[224:227], v[158:161], v[98:101]
	v_mfma_f32_16x16x32_bf16 v[86:89], v[192:195], v[166:169], v[86:89]
	v_mfma_f32_16x16x32_bf16 v[82:85], v[224:227], v[166:169], v[82:85]
	v_mfma_f32_16x16x32_bf16 v[70:73], v[192:195], v[174:177], v[70:73]
	v_mfma_f32_16x16x32_bf16 v[66:69], v[224:227], v[174:177], v[66:69]
	s_barrier
	s_mov_b32 m0, s69
	s_add_u32 s100, s44, 0x80
	s_addc_u32 s101, s45, 0
	ds_read_b128 v[146:149], v223 offset:16384
	global_load_lds_dwordx4 v0, s[44:45]
	s_mov_b32 m0, s74
	ds_read_b128 v[174:177], v223 offset:23552
	global_load_lds_dwordx4 v182, s[44:45]
	ds_read_b128 v[150:153], v223 offset:17408
	ds_read_b128 v[154:157], v223 offset:18432
	ds_read_b128 v[158:161], v223 offset:19456
	ds_read_b128 v[162:165], v223 offset:20480
	ds_read_b128 v[166:169], v223 offset:21504
	ds_read_b128 v[170:173], v223 offset:22528
	s_barrier
	s_waitcnt lgkmcnt(0)
	v_mfma_f32_16x16x32_bf16 v[62:65], v[130:133], v[146:149], v[62:65]
	v_mfma_f32_16x16x32_bf16 v[58:61], v[138:141], v[146:149], v[58:61]
	v_mfma_f32_16x16x32_bf16 v[46:49], v[130:133], v[154:157], v[46:49]
	v_mfma_f32_16x16x32_bf16 v[42:45], v[138:141], v[154:157], v[42:45]
	v_mfma_f32_16x16x32_bf16 v[30:33], v[130:133], v[162:165], v[30:33]
	v_mfma_f32_16x16x32_bf16 v[26:29], v[138:141], v[162:165], v[26:29]
	v_mfma_f32_16x16x32_bf16 v[14:17], v[130:133], v[170:173], v[14:17]
	v_mfma_f32_16x16x32_bf16 v[10:13], v[138:141], v[170:173], v[10:13]
	v_mfma_f32_16x16x32_bf16 v[62:65], v[134:137], v[150:153], v[62:65]
	v_mfma_f32_16x16x32_bf16 v[58:61], v[142:145], v[150:153], v[58:61]
	v_mfma_f32_16x16x32_bf16 v[46:49], v[134:137], v[158:161], v[46:49]
	v_mfma_f32_16x16x32_bf16 v[42:45], v[142:145], v[158:161], v[42:45]
	v_mfma_f32_16x16x32_bf16 v[30:33], v[134:137], v[166:169], v[30:33]
	v_mfma_f32_16x16x32_bf16 v[26:29], v[142:145], v[166:169], v[26:29]
	v_mfma_f32_16x16x32_bf16 v[14:17], v[134:137], v[174:177], v[14:17]
	v_mfma_f32_16x16x32_bf16 v[10:13], v[142:145], v[174:177], v[10:13]
	s_barrier
	s_add_u32 s52, s52, s38
	s_addc_u32 s53, s53, 0
	s_add_i32 s30, s30, s68
	s_mov_b32 m0, s30
	s_nop 0
	global_load_lds_dwordx4 v0, s[52:53]
	s_add_i32 m0, s30, 0x2000
	s_nop 0
	global_load_lds_dwordx4 v182, s[52:53]
	s_waitcnt vmcnt(6)
	s_barrier
; #define PG8_STAGE(bufoff, gbase, voff) do { _Pragma("unroll") for (int _i = 0; _i < 2; ++_i) \
;         __builtin_amdgcn_global_load_lds((const unsigned*)((const char*)(gbase) + (voff)[_i]), (LAS unsigned*)(lds + (bufoff) + ldsw + _i * 8192), 16, 0, 0); } while (0)
; #define PG8_LDA(dst, b, h) do { _Pragma("unroll") for (int m = 0; m < 4; ++m) _Pragma("unroll") for (int k = 0; k < 2; ++k) dst[m][k] = *(const LAS bf16x8*)(lds + PG8_SA(b, h) + aoff + m * 2048 + k * 1024); } while (0)
; #define PG8_LDB(dst, b, h) do { _Pragma("unroll") for (int n = 0; n < 2; ++n) _Pragma("unroll") for (int k = 0; k < 2; ++k) dst[n][k] = *(const LAS bf16x8*)(lds + PG8_SB(b, h) + boff + n * 2048 + k * 1024); } while (0)
; #define PG8_MMA(ai, bj, At, Bt) do { __builtin_amdgcn_s_setprio(1); _Pragma("unroll") for (int m = 0; m < 4; ++m) _Pragma("unroll") for (int n = 0; n < 2; ++n) _Pragma("unroll") for (int k = 0; k < 2; ++k) \
;         acc[ai][bj][m][n] = __builtin_amdgcn_mfma_f32_16x16x32_bf16(Bt[n][k], At[m][k], acc[ai][bj][m][n], 0, 0, 0); __builtin_amdgcn_s_setprio(0); } while (0)
; #define PG8_WAIT_V(n) asm volatile("s_waitcnt vmcnt(" #n ")" ::: "memory")
; #define PG8_WAIT_L(n) asm volatile("s_waitcnt lgkmcnt(" #n ")" ::: "memory")
; #define PG8_BAR __builtin_amdgcn_s_barrier()
; #define PG8_SCHED __builtin_amdgcn_sched_barrier(0)
; template <int MODE, class EpiT, class Sched>
; __device__ __forceinline__ void gemm_phase(LAS unsigned char* lds, const Gemm g, const Sched& S, const EpiT& E) {
;     ...
;             PG8_WAIT_V(6); PG8_BAR; PG8_MMA(1, 1, At, B1); PG8_BAR;
;             PG8_LDB(B0, 1, 0); PG8_SCHED; PG8_LDA(At, 1, 0); PG8_STAGE(PG8_SA(0, 1), a2 + hstep, voffA);
;             PG8_WAIT_L(8); PG8_BAR; PG8_WAIT_L(0); PG8_MMA(0, 0, At, B0); PG8_BAR; PG8_SCHED;
;             PG8_LDB(B1, 1, 1); PG8_STAGE(PG8_SB(1, 0), b3, voffB);
;             PG8_BAR; PG8_WAIT_L(0); PG8_MMA(0, 1, At, B1); PG8_BAR;
;             PG8_LDA(At, 1, 1); PG8_STAGE(PG8_SA(1, 0), a3, voffA);
;             PG8_BAR; PG8_WAIT_L(0); PG8_MMA(1, 0, At, B0); PG8_BAR; PG8_SCHED;
	v_mfma_f32_16x16x32_bf16 v[54:57], v[188:191], v[146:149], v[54:57]
	v_mfma_f32_16x16x32_bf16 v[50:53], v[196:199], v[146:149], v[50:53]
	v_mfma_f32_16x16x32_bf16 v[38:41], v[188:191], v[154:157], v[38:41]
	v_mfma_f32_16x16x32_bf16 v[34:37], v[196:199], v[154:157], v[34:37]
	v_mfma_f32_16x16x32_bf16 v[22:25], v[188:191], v[162:165], v[22:25]
	v_mfma_f32_16x16x32_bf16 v[18:21], v[196:199], v[162:165], v[18:21]
	v_mfma_f32_16x16x32_bf16 v[6:9], v[188:191], v[170:173], v[6:9]
	v_mfma_f32_16x16x32_bf16 v[2:5], v[196:199], v[170:173], v[2:5]
	v_mfma_f32_16x16x32_bf16 v[54:57], v[192:195], v[150:153], v[54:57]
	v_mfma_f32_16x16x32_bf16 v[50:53], v[224:227], v[150:153], v[50:53]
	v_mfma_f32_16x16x32_bf16 v[38:41], v[192:195], v[158:161], v[38:41]
	v_mfma_f32_16x16x32_bf16 v[34:37], v[224:227], v[158:161], v[34:37]
	v_mfma_f32_16x16x32_bf16 v[22:25], v[192:195], v[166:169], v[22:25]
	v_mfma_f32_16x16x32_bf16 v[18:21], v[224:227], v[166:169], v[18:21]
	v_mfma_f32_16x16x32_bf16 v[6:9], v[192:195], v[174:177], v[6:9]
	v_mfma_f32_16x16x32_bf16 v[2:5], v[224:227], v[174:177], v[2:5]
	s_barrier
	s_add_i32 s30, 0, 0x18000
	ds_read_b128 v[130:133], v251 offset:32768
	ds_read_b128 v[134:137], v251 offset:33792
	ds_read_b128 v[138:141], v251 offset:34816
	ds_read_b128 v[142:145], v251 offset:35840
	s_add_u32 s44, s44, s38
	s_addc_u32 s45, s45, 0
	s_mov_b32 m0, s75
	ds_read_b128 v[146:149], v223 offset:32768
	global_load_lds_dwordx4 v0, s[44:45]
	s_mov_b32 m0, s9
	ds_read_b128 v[174:177], v223 offset:39936
	global_load_lds_dwordx4 v182, s[44:45]
	ds_read_b128 v[150:153], v223 offset:33792
	ds_read_b128 v[154:157], v223 offset:34816
	ds_read_b128 v[158:161], v223 offset:35840
	ds_read_b128 v[162:165], v223 offset:36864
	ds_read_b128 v[166:169], v223 offset:37888
	ds_read_b128 v[170:173], v223 offset:38912
	s_waitcnt lgkmcnt(8)
	s_barrier
	s_waitcnt lgkmcnt(0)
	v_mfma_f32_16x16x32_bf16 v[126:129], v[130:133], v[146:149], v[126:129]
	v_mfma_f32_16x16x32_bf16 v[122:125], v[138:141], v[146:149], v[122:125]
	v_mfma_f32_16x16x32_bf16 v[110:113], v[130:133], v[154:157], v[110:113]
	v_mfma_f32_16x16x32_bf16 v[106:109], v[138:141], v[154:157], v[106:109]
	v_mfma_f32_16x16x32_bf16 v[94:97], v[130:133], v[162:165], v[94:97]
	v_mfma_f32_16x16x32_bf16 v[90:93], v[138:141], v[162:165], v[90:93]
	v_mfma_f32_16x16x32_bf16 v[78:81], v[130:133], v[170:173], v[78:81]
	v_mfma_f32_16x16x32_bf16 v[74:77], v[138:141], v[170:173], v[74:77]
	v_mfma_f32_16x16x32_bf16 v[126:129], v[134:137], v[150:153], v[126:129]
	v_mfma_f32_16x16x32_bf16 v[122:125], v[142:145], v[150:153], v[122:125]
	v_mfma_f32_16x16x32_bf16 v[110:113], v[134:137], v[158:161], v[110:113]
	v_mfma_f32_16x16x32_bf16 v[106:109], v[142:145], v[158:161], v[106:109]
	v_mfma_f32_16x16x32_bf16 v[94:97], v[134:137], v[166:169], v[94:97]
	v_mfma_f32_16x16x32_bf16 v[90:93], v[142:145], v[166:169], v[90:93]
	v_mfma_f32_16x16x32_bf16 v[78:81], v[134:137], v[174:177], v[78:81]
	v_mfma_f32_16x16x32_bf16 v[74:77], v[142:145], v[174:177], v[74:77]
	s_barrier
	s_add_i32 s44, 0, 0x1c000
	s_add_i32 s30, s30, s68
	s_mov_b32 m0, s30
	ds_read_b128 v[188:191], v251 offset:49152
	global_load_lds_dwordx4 v0, s[98:99]
	s_add_i32 m0, s30, 0x2000
	ds_read_b128 v[224:227], v251 offset:52224
	global_load_lds_dwordx4 v182, s[98:99]
	ds_read_b128 v[192:195], v251 offset:50176
	ds_read_b128 v[196:199], v251 offset:51200
	s_barrier
	s_waitcnt lgkmcnt(0)
	v_mfma_f32_16x16x32_bf16 v[118:121], v[188:191], v[146:149], v[118:121]
	v_mfma_f32_16x16x32_bf16 v[114:117], v[196:199], v[146:149], v[114:117]
	v_mfma_f32_16x16x32_bf16 v[102:105], v[188:191], v[154:157], v[102:105]
	v_mfma_f32_16x16x32_bf16 v[98:101], v[196:199], v[154:157], v[98:101]
	v_mfma_f32_16x16x32_bf16 v[86:89], v[188:191], v[162:165], v[86:89]
	v_mfma_f32_16x16x32_bf16 v[82:85], v[196:199], v[162:165], v[82:85]
	v_mfma_f32_16x16x32_bf16 v[70:73], v[188:191], v[170:173], v[70:73]
	v_mfma_f32_16x16x32_bf16 v[66:69], v[196:199], v[170:173], v[66:69]
	v_mfma_f32_16x16x32_bf16 v[118:121], v[192:195], v[150:153], v[118:121]
	v_mfma_f32_16x16x32_bf16 v[114:117], v[224:227], v[150:153], v[114:117]
	v_mfma_f32_16x16x32_bf16 v[102:105], v[192:195], v[158:161], v[102:105]
	v_mfma_f32_16x16x32_bf16 v[98:101], v[224:227], v[158:161], v[98:101]
	v_mfma_f32_16x16x32_bf16 v[86:89], v[192:195], v[166:169], v[86:89]
	v_mfma_f32_16x16x32_bf16 v[82:85], v[224:227], v[166:169], v[82:85]
	v_mfma_f32_16x16x32_bf16 v[70:73], v[192:195], v[174:177], v[70:73]
	v_mfma_f32_16x16x32_bf16 v[66:69], v[224:227], v[174:177], v[66:69]
	s_barrier
	s_mov_b32 m0, s57
	ds_read_b128 v[146:149], v223 offset:49152
	global_load_lds_dwordx4 v0, s[100:101]
	s_mov_b32 m0, s60
	ds_read_b128 v[174:177], v223 offset:56320
	global_load_lds_dwordx4 v182, s[100:101]
	ds_read_b128 v[150:153], v223 offset:50176
	ds_read_b128 v[154:157], v223 offset:51200
	ds_read_b128 v[158:161], v223 offset:52224
	ds_read_b128 v[162:165], v223 offset:53248
	ds_read_b128 v[166:169], v223 offset:54272
	ds_read_b128 v[170:173], v223 offset:55296
	s_barrier
	s_waitcnt lgkmcnt(0)
	v_mfma_f32_16x16x32_bf16 v[62:65], v[130:133], v[146:149], v[62:65]
	v_mfma_f32_16x16x32_bf16 v[58:61], v[138:141], v[146:149], v[58:61]
	v_mfma_f32_16x16x32_bf16 v[46:49], v[130:133], v[154:157], v[46:49]
	v_mfma_f32_16x16x32_bf16 v[42:45], v[138:141], v[154:157], v[42:45]
	v_mfma_f32_16x16x32_bf16 v[30:33], v[130:133], v[162:165], v[30:33]
	v_mfma_f32_16x16x32_bf16 v[26:29], v[138:141], v[162:165], v[26:29]
	v_mfma_f32_16x16x32_bf16 v[14:17], v[130:133], v[170:173], v[14:17]
	v_mfma_f32_16x16x32_bf16 v[10:13], v[138:141], v[170:173], v[10:13]
	v_mfma_f32_16x16x32_bf16 v[62:65], v[134:137], v[150:153], v[62:65]
	v_mfma_f32_16x16x32_bf16 v[58:61], v[142:145], v[150:153], v[58:61]
	v_mfma_f32_16x16x32_bf16 v[46:49], v[134:137], v[158:161], v[46:49]
	v_mfma_f32_16x16x32_bf16 v[42:45], v[142:145], v[158:161], v[42:45]
	v_mfma_f32_16x16x32_bf16 v[30:33], v[134:137], v[166:169], v[30:33]
	v_mfma_f32_16x16x32_bf16 v[26:29], v[142:145], v[166:169], v[26:29]
	v_mfma_f32_16x16x32_bf16 v[14:17], v[134:137], v[174:177], v[14:17]
	v_mfma_f32_16x16x32_bf16 v[10:13], v[142:145], v[174:177], v[10:13]
	s_barrier
; #define PG8_STAGE(bufoff, gbase, voff) do { _Pragma("unroll") for (int _i = 0; _i < 2; ++_i) \
;         __builtin_amdgcn_global_load_lds((const unsigned*)((const char*)(gbase) + (voff)[_i]), (LAS unsigned*)(lds + (bufoff) + ldsw + _i * 8192), 16, 0, 0); } while (0)
; #define PG8_MMA(ai, bj, At, Bt) do { __builtin_amdgcn_s_setprio(1); _Pragma("unroll") for (int m = 0; m < 4; ++m) _Pragma("unroll") for (int n = 0; n < 2; ++n) _Pragma("unroll") for (int k = 0; k < 2; ++k) \
;         acc[ai][bj][m][n] = __builtin_amdgcn_mfma_f32_16x16x32_bf16(Bt[n][k], At[m][k], acc[ai][bj][m][n], 0, 0, 0); __builtin_amdgcn_s_setprio(0); } while (0)
; #define PG8_WAIT_V(n) asm volatile("s_waitcnt vmcnt(" #n ")" ::: "memory")
; #define PG8_WAIT_L(n) asm volatile("s_waitcnt lgkmcnt(" #n ")" ::: "memory")
; #define PG8_BAR __builtin_amdgcn_s_barrier()
; #define PG8_SCHED __builtin_amdgcn_sched_barrier(0)
;     __device__ __forceinline__ void scales2(const Unit& u, int wr, int fr, int fq, float& sA, float& sB) const {
;         const int rowA = u.pm * BM + wr * 64 + fq * 16 + fr;
;         const f32x4* pa = (const f32x4*)(ssq_in + (size_t)rowA * 16); const f32x4* pb = (const f32x4*)(ssq_in + (size_t)(rowA + HALF) * 16);
;         const f32x4 a0 = pa[0], a1 = pa[1], a2 = pa[2], a3 = pa[3], b0 = pb[0], b1 = pb[1], b2 = pb[2], b3 = pb[3];
;         const float ta = (((a0[0] + a0[1]) + (a0[2] + a0[3])) + ((a1[0] + a1[1]) + (a1[2] + a1[3]))) + (((a2[0] + a2[1]) + (a2[2] + a2[3])) + ((a3[0] + a3[1]) + (a3[2] + a3[3])));
;         const float tb = (((b0[0] + b0[1]) + (b0[2] + b0[3])) + ((b1[0] + b1[1]) + (b1[2] + b1[3]))) + (((b2[0] + b2[1]) + (b2[2] + b2[3])) + ((b3[0] + b3[1]) + (b3[2] + b3[3])));
;         sA = rsqrtf(ta * (1.0f / 1024.0f) + EPS); sB = rsqrtf(tb * (1.0f / 1024.0f) + EPS);
; template <int MODE, class EpiT, class Sched>
; __device__ __forceinline__ void gemm_phase(LAS unsigned char* lds, const Gemm g, const Sched& S, const EpiT& E) {
;     ...
;             PG8_BAR; PG8_WAIT_L(0); PG8_MMA(1, 0, At, B0); PG8_BAR; PG8_SCHED;
;             PG8_STAGE(PG8_SB(1, 1), b3 + hstep, voffB);
;             PG8_WAIT_V(6); PG8_BAR; PG8_MMA(1, 1, At, B1); PG8_BAR;
;         }
;         E.template run<MODE>(acc, cur, wr, wc, fr, fq, SC + ui * 256);
;         if (!has_next) break;
	s_add_i32 s30, s44, s68
	s_add_u32 s98, s98, s38
	s_addc_u32 s99, s99, 0
	s_mov_b32 m0, s30
	s_nop 0
	global_load_lds_dwordx4 v0, s[98:99]
	s_add_i32 m0, s30, 0x2000
	s_nop 0
	global_load_lds_dwordx4 v182, s[98:99]
	s_waitcnt vmcnt(6)
	s_barrier
	v_mfma_f32_16x16x32_bf16 v[54:57], v[188:191], v[146:149], v[54:57]
	v_mfma_f32_16x16x32_bf16 v[50:53], v[196:199], v[146:149], v[50:53]
	v_mfma_f32_16x16x32_bf16 v[38:41], v[188:191], v[154:157], v[38:41]
	v_mfma_f32_16x16x32_bf16 v[34:37], v[196:199], v[154:157], v[34:37]
	v_mfma_f32_16x16x32_bf16 v[22:25], v[188:191], v[162:165], v[22:25]
	v_mfma_f32_16x16x32_bf16 v[18:21], v[196:199], v[162:165], v[18:21]
	v_mfma_f32_16x16x32_bf16 v[6:9], v[188:191], v[170:173], v[6:9]
	v_mfma_f32_16x16x32_bf16 v[2:5], v[196:199], v[170:173], v[2:5]
	v_mfma_f32_16x16x32_bf16 v[54:57], v[192:195], v[150:153], v[54:57]
	v_mfma_f32_16x16x32_bf16 v[50:53], v[224:227], v[150:153], v[50:53]
	v_mfma_f32_16x16x32_bf16 v[38:41], v[192:195], v[158:161], v[38:41]
	v_mfma_f32_16x16x32_bf16 v[34:37], v[224:227], v[158:161], v[34:37]
	v_mfma_f32_16x16x32_bf16 v[22:25], v[192:195], v[166:169], v[22:25]
	v_mfma_f32_16x16x32_bf16 v[18:21], v[224:227], v[166:169], v[18:21]
	v_mfma_f32_16x16x32_bf16 v[6:9], v[192:195], v[174:177], v[6:9]
	v_mfma_f32_16x16x32_bf16 v[2:5], v[224:227], v[174:177], v[2:5]
	s_barrier
	s_add_u32 s4, s4, 0x100
	s_addc_u32 s5, s5, 0
	s_add_u32 s23, s23, 0x100
	s_addc_u32 s24, s24, 0
	s_cmp_ge_u32 s89, s21
	s_mov_b32 s30, s89
	s_cbranch_scc0 .LBB0_159
	s_lshl_b32 s4, s22, 8
	s_add_i32 s4, s4, s56
	v_or_b32_e32 v130, s4, v222
	v_ashrrev_i32_e32 v131, 31, v130
	v_lshlrev_b64 v[130:131], 6, v[130:131]
	v_lshl_add_u64 v[146:147], s[66:67], 0, v[130:131]
	global_load_dwordx4 v[130:133], v[146:147], off offset:16
	global_load_dwordx4 v[134:137], v[146:147], off offset:48
	global_load_dwordx4 v[138:141], v[146:147], off
	global_load_dwordx4 v[142:145], v[146:147], off offset:32
	v_or_b32_e32 v192, s4, v181
	s_mov_b64 s[4:5], 0x2000
	v_lshl_add_u64 v[158:159], v[146:147], 0, s[4:5]
	v_add_co_u32_e32 v146, vcc, 0x2000, v146
	s_mov_b32 s4, 0x3a800000
	s_nop 0
	v_addc_co_u32_e32 v147, vcc, 0, v147, vcc
	global_load_dwordx4 v[146:149], v[146:147], off
	s_nop 0
	global_load_dwordx4 v[150:153], v[158:159], off offset:16
	global_load_dwordx4 v[154:157], v[158:159], off offset:48
	s_nop 0
	global_load_dwordx4 v[158:161], v[158:159], off offset:32
	v_lshl_or_b32 v188, s2, 8, v221
	v_ashrrev_i32_e32 v193, 31, v192
	v_ashrrev_i32_e32 v189, 31, v188
	v_or_b32_e32 v194, 16, v192
	v_ashrrev_i32_e32 v195, 31, v194
	s_waitcnt vmcnt(0)
	v_mov_b32_e32 v162, v138
	v_mov_b32_e32 v163, v142
	v_mov_b32_e32 v142, v139
	v_pk_add_f32 v[138:139], v[162:163], v[142:143]
	v_mov_b32_e32 v142, v140
	v_mov_b32_e32 v143, v144
	v_mov_b32_e32 v144, v141
	v_pk_add_f32 v[140:141], v[142:143], v[144:145]
	s_nop 0
	v_pk_add_f32 v[138:139], v[138:139], v[140:141]
	v_mov_b32_e32 v140, v130
	v_mov_b32_e32 v141, v134
	v_mov_b32_e32 v134, v131
	v_pk_add_f32 v[130:131], v[140:141], v[134:135]
	v_mov_b32_e32 v134, v132
	v_mov_b32_e32 v135, v136
	v_mov_b32_e32 v136, v133
	v_pk_add_f32 v[132:133], v[134:135], v[136:137]
	v_mov_b32_e32 v134, v148
	v_pk_add_f32 v[130:131], v[130:131], v[132:133]
	v_mov_b32_e32 v132, v146
	v_mov_b32_e32 v133, v158
	v_mov_b32_e32 v158, v147
	v_mov_b32_e32 v135, v160
	v_mov_b32_e32 v160, v149
	v_pk_add_f32 v[132:133], v[132:133], v[158:159]
	v_pk_add_f32 v[134:135], v[134:135], v[160:161]
	v_mov_b32_e32 v136, v152
	v_pk_add_f32 v[132:133], v[132:133], v[134:135]
	v_mov_b32_e32 v134, v150
	v_mov_b32_e32 v135, v154
	v_mov_b32_e32 v154, v151
	v_mov_b32_e32 v137, v156
	v_mov_b32_e32 v156, v153
	v_pk_add_f32 v[134:135], v[134:135], v[154:155]
	v_pk_add_f32 v[136:137], v[136:137], v[156:157]
	v_pk_add_f32 v[130:131], v[138:139], v[130:131]
	v_pk_add_f32 v[134:135], v[134:135], v[136:137]
	s_nop 0
	v_pk_add_f32 v[132:133], v[132:133], v[134:135]
	v_mov_b32_e32 v135, v130
	v_mov_b32_e32 v134, v132
	v_mov_b32_e32 v130, v133
	v_pk_add_f32 v[130:131], v[134:135], v[130:131]
	s_nop 0
	v_pk_fma_f32 v[190:191], v[130:131], s[4:5], v[178:179] op_sel_hi:[1,0,0]
	s_mov_b32 s4, 0x800000
	v_mul_f32_e32 v130, 0x4b800000, v191
	v_cmp_gt_f32_e64 s[44:45], s4, v191
	v_cmp_gt_f32_e32 vcc, s4, v190
	s_nop 0
	v_cndmask_b32_e64 v130, v191, v130, s[44:45]
	v_rsq_f32_e32 v130, v130
	s_nop 0
	v_mul_f32_e32 v131, 0x45800000, v130
	v_cndmask_b32_e64 v226, v130, v131, s[44:45]
	v_lshlrev_b64 v[130:131], 10, v[192:193]
	v_lshl_add_u64 v[130:131], v[130:131], 0, v[188:189]
	v_lshlrev_b64 v[198:199], 1, v[130:131]
	v_lshl_add_u64 v[130:131], s[34:35], 0, v[198:199]
	v_lshl_add_u64 v[132:133], s[92:93], 0, v[198:199]
	global_load_dwordx4 v[170:173], v[130:131], off
	global_load_dwordx4 v[174:177], v[132:133], off
	v_lshl_add_u64 v[134:135], s[6:7], 0, v[198:199]
	global_load_dwordx4 v[166:169], v[134:135], off
	global_load_dwordx4 v[158:161], v[130:131], off offset:256
	global_load_dwordx4 v[162:165], v[132:133], off offset:256
	global_load_dwordx4 v[146:149], v[134:135], off offset:256
	v_and_b32_e32 v130, 64, v205
	v_or_b32_e32 v200, v130, v181
	v_lshlrev_b32_e32 v225, 2, v200
	ds_bpermute_b32 v200, v225, v226
	v_xor_b32_e32 v131, 16, v205
	v_add_u32_e32 v130, 64, v130
	v_cmp_lt_i32_e64 s[44:45], v131, v130
	s_waitcnt lgkmcnt(0)
; __device__ __forceinline__ float bf_lo(unsigned w) { return __uint_as_float(w << 16); }
;     template <int mode> __device__ __forceinline__ void run(const f32x4 (&acc)[2][2][4][2], const Unit& u, int wr, int wc, int fr, int fq, const LAS float* sc) const {
;     ...
;                     const size_t offn = (size_t)(row0 + ((g + 1) >> 2) * HALF + ((g + 1) & 3) * 16) * D + col0;
; #pragma unroll
;                     for (int bj = 0; bj < 2; ++bj) {
;                         const size_t o = offn + bj * HALF;
;                         if (mode == 5) { xi[nb][2 * bj] = *(const f32x4*)(xin + o); xi[nb][2 * bj + 1] = *(const f32x4*)(xin + o + 4); }
;                         else { xh[nb][bj] = *(const u32x4*)(hin + o); xl[nb][bj] = *(const u32x4*)(lin + o); }
;                         if (mode == 4) pq[nb][bj] = *(const u32x4*)(ob + o);
;                     }
;                 }
;                 float s = 1.f;
;                 if (mode == 4) s = __shfl(ai ? sB : sA, m * 16 + fr);
;                 float ss = 0.f;
; #pragma unroll
;                 for (int bj = 0; bj < 2; ++bj) {
;                     u32x4 wh, wl;
; #pragma unroll
;                     for (int n = 0; n < 2; ++n) {
;                         const int q = 2 * bj + n;
;                         const unsigned h0 = n ? xh[cb][bj].z : xh[cb][bj].x, h1 = n ? xh[cb][bj].w : xh[cb][bj].y, l0 = n ? xl[cb][bj].z : xl[cb][bj].x, l1 = n ? xl[cb][bj].w : xl[cb][bj].y;
;                         f32x4 xo;
;                         if (mode == 5) xo = xi[cb][q];
;                         else { xo[0] = bf_lo(h0) + bf_lo(l0); xo[1] = bf_hi(h0) + bf_hi(l0); xo[2] = bf_lo(h1) + bf_lo(l1); xo[3] = bf_hi(h1) + bf_hi(l1); }
;                         f32x4 v;
;                         if (mode != 4) v = xo + acc[ai][bj][m][n] * alpha + bvv[q];
;                         else {
;                             const f32x4 a = acc[ai][bj][m][n] * s;
;                             const unsigned p0 = n ? pq[cb][bj].z : pq[cb][bj].x, p1 = n ? pq[cb][bj].w : pq[cb][bj].y;
;                             v[0] = xo[0] + sigmoidf_(a[0]) * bf_lo(p0); v[1] = xo[1] + sigmoidf_(a[1]) * bf_hi(p0);
;                             v[2] = xo[2] + sigmoidf_(a[2]) * bf_lo(p1); v[3] = xo[3] + sigmoidf_(a[3]) * bf_hi(p1);
;                         }
;                         const unsigned w0 = pk2(v[0], v[1]), w1 = pk2(v[2], v[3]);
	v_pk_mul_f32 v[126:127], v[126:127], v[200:201] op_sel_hi:[1,0]
	v_cndmask_b32_e64 v131, v205, v131, s[44:45]
	v_lshlrev_b32_e32 v191, 2, v131
	v_xor_b32_e32 v131, 32, v205
	v_mul_f32_e32 v126, 0xbfb8aa3b, v126
	v_cmp_lt_i32_e64 s[44:45], v131, v130
	v_exp_f32_e32 v126, v126
	v_pk_mul_f32 v[128:129], v[128:129], v[200:201] op_sel_hi:[1,0]
	v_cndmask_b32_e64 v130, v205, v131, s[44:45]
	v_lshlrev_b32_e32 v224, 2, v130
	v_lshlrev_b64 v[130:131], 10, v[194:195]
	v_lshl_add_u64 v[130:131], v[130:131], 0, v[188:189]
	v_lshlrev_b64 v[196:197], 1, v[130:131]
	v_add_f32_e32 v126, 1.0, v126
	v_lshl_add_u64 v[130:131], s[34:35], 0, v[196:197]
	v_lshl_add_u64 v[132:133], s[92:93], 0, v[196:197]
	v_lshl_add_u64 v[228:229], s[6:7], 0, v[196:197]
	v_rcp_f32_e32 v126, v126
	global_load_dwordx4 v[150:153], v[130:131], off
	global_load_dwordx4 v[154:157], v[132:133], off
	global_load_dwordx4 v[142:145], v[228:229], off
	global_load_dwordx4 v[134:137], v[130:131], off offset:256
	global_load_dwordx4 v[138:141], v[132:133], off offset:256
	s_nop 0
	global_load_dwordx4 v[130:133], v[228:229], off offset:256
	v_pk_mul_f32 v[122:123], v[122:123], v[200:201] op_sel_hi:[1,0]
	v_pk_mul_f32 v[124:125], v[124:125], v[200:201] op_sel_hi:[1,0]
	v_mul_f32_e32 v122, 0xbfb8aa3b, v122
	v_exp_f32_e32 v122, v122
	v_pk_mul_f32 v[118:119], v[118:119], v[200:201] op_sel_hi:[1,0]
	v_pk_mul_f32 v[120:121], v[120:121], v[200:201] op_sel_hi:[1,0]
	v_mul_f32_e32 v118, 0xbfb8aa3b, v118
	v_add_f32_e32 v122, 1.0, v122
	v_rcp_f32_e32 v122, v122
	v_exp_f32_e32 v118, v118
	v_pk_mul_f32 v[114:115], v[114:115], v[200:201] op_sel_hi:[1,0]
	v_pk_mul_f32 v[116:117], v[116:117], v[200:201] op_sel_hi:[1,0]
	v_mul_f32_e32 v114, 0xbfb8aa3b, v114
	v_add_f32_e32 v118, 1.0, v118
	v_rcp_f32_e32 v118, v118
	v_exp_f32_e32 v114, v114
	s_lshl_b32 s44, s2, 2
	s_ashr_i32 s45, s44, 31
	v_add_f32_e32 v114, 1.0, v114
	v_rcp_f32_e32 v114, v114
	s_waitcnt vmcnt(11)
	v_lshlrev_b32_e32 v227, 16, v170
	s_waitcnt vmcnt(10)
	v_lshlrev_b32_e32 v228, 16, v174
	v_and_b32_e32 v174, 0xffff0000, v174
	v_and_b32_e32 v170, 0xffff0000, v170
	v_add_f32_e32 v227, v228, v227
	v_add_f32_e32 v170, v174, v170
	v_lshlrev_b32_e32 v174, 16, v171
	v_lshlrev_b32_e32 v228, 16, v175
	v_and_b32_e32 v175, 0xffff0000, v175
	v_and_b32_e32 v171, 0xffff0000, v171
	v_add_f32_e32 v171, v175, v171
	s_waitcnt vmcnt(9)
	v_lshlrev_b32_e32 v175, 16, v166
	v_fmac_f32_e32 v227, v126, v175
	v_mul_f32_e32 v126, 0xbfb8aa3b, v127
	v_exp_f32_e32 v126, v126
	v_and_b32_e32 v127, 0xffff0000, v166
	v_add_f32_e32 v174, v228, v174
	v_add_f32_e32 v126, 1.0, v126
	v_rcp_f32_e32 v126, v126
	s_nop 0
	v_fmac_f32_e32 v170, v126, v127
	v_mul_f32_e32 v126, 0xbfb8aa3b, v128
	v_exp_f32_e32 v126, v126
	v_lshlrev_b32_e32 v127, 16, v167
	v_add_f32_e32 v126, 1.0, v126
	v_rcp_f32_e32 v126, v126
	s_nop 0
	v_fmac_f32_e32 v174, v126, v127
	v_mul_f32_e32 v126, 0xbfb8aa3b, v129
	v_exp_f32_e32 v126, v126
	v_and_b32_e32 v127, 0xffff0000, v167
	v_add_f32_e32 v126, 1.0, v126
	v_rcp_f32_e32 v126, v126
	s_nop 0
	v_fmac_f32_e32 v171, v126, v127
	v_cvt_pk_bf16_f32 v126, v227, v170
	v_cvt_pk_bf16_f32 v127, v174, v171
	s_nop 0
	v_lshlrev_b32_e32 v128, 16, v126
	v_and_b32_e32 v129, 0xffff0000, v126
	v_sub_f32_e32 v128, v227, v128
	v_sub_f32_e32 v129, v170, v129
	v_cvt_pk_bf16_f32 v166, v128, v129
	v_lshlrev_b32_e32 v128, 16, v127
	v_and_b32_e32 v129, 0xffff0000, v127
	v_sub_f32_e32 v128, v174, v128
	v_sub_f32_e32 v129, v171, v129
	v_cvt_pk_bf16_f32 v167, v128, v129
	v_mul_f32_e32 v128, v170, v170
	v_mul_f32_e32 v129, v171, v171
	v_fmac_f32_e32 v128, v227, v227
	v_fmac_f32_e32 v129, v174, v174
	v_add_f32_e32 v170, v128, v129
	v_lshlrev_b32_e32 v128, 16, v172
	v_lshlrev_b32_e32 v129, 16, v176
	v_add_f32_e32 v171, v129, v128
	v_and_b32_e32 v128, 0xffff0000, v176
	v_and_b32_e32 v129, 0xffff0000, v172
	v_add_f32_e32 v172, v128, v129
	v_lshlrev_b32_e32 v128, 16, v173
	v_lshlrev_b32_e32 v129, 16, v177
	v_add_f32_e32 v174, v129, v128
	v_and_b32_e32 v128, 0xffff0000, v177
	v_and_b32_e32 v129, 0xffff0000, v173
	v_add_f32_e32 v173, v128, v129
	v_lshlrev_b32_e32 v128, 16, v168
	v_fmac_f32_e32 v171, v122, v128
	v_mul_f32_e32 v122, 0xbfb8aa3b, v123
	v_exp_f32_e32 v122, v122
	v_and_b32_e32 v123, 0xffff0000, v168
	v_add_f32_e32 v122, 1.0, v122
	v_rcp_f32_e32 v122, v122
	s_nop 0
	v_fmac_f32_e32 v172, v122, v123
	v_mul_f32_e32 v122, 0xbfb8aa3b, v124
	v_exp_f32_e32 v122, v122
	v_lshlrev_b32_e32 v123, 16, v169
	v_cvt_pk_bf16_f32 v128, v171, v172
	v_add_f32_e32 v122, 1.0, v122
	v_rcp_f32_e32 v122, v122
	s_nop 0
	v_fmac_f32_e32 v174, v122, v123
	v_mul_f32_e32 v122, 0xbfb8aa3b, v125
	v_exp_f32_e32 v122, v122
	v_and_b32_e32 v123, 0xffff0000, v169
	v_lshl_add_u64 v[124:125], s[28:29], 0, v[198:199]
	v_add_f32_e32 v122, 1.0, v122
	v_rcp_f32_e32 v122, v122
	s_nop 0
	v_fmac_f32_e32 v173, v122, v123
	v_lshlrev_b32_e32 v122, 16, v128
	v_and_b32_e32 v123, 0xffff0000, v128
	v_sub_f32_e32 v122, v171, v122
	v_sub_f32_e32 v123, v172, v123
	v_cvt_pk_bf16_f32 v129, v174, v173
	v_cvt_pk_bf16_f32 v168, v122, v123
	s_nop 0
	v_lshlrev_b32_e32 v122, 16, v129
	v_and_b32_e32 v123, 0xffff0000, v129
	v_sub_f32_e32 v122, v174, v122
	v_sub_f32_e32 v123, v173, v123
	v_cvt_pk_bf16_f32 v169, v122, v123
	v_mul_f32_e32 v122, v172, v172
	v_mul_f32_e32 v123, v173, v173
	v_fmac_f32_e32 v122, v171, v171
	v_fmac_f32_e32 v123, v174, v174
	v_add_f32_e32 v122, v122, v123
	v_add_f32_e32 v170, v170, v122
	v_lshl_add_u64 v[122:123], s[10:11], 0, v[198:199]
	global_store_dwordx4 v[122:123], v[126:129], off
	global_store_dwordx4 v[124:125], v[166:169], off
	s_waitcnt vmcnt(10)
; __device__ __forceinline__ float bf_lo(unsigned w) { return __uint_as_float(w << 16); }
; __device__ __forceinline__ float bf_hi(unsigned w) { return __uint_as_float(w & 0xffff0000u); }
;     template <int mode> __device__ __forceinline__ void run(const f32x4 (&acc)[2][2][4][2], const Unit& u, int wr, int wc, int fr, int fq, const LAS float* sc) const {
;     ...
;                 for (int bj = 0; bj < 2; ++bj) {
;                     u32x4 wh, wl;
; #pragma unroll
;                     for (int n = 0; n < 2; ++n) {
;                         const int q = 2 * bj + n;
;                         const unsigned h0 = n ? xh[cb][bj].z : xh[cb][bj].x, h1 = n ? xh[cb][bj].w : xh[cb][bj].y, l0 = n ? xl[cb][bj].z : xl[cb][bj].x, l1 = n ? xl[cb][bj].w : xl[cb][bj].y;
;                         f32x4 xo;
;                         if (mode == 5) xo = xi[cb][q];
;                         else { xo[0] = bf_lo(h0) + bf_lo(l0); xo[1] = bf_hi(h0) + bf_hi(l0); xo[2] = bf_lo(h1) + bf_lo(l1); xo[3] = bf_hi(h1) + bf_hi(l1); }
;                         f32x4 v;
;                         if (mode != 4) v = xo + acc[ai][bj][m][n] * alpha + bvv[q];
;                         else {
;                             const f32x4 a = acc[ai][bj][m][n] * s;
;                             const unsigned p0 = n ? pq[cb][bj].z : pq[cb][bj].x, p1 = n ? pq[cb][bj].w : pq[cb][bj].y;
;                             v[0] = xo[0] + sigmoidf_(a[0]) * bf_lo(p0); v[1] = xo[1] + sigmoidf_(a[1]) * bf_hi(p0);
;                             v[2] = xo[2] + sigmoidf_(a[2]) * bf_lo(p1); v[3] = xo[3] + sigmoidf_(a[3]) * bf_hi(p1);
;                         }
;                         const unsigned w0 = pk2(v[0], v[1]), w1 = pk2(v[2], v[3]);
;                         const unsigned m0 = pk2(v[0] - bf_lo(w0), v[1] - bf_hi(w0)), m1 = pk2(v[2] - bf_lo(w1), v[3] - bf_hi(w1));
;                         if (n == 0) { wh.x = w0; wh.y = w1; wl.x = m0; wl.y = m1; } else { wh.z = w0; wh.w = w1; wl.z = m0; wl.w = m1; }
;                         ss += (v[0] * v[0] + v[1] * v[1]) + (v[2] * v[2] + v[3] * v[3]);
;                     }
;                     *(u32x4*)(xb + off + bj * HALF) = wh;
;                     *(u32x4*)(lout + off + bj * HALF) = wl;
;                 }
;                 ss += __shfl_xor(ss, 16); ss += __shfl_xor(ss, 32);
;                 if (fq == 0) ssq_out[(size_t)row * 16 + u.pn * 4 + wc] = ss;
	v_lshlrev_b32_e32 v126, 16, v158
	s_waitcnt vmcnt(9)
	v_lshlrev_b32_e32 v127, 16, v162
	v_add_f32_e32 v128, v127, v126
	v_and_b32_e32 v126, 0xffff0000, v162
	v_and_b32_e32 v127, 0xffff0000, v158
	v_add_f32_e32 v129, v126, v127
	v_lshlrev_b32_e32 v126, 16, v159
	v_lshlrev_b32_e32 v127, 16, v163
	v_add_f32_e32 v158, v127, v126
	v_and_b32_e32 v126, 0xffff0000, v163
	v_and_b32_e32 v127, 0xffff0000, v159
	v_add_f32_e32 v159, v126, v127
	s_waitcnt vmcnt(8)
	v_lshlrev_b32_e32 v126, 16, v146
	v_fmac_f32_e32 v128, v118, v126
	v_mul_f32_e32 v118, 0xbfb8aa3b, v119
	v_exp_f32_e32 v118, v118
	v_and_b32_e32 v119, 0xffff0000, v146
	v_add_f32_e32 v118, 1.0, v118
	v_rcp_f32_e32 v118, v118
	s_nop 0
	v_fmac_f32_e32 v129, v118, v119
	v_mul_f32_e32 v118, 0xbfb8aa3b, v120
	v_exp_f32_e32 v118, v118
	v_lshlrev_b32_e32 v119, 16, v147
	v_add_f32_e32 v118, 1.0, v118
	v_rcp_f32_e32 v118, v118
	s_nop 0
	v_fmac_f32_e32 v158, v118, v119
	v_mul_f32_e32 v118, 0xbfb8aa3b, v121
	v_exp_f32_e32 v118, v118
	v_and_b32_e32 v119, 0xffff0000, v147
	v_add_f32_e32 v118, 1.0, v118
	v_rcp_f32_e32 v118, v118
	s_nop 0
	v_fmac_f32_e32 v159, v118, v119
	v_cvt_pk_bf16_f32 v118, v128, v129
	v_cvt_pk_bf16_f32 v119, v158, v159
	s_nop 0
	v_lshlrev_b32_e32 v120, 16, v118
	v_and_b32_e32 v121, 0xffff0000, v118
	v_sub_f32_e32 v120, v128, v120
	v_sub_f32_e32 v121, v129, v121
	v_cvt_pk_bf16_f32 v126, v120, v121
	v_lshlrev_b32_e32 v120, 16, v119
	v_and_b32_e32 v121, 0xffff0000, v119
	v_sub_f32_e32 v120, v158, v120
	v_sub_f32_e32 v121, v159, v121
	v_cvt_pk_bf16_f32 v127, v120, v121
	v_mul_f32_e32 v120, v129, v129
	v_mul_f32_e32 v121, v159, v159
	v_fmac_f32_e32 v120, v128, v128
	v_fmac_f32_e32 v121, v158, v158
	v_add_f32_e32 v120, v120, v121
	v_add_f32_e32 v146, v120, v170
	v_lshlrev_b32_e32 v120, 16, v160
	v_lshlrev_b32_e32 v121, 16, v164
	v_add_f32_e32 v147, v121, v120
	v_and_b32_e32 v120, 0xffff0000, v164
	v_and_b32_e32 v121, 0xffff0000, v160
	v_add_f32_e32 v158, v120, v121
	v_lshlrev_b32_e32 v120, 16, v161
	v_lshlrev_b32_e32 v121, 16, v165
	v_add_f32_e32 v159, v121, v120
	v_and_b32_e32 v120, 0xffff0000, v165
	v_and_b32_e32 v121, 0xffff0000, v161
	v_add_f32_e32 v160, v120, v121
	v_lshlrev_b32_e32 v120, 16, v148
	v_fmac_f32_e32 v147, v114, v120
	v_mul_f32_e32 v114, 0xbfb8aa3b, v115
	v_exp_f32_e32 v114, v114
	v_and_b32_e32 v115, 0xffff0000, v148
	v_add_f32_e32 v114, 1.0, v114
	v_rcp_f32_e32 v114, v114
	s_nop 0
	v_fmac_f32_e32 v158, v114, v115
	v_mul_f32_e32 v114, 0xbfb8aa3b, v116
	v_exp_f32_e32 v114, v114
	v_lshlrev_b32_e32 v115, 16, v149
	v_cvt_pk_bf16_f32 v120, v147, v158
	v_add_f32_e32 v114, 1.0, v114
	v_rcp_f32_e32 v114, v114
	s_nop 0
	v_fmac_f32_e32 v159, v114, v115
	v_mul_f32_e32 v114, 0xbfb8aa3b, v117
	v_exp_f32_e32 v114, v114
	v_and_b32_e32 v115, 0xffff0000, v149
	v_add_f32_e32 v114, 1.0, v114
	v_rcp_f32_e32 v114, v114
	s_nop 0
	v_fmac_f32_e32 v160, v114, v115
	v_lshlrev_b32_e32 v114, 16, v120
	v_and_b32_e32 v115, 0xffff0000, v120
	v_sub_f32_e32 v114, v147, v114
	v_sub_f32_e32 v115, v158, v115
	v_cvt_pk_bf16_f32 v121, v159, v160
	v_cvt_pk_bf16_f32 v128, v114, v115
	s_nop 0
	v_lshlrev_b32_e32 v114, 16, v121
	v_and_b32_e32 v115, 0xffff0000, v121
	v_sub_f32_e32 v114, v159, v114
	v_sub_f32_e32 v115, v160, v115
	v_cvt_pk_bf16_f32 v129, v114, v115
	v_mul_f32_e32 v114, v158, v158
	v_mul_f32_e32 v115, v160, v160
	v_fmac_f32_e32 v114, v147, v147
	v_fmac_f32_e32 v115, v159, v159
	v_add_f32_e32 v114, v114, v115
	v_add_f32_e32 v114, v114, v146
	ds_bpermute_b32 v115, v191, v114
	global_store_dwordx4 v[122:123], v[118:121], off offset:256
	global_store_dwordx4 v[124:125], v[126:129], off offset:256
	s_waitcnt lgkmcnt(0)
	v_add_f32_e32 v114, v114, v115
	ds_bpermute_b32 v115, v224, v114
	s_and_saveexec_b64 s[4:5], s[40:41]
	s_cbranch_execz .LBB0_162
	v_lshlrev_b64 v[116:117], 6, v[192:193]
	v_lshl_add_u64 v[116:117], s[62:63], 0, v[116:117]
	v_lshl_add_u64 v[116:117], s[44:45], 2, v[116:117]
	s_lshl_b32 s24, s20, 2
	v_lshl_add_u64 v[116:117], v[116:117], 0, s[24:25]
	s_waitcnt lgkmcnt(0)
	v_add_f32_e32 v114, v114, v115
	global_store_dword v[116:117], v114, off

; #define PG8_STAGE(bufoff, gbase, voff) do { _Pragma("unroll") for (int _i = 0; _i < 2; ++_i) \
;         __builtin_amdgcn_global_load_lds((const unsigned*)((const char*)(gbase) + (voff)[_i]), (LAS unsigned*)(lds + (bufoff) + ldsw + _i * 8192), 16, 0, 0); } while (0)
; #define PG8_LDA(dst, b, h) do { _Pragma("unroll") for (int m = 0; m < 4; ++m) _Pragma("unroll") for (int k = 0; k < 2; ++k) dst[m][k] = *(const LAS bf16x8*)(lds + PG8_SA(b, h) + aoff + m * 2048 + k * 1024); } while (0)
; #define PG8_LDB(dst, b, h) do { _Pragma("unroll") for (int n = 0; n < 2; ++n) _Pragma("unroll") for (int k = 0; k < 2; ++k) dst[n][k] = *(const LAS bf16x8*)(lds + PG8_SB(b, h) + boff + n * 2048 + k * 1024); } while (0)
; #define PG8_MMA(ai, bj, At, Bt) do { __builtin_amdgcn_s_setprio(1); _Pragma("unroll") for (int m = 0; m < 4; ++m) _Pragma("unroll") for (int n = 0; n < 2; ++n) _Pragma("unroll") for (int k = 0; k < 2; ++k) \
;         acc[ai][bj][m][n] = __builtin_amdgcn_mfma_f32_16x16x32_bf16(Bt[n][k], At[m][k], acc[ai][bj][m][n], 0, 0, 0); __builtin_amdgcn_s_setprio(0); } while (0)
; #define PG8_WAIT_V(n) asm volatile("s_waitcnt vmcnt(" #n ")" ::: "memory")
; #define PG8_WAIT_L(n) asm volatile("s_waitcnt lgkmcnt(" #n ")" ::: "memory")
; #define PG8_BAR __builtin_amdgcn_s_barrier()
; #define PG8_SCHED __builtin_amdgcn_sched_barrier(0)
; template <int MODE, class EpiT, class Sched>
; __device__ __forceinline__ void gemm_phase(LAS unsigned char* lds, const Gemm g, const Sched& S, const EpiT& E) {
;     ...
;             PG8_LDB(B0, 0, 0); PG8_SCHED; PG8_LDA(At, 0, 0); PG8_STAGE(PG8_SA(1, 1), a1 + hstep, voffA);
;             PG8_WAIT_L(8); PG8_BAR; PG8_WAIT_L(0); PG8_MMA(0, 0, At, B0); PG8_BAR; PG8_SCHED;
;             PG8_LDB(B1, 0, 1); PG8_STAGE(PG8_SB(0, 0), b2, voffB);
;             PG8_BAR; PG8_WAIT_L(0); PG8_MMA(0, 1, At, B1); PG8_BAR;
;             PG8_LDA(At, 0, 1); PG8_STAGE(PG8_SA(0, 0), a2, voffA);
;             PG8_BAR; PG8_WAIT_L(0); PG8_MMA(1, 0, At, B0); PG8_BAR; PG8_SCHED;
;             PG8_STAGE(PG8_SB(0, 1), b2 + hstep, voffB);
;             PG8_WAIT_V(6); PG8_BAR; PG8_MMA(1, 1, At, B1); PG8_BAR;
.LBB0_195:
	s_add_i32 vcc_lo, s44, 2
	s_add_u32 s52, s4, 0x80
	s_addc_u32 s45, s5, 0
	s_add_u32 s100, s4, s38
	s_addc_u32 s101, s5, 0
	ds_read_b128 v[58:61], v249
	ds_read_b128 v[62:65], v249 offset:1024
	ds_read_b128 v[70:73], v249 offset:2048
	ds_read_b128 v[74:77], v249 offset:3072
	s_cmp_eq_u32 s75, s44
	s_cselect_b32 s44, s68, s52
	s_cselect_b32 s45, s69, s45
	s_cselect_b32 s53, s47, s90
	s_cselect_b32 s52, s46, s89
	s_add_i32 m0, s21, 0xc000
	ds_read_b128 v[138:141], v196
	global_load_lds_dwordx4 v0, s[100:101]
	s_add_i32 m0, s21, 0xe000
	ds_read_b128 v[184:187], v196 offset:7168
	global_load_lds_dwordx4 v174, s[100:101]
	ds_read_b128 v[142:145], v196 offset:1024
	ds_read_b128 v[146:149], v196 offset:2048
	ds_read_b128 v[150:153], v196 offset:3072
	ds_read_b128 v[162:165], v196 offset:4096
	ds_read_b128 v[166:169], v196 offset:5120
	ds_read_b128 v[170:173], v196 offset:6144
	s_waitcnt lgkmcnt(8)
	s_barrier
	s_waitcnt lgkmcnt(0)
	v_mfma_f32_16x16x32_bf16 v[158:161], v[58:61], v[138:141], v[158:161]
	v_mfma_f32_16x16x32_bf16 v[154:157], v[70:73], v[138:141], v[154:157]
	v_mfma_f32_16x16x32_bf16 v[126:129], v[58:61], v[146:149], v[126:129]
	v_mfma_f32_16x16x32_bf16 v[122:125], v[70:73], v[146:149], v[122:125]
	v_mfma_f32_16x16x32_bf16 v[110:113], v[58:61], v[162:165], v[110:113]
	v_mfma_f32_16x16x32_bf16 v[106:109], v[70:73], v[162:165], v[106:109]
	v_mfma_f32_16x16x32_bf16 v[94:97], v[58:61], v[170:173], v[94:97]
	v_mfma_f32_16x16x32_bf16 v[90:93], v[70:73], v[170:173], v[90:93]
	v_mfma_f32_16x16x32_bf16 v[158:161], v[62:65], v[142:145], v[158:161]
	v_mfma_f32_16x16x32_bf16 v[154:157], v[74:77], v[142:145], v[154:157]
	v_mfma_f32_16x16x32_bf16 v[126:129], v[62:65], v[150:153], v[126:129]
	v_mfma_f32_16x16x32_bf16 v[122:125], v[74:77], v[150:153], v[122:125]
	v_mfma_f32_16x16x32_bf16 v[110:113], v[62:65], v[166:169], v[110:113]
	v_mfma_f32_16x16x32_bf16 v[106:109], v[74:77], v[166:169], v[106:109]
	v_mfma_f32_16x16x32_bf16 v[94:97], v[62:65], v[184:187], v[94:97]
	v_mfma_f32_16x16x32_bf16 v[90:93], v[74:77], v[184:187], v[90:93]
	s_barrier
	ds_read_b128 v[188:191], v249 offset:16384
	ds_read_b128 v[220:223], v249 offset:17408
	ds_read_b128 v[224:227], v249 offset:18432
	ds_read_b128 v[228:231], v249 offset:19456
	s_add_u32 s98, s52, 0x80
	s_addc_u32 s99, s53, 0
	s_add_i32 m0, s20, 0x10000
	s_nop 0
	global_load_lds_dwordx4 v0, s[52:53]
	s_add_i32 m0, s20, 0x12000
	s_nop 0
	global_load_lds_dwordx4 v174, s[52:53]
	s_barrier
	s_waitcnt lgkmcnt(0)
	v_mfma_f32_16x16x32_bf16 v[134:137], v[188:191], v[138:141], v[134:137]
	v_mfma_f32_16x16x32_bf16 v[130:133], v[224:227], v[138:141], v[130:133]
	v_mfma_f32_16x16x32_bf16 v[118:121], v[188:191], v[146:149], v[118:121]
	v_mfma_f32_16x16x32_bf16 v[114:117], v[224:227], v[146:149], v[114:117]
	v_mfma_f32_16x16x32_bf16 v[102:105], v[188:191], v[162:165], v[102:105]
	v_mfma_f32_16x16x32_bf16 v[98:101], v[224:227], v[162:165], v[98:101]
	v_mfma_f32_16x16x32_bf16 v[86:89], v[188:191], v[170:173], v[86:89]
	v_mfma_f32_16x16x32_bf16 v[82:85], v[224:227], v[170:173], v[82:85]
	v_mfma_f32_16x16x32_bf16 v[134:137], v[220:223], v[142:145], v[134:137]
	v_mfma_f32_16x16x32_bf16 v[130:133], v[228:231], v[142:145], v[130:133]
	v_mfma_f32_16x16x32_bf16 v[118:121], v[220:223], v[150:153], v[118:121]
	v_mfma_f32_16x16x32_bf16 v[114:117], v[228:231], v[150:153], v[114:117]
	v_mfma_f32_16x16x32_bf16 v[102:105], v[220:223], v[166:169], v[102:105]
	v_mfma_f32_16x16x32_bf16 v[98:101], v[228:231], v[166:169], v[98:101]
	v_mfma_f32_16x16x32_bf16 v[86:89], v[220:223], v[184:187], v[86:89]
	v_mfma_f32_16x16x32_bf16 v[82:85], v[228:231], v[184:187], v[82:85]
	s_barrier
	s_mov_b32 m0, s21
	s_add_u32 s100, s44, 0x80
	s_addc_u32 s101, s45, 0
	ds_read_b128 v[138:141], v196 offset:16384
	global_load_lds_dwordx4 v0, s[44:45]
	s_mov_b32 m0, s50
	ds_read_b128 v[184:187], v196 offset:23552
	global_load_lds_dwordx4 v174, s[44:45]
	ds_read_b128 v[142:145], v196 offset:17408
	ds_read_b128 v[146:149], v196 offset:18432
	ds_read_b128 v[150:153], v196 offset:19456
	ds_read_b128 v[162:165], v196 offset:20480
	ds_read_b128 v[166:169], v196 offset:21504
	ds_read_b128 v[170:173], v196 offset:22528
	s_barrier
	s_waitcnt lgkmcnt(0)
	v_mfma_f32_16x16x32_bf16 v[78:81], v[58:61], v[138:141], v[78:81]
	v_mfma_f32_16x16x32_bf16 v[66:69], v[70:73], v[138:141], v[66:69]
	v_mfma_f32_16x16x32_bf16 v[46:49], v[58:61], v[146:149], v[46:49]
	v_mfma_f32_16x16x32_bf16 v[42:45], v[70:73], v[146:149], v[42:45]
	v_mfma_f32_16x16x32_bf16 v[30:33], v[58:61], v[162:165], v[30:33]
	v_mfma_f32_16x16x32_bf16 v[26:29], v[70:73], v[162:165], v[26:29]
	v_mfma_f32_16x16x32_bf16 v[14:17], v[58:61], v[170:173], v[14:17]
	v_mfma_f32_16x16x32_bf16 v[10:13], v[70:73], v[170:173], v[10:13]
	v_mfma_f32_16x16x32_bf16 v[78:81], v[62:65], v[142:145], v[78:81]
	v_mfma_f32_16x16x32_bf16 v[66:69], v[74:77], v[142:145], v[66:69]
	v_mfma_f32_16x16x32_bf16 v[46:49], v[62:65], v[150:153], v[46:49]
	v_mfma_f32_16x16x32_bf16 v[42:45], v[74:77], v[150:153], v[42:45]
	v_mfma_f32_16x16x32_bf16 v[30:33], v[62:65], v[166:169], v[30:33]
	v_mfma_f32_16x16x32_bf16 v[26:29], v[74:77], v[166:169], v[26:29]
	v_mfma_f32_16x16x32_bf16 v[14:17], v[62:65], v[184:187], v[14:17]
	v_mfma_f32_16x16x32_bf16 v[10:13], v[74:77], v[184:187], v[10:13]
	s_barrier
	s_add_u32 s52, s52, s38
	s_addc_u32 s53, s53, 0
	s_add_i32 m0, s20, 0x14000
	s_nop 0
	global_load_lds_dwordx4 v0, s[52:53]
	s_add_i32 m0, s20, 0x16000
	s_nop 0
	global_load_lds_dwordx4 v174, s[52:53]
	s_waitcnt vmcnt(6)
	s_barrier
; #define PG8_STAGE(bufoff, gbase, voff) do { _Pragma("unroll") for (int _i = 0; _i < 2; ++_i) \
;         __builtin_amdgcn_global_load_lds((const unsigned*)((const char*)(gbase) + (voff)[_i]), (LAS unsigned*)(lds + (bufoff) + ldsw + _i * 8192), 16, 0, 0); } while (0)
; #define PG8_LDA(dst, b, h) do { _Pragma("unroll") for (int m = 0; m < 4; ++m) _Pragma("unroll") for (int k = 0; k < 2; ++k) dst[m][k] = *(const LAS bf16x8*)(lds + PG8_SA(b, h) + aoff + m * 2048 + k * 1024); } while (0)
; #define PG8_LDB(dst, b, h) do { _Pragma("unroll") for (int n = 0; n < 2; ++n) _Pragma("unroll") for (int k = 0; k < 2; ++k) dst[n][k] = *(const LAS bf16x8*)(lds + PG8_SB(b, h) + boff + n * 2048 + k * 1024); } while (0)
; #define PG8_MMA(ai, bj, At, Bt) do { __builtin_amdgcn_s_setprio(1); _Pragma("unroll") for (int m = 0; m < 4; ++m) _Pragma("unroll") for (int n = 0; n < 2; ++n) _Pragma("unroll") for (int k = 0; k < 2; ++k) \
;         acc[ai][bj][m][n] = __builtin_amdgcn_mfma_f32_16x16x32_bf16(Bt[n][k], At[m][k], acc[ai][bj][m][n], 0, 0, 0); __builtin_amdgcn_s_setprio(0); } while (0)
; #define PG8_WAIT_V(n) asm volatile("s_waitcnt vmcnt(" #n ")" ::: "memory")
; #define PG8_WAIT_L(n) asm volatile("s_waitcnt lgkmcnt(" #n ")" ::: "memory")
; #define PG8_BAR __builtin_amdgcn_s_barrier()
; #define PG8_SCHED __builtin_amdgcn_sched_barrier(0)
; template <int MODE, class EpiT, class Sched>
; __device__ __forceinline__ void gemm_phase(LAS unsigned char* lds, const Gemm g, const Sched& S, const EpiT& E) {
;     ...
;             PG8_WAIT_V(6); PG8_BAR; PG8_MMA(1, 1, At, B1); PG8_BAR;
;             PG8_LDB(B0, 1, 0); PG8_SCHED; PG8_LDA(At, 1, 0); PG8_STAGE(PG8_SA(0, 1), a2 + hstep, voffA);
;             PG8_WAIT_L(8); PG8_BAR; PG8_WAIT_L(0); PG8_MMA(0, 0, At, B0); PG8_BAR; PG8_SCHED;
;             PG8_LDB(B1, 1, 1); PG8_STAGE(PG8_SB(1, 0), b3, voffB);
;             PG8_BAR; PG8_WAIT_L(0); PG8_MMA(0, 1, At, B1); PG8_BAR;
;             PG8_LDA(At, 1, 1); PG8_STAGE(PG8_SA(1, 0), a3, voffA);
;             PG8_BAR; PG8_WAIT_L(0); PG8_MMA(1, 0, At, B0); PG8_BAR; PG8_SCHED;
	v_mfma_f32_16x16x32_bf16 v[54:57], v[188:191], v[138:141], v[54:57]
	v_mfma_f32_16x16x32_bf16 v[50:53], v[224:227], v[138:141], v[50:53]
	v_mfma_f32_16x16x32_bf16 v[38:41], v[188:191], v[146:149], v[38:41]
	v_mfma_f32_16x16x32_bf16 v[34:37], v[224:227], v[146:149], v[34:37]
	v_mfma_f32_16x16x32_bf16 v[22:25], v[188:191], v[162:165], v[22:25]
	v_mfma_f32_16x16x32_bf16 v[18:21], v[224:227], v[162:165], v[18:21]
	v_mfma_f32_16x16x32_bf16 v[6:9], v[188:191], v[170:173], v[6:9]
	v_mfma_f32_16x16x32_bf16 v[2:5], v[224:227], v[170:173], v[2:5]
	v_mfma_f32_16x16x32_bf16 v[54:57], v[220:223], v[142:145], v[54:57]
	v_mfma_f32_16x16x32_bf16 v[50:53], v[228:231], v[142:145], v[50:53]
	v_mfma_f32_16x16x32_bf16 v[38:41], v[220:223], v[150:153], v[38:41]
	v_mfma_f32_16x16x32_bf16 v[34:37], v[228:231], v[150:153], v[34:37]
	v_mfma_f32_16x16x32_bf16 v[22:25], v[220:223], v[166:169], v[22:25]
	v_mfma_f32_16x16x32_bf16 v[18:21], v[228:231], v[166:169], v[18:21]
	v_mfma_f32_16x16x32_bf16 v[6:9], v[220:223], v[184:187], v[6:9]
	v_mfma_f32_16x16x32_bf16 v[2:5], v[228:231], v[184:187], v[2:5]
	s_barrier
	ds_read_b128 v[58:61], v249 offset:32768
	ds_read_b128 v[62:65], v249 offset:33792
	ds_read_b128 v[70:73], v249 offset:34816
	ds_read_b128 v[74:77], v249 offset:35840
	s_add_u32 s44, s44, s38
	s_addc_u32 s45, s45, 0
	s_mov_b32 m0, s51
	ds_read_b128 v[138:141], v196 offset:32768
	global_load_lds_dwordx4 v0, s[44:45]
	s_mov_b32 m0, s56
	ds_read_b128 v[184:187], v196 offset:39936
	global_load_lds_dwordx4 v174, s[44:45]
	ds_read_b128 v[142:145], v196 offset:33792
	ds_read_b128 v[146:149], v196 offset:34816
	ds_read_b128 v[150:153], v196 offset:35840
	ds_read_b128 v[162:165], v196 offset:36864
	ds_read_b128 v[166:169], v196 offset:37888
	ds_read_b128 v[170:173], v196 offset:38912
	s_waitcnt lgkmcnt(8)
	s_barrier
	s_waitcnt lgkmcnt(0)
	v_mfma_f32_16x16x32_bf16 v[158:161], v[58:61], v[138:141], v[158:161]
	v_mfma_f32_16x16x32_bf16 v[154:157], v[70:73], v[138:141], v[154:157]
	v_mfma_f32_16x16x32_bf16 v[126:129], v[58:61], v[146:149], v[126:129]
	v_mfma_f32_16x16x32_bf16 v[122:125], v[70:73], v[146:149], v[122:125]
	v_mfma_f32_16x16x32_bf16 v[110:113], v[58:61], v[162:165], v[110:113]
	v_mfma_f32_16x16x32_bf16 v[106:109], v[70:73], v[162:165], v[106:109]
	v_mfma_f32_16x16x32_bf16 v[94:97], v[58:61], v[170:173], v[94:97]
	v_mfma_f32_16x16x32_bf16 v[90:93], v[70:73], v[170:173], v[90:93]
	v_mfma_f32_16x16x32_bf16 v[158:161], v[62:65], v[142:145], v[158:161]
	v_mfma_f32_16x16x32_bf16 v[154:157], v[74:77], v[142:145], v[154:157]
	v_mfma_f32_16x16x32_bf16 v[126:129], v[62:65], v[150:153], v[126:129]
	v_mfma_f32_16x16x32_bf16 v[122:125], v[74:77], v[150:153], v[122:125]
	v_mfma_f32_16x16x32_bf16 v[110:113], v[62:65], v[166:169], v[110:113]
	v_mfma_f32_16x16x32_bf16 v[106:109], v[74:77], v[166:169], v[106:109]
	v_mfma_f32_16x16x32_bf16 v[94:97], v[62:65], v[184:187], v[94:97]
	v_mfma_f32_16x16x32_bf16 v[90:93], v[74:77], v[184:187], v[90:93]
	s_barrier
	s_add_i32 m0, s20, 0x18000
	ds_read_b128 v[188:191], v249 offset:49152
	global_load_lds_dwordx4 v0, s[98:99]
	s_add_i32 m0, s20, 0x1a000
	ds_read_b128 v[228:231], v249 offset:52224
	global_load_lds_dwordx4 v174, s[98:99]
	ds_read_b128 v[220:223], v249 offset:50176
	ds_read_b128 v[224:227], v249 offset:51200
	s_barrier
	s_waitcnt lgkmcnt(0)
	v_mfma_f32_16x16x32_bf16 v[134:137], v[188:191], v[138:141], v[134:137]
	v_mfma_f32_16x16x32_bf16 v[130:133], v[224:227], v[138:141], v[130:133]
	v_mfma_f32_16x16x32_bf16 v[118:121], v[188:191], v[146:149], v[118:121]
	v_mfma_f32_16x16x32_bf16 v[114:117], v[224:227], v[146:149], v[114:117]
	v_mfma_f32_16x16x32_bf16 v[102:105], v[188:191], v[162:165], v[102:105]
	v_mfma_f32_16x16x32_bf16 v[98:101], v[224:227], v[162:165], v[98:101]
	v_mfma_f32_16x16x32_bf16 v[86:89], v[188:191], v[170:173], v[86:89]
	v_mfma_f32_16x16x32_bf16 v[82:85], v[224:227], v[170:173], v[82:85]
	v_mfma_f32_16x16x32_bf16 v[134:137], v[220:223], v[142:145], v[134:137]
	v_mfma_f32_16x16x32_bf16 v[130:133], v[228:231], v[142:145], v[130:133]
	v_mfma_f32_16x16x32_bf16 v[118:121], v[220:223], v[150:153], v[118:121]
	v_mfma_f32_16x16x32_bf16 v[114:117], v[228:231], v[150:153], v[114:117]
	v_mfma_f32_16x16x32_bf16 v[102:105], v[220:223], v[166:169], v[102:105]
	v_mfma_f32_16x16x32_bf16 v[98:101], v[228:231], v[166:169], v[98:101]
	v_mfma_f32_16x16x32_bf16 v[86:89], v[220:223], v[184:187], v[86:89]
	v_mfma_f32_16x16x32_bf16 v[82:85], v[228:231], v[184:187], v[82:85]
	s_barrier
; #define PG8_STAGE(bufoff, gbase, voff) do { _Pragma("unroll") for (int _i = 0; _i < 2; ++_i) \
;         __builtin_amdgcn_global_load_lds((const unsigned*)((const char*)(gbase) + (voff)[_i]), (LAS unsigned*)(lds + (bufoff) + ldsw + _i * 8192), 16, 0, 0); } while (0)
; #define PG8_LDA(dst, b, h) do { _Pragma("unroll") for (int m = 0; m < 4; ++m) _Pragma("unroll") for (int k = 0; k < 2; ++k) dst[m][k] = *(const LAS bf16x8*)(lds + PG8_SA(b, h) + aoff + m * 2048 + k * 1024); } while (0)
; #define PG8_LDB(dst, b, h) do { _Pragma("unroll") for (int n = 0; n < 2; ++n) _Pragma("unroll") for (int k = 0; k < 2; ++k) dst[n][k] = *(const LAS bf16x8*)(lds + PG8_SB(b, h) + boff + n * 2048 + k * 1024); } while (0)
; #define PG8_MMA(ai, bj, At, Bt) do { __builtin_amdgcn_s_setprio(1); _Pragma("unroll") for (int m = 0; m < 4; ++m) _Pragma("unroll") for (int n = 0; n < 2; ++n) _Pragma("unroll") for (int k = 0; k < 2; ++k) \
;         acc[ai][bj][m][n] = __builtin_amdgcn_mfma_f32_16x16x32_bf16(Bt[n][k], At[m][k], acc[ai][bj][m][n], 0, 0, 0); __builtin_amdgcn_s_setprio(0); } while (0)
; #define PG8_WAIT_V(n) asm volatile("s_waitcnt vmcnt(" #n ")" ::: "memory")
; #define PG8_WAIT_L(n) asm volatile("s_waitcnt lgkmcnt(" #n ")" ::: "memory")
; #define PG8_BAR __builtin_amdgcn_s_barrier()
; #define PG8_SCHED __builtin_amdgcn_sched_barrier(0)
; template <int MODE, class EpiT, class Sched>
; __device__ __forceinline__ void gemm_phase(LAS unsigned char* lds, const Gemm g, const Sched& S, const EpiT& E) {
;     ...
;             PG8_LDB(B1, 1, 1); PG8_STAGE(PG8_SB(1, 0), b3, voffB);
;             PG8_BAR; PG8_WAIT_L(0); PG8_MMA(0, 1, At, B1); PG8_BAR;
;             PG8_LDA(At, 1, 1); PG8_STAGE(PG8_SA(1, 0), a3, voffA);
;             PG8_BAR; PG8_WAIT_L(0); PG8_MMA(1, 0, At, B0); PG8_BAR; PG8_SCHED;
;             PG8_STAGE(PG8_SB(1, 1), b3 + hstep, voffB);
;             PG8_WAIT_V(6); PG8_BAR; PG8_MMA(1, 1, At, B1); PG8_BAR;
;         }
;         E.template run<MODE>(acc, cur, wr, wc, fr, fq, SC + ui * 256);
;         if (!has_next) break;
	s_mov_b32 m0, s61
	ds_read_b128 v[138:141], v196 offset:49152
	global_load_lds_dwordx4 v0, s[100:101]
	s_mov_b32 m0, s74
	ds_read_b128 v[184:187], v196 offset:56320
	global_load_lds_dwordx4 v174, s[100:101]
	ds_read_b128 v[142:145], v196 offset:50176
	ds_read_b128 v[146:149], v196 offset:51200
	ds_read_b128 v[150:153], v196 offset:52224
	ds_read_b128 v[162:165], v196 offset:53248
	ds_read_b128 v[166:169], v196 offset:54272
	ds_read_b128 v[170:173], v196 offset:55296
	s_barrier
	s_waitcnt lgkmcnt(0)
	v_mfma_f32_16x16x32_bf16 v[78:81], v[58:61], v[138:141], v[78:81]
	v_mfma_f32_16x16x32_bf16 v[66:69], v[70:73], v[138:141], v[66:69]
	v_mfma_f32_16x16x32_bf16 v[46:49], v[58:61], v[146:149], v[46:49]
	v_mfma_f32_16x16x32_bf16 v[42:45], v[70:73], v[146:149], v[42:45]
	v_mfma_f32_16x16x32_bf16 v[30:33], v[58:61], v[162:165], v[30:33]
	v_mfma_f32_16x16x32_bf16 v[26:29], v[70:73], v[162:165], v[26:29]
	v_mfma_f32_16x16x32_bf16 v[14:17], v[58:61], v[170:173], v[14:17]
	v_mfma_f32_16x16x32_bf16 v[10:13], v[70:73], v[170:173], v[10:13]
	v_mfma_f32_16x16x32_bf16 v[78:81], v[62:65], v[142:145], v[78:81]
	v_mfma_f32_16x16x32_bf16 v[66:69], v[74:77], v[142:145], v[66:69]
	v_mfma_f32_16x16x32_bf16 v[46:49], v[62:65], v[150:153], v[46:49]
	v_mfma_f32_16x16x32_bf16 v[42:45], v[74:77], v[150:153], v[42:45]
	v_mfma_f32_16x16x32_bf16 v[30:33], v[62:65], v[166:169], v[30:33]
	v_mfma_f32_16x16x32_bf16 v[26:29], v[74:77], v[166:169], v[26:29]
	v_mfma_f32_16x16x32_bf16 v[14:17], v[62:65], v[184:187], v[14:17]
	v_mfma_f32_16x16x32_bf16 v[10:13], v[74:77], v[184:187], v[10:13]
	s_barrier
	s_add_u32 s98, s98, s38
	s_addc_u32 s99, s99, 0
	s_add_i32 m0, s20, 0x1c000
	s_nop 0
	global_load_lds_dwordx4 v0, s[98:99]
	s_add_i32 m0, s20, 0x1e000
	s_nop 0
	global_load_lds_dwordx4 v174, s[98:99]
	s_waitcnt vmcnt(6)
	s_barrier
	v_mfma_f32_16x16x32_bf16 v[54:57], v[188:191], v[138:141], v[54:57]
	v_mfma_f32_16x16x32_bf16 v[50:53], v[224:227], v[138:141], v[50:53]
	v_mfma_f32_16x16x32_bf16 v[38:41], v[188:191], v[146:149], v[38:41]
	v_mfma_f32_16x16x32_bf16 v[34:37], v[224:227], v[146:149], v[34:37]
	v_mfma_f32_16x16x32_bf16 v[22:25], v[188:191], v[162:165], v[22:25]
	v_mfma_f32_16x16x32_bf16 v[18:21], v[224:227], v[162:165], v[18:21]
	v_mfma_f32_16x16x32_bf16 v[6:9], v[188:191], v[170:173], v[6:9]
	v_mfma_f32_16x16x32_bf16 v[2:5], v[224:227], v[170:173], v[2:5]
	v_mfma_f32_16x16x32_bf16 v[54:57], v[220:223], v[142:145], v[54:57]
	v_mfma_f32_16x16x32_bf16 v[50:53], v[228:231], v[142:145], v[50:53]
	v_mfma_f32_16x16x32_bf16 v[38:41], v[220:223], v[150:153], v[38:41]
	v_mfma_f32_16x16x32_bf16 v[34:37], v[228:231], v[150:153], v[34:37]
	v_mfma_f32_16x16x32_bf16 v[22:25], v[220:223], v[166:169], v[22:25]
	v_mfma_f32_16x16x32_bf16 v[18:21], v[228:231], v[166:169], v[18:21]
	v_mfma_f32_16x16x32_bf16 v[6:9], v[220:223], v[184:187], v[6:9]
	v_mfma_f32_16x16x32_bf16 v[2:5], v[228:231], v[184:187], v[2:5]
	s_barrier
	s_add_u32 s4, s4, 0x100
	s_addc_u32 s5, s5, 0
	s_add_u32 s89, s89, 0x100
	s_addc_u32 s90, s90, 0
	s_cmp_ge_u32 vcc_lo, s60
	s_mov_b32 s44, vcc_lo
	s_cbranch_scc0 .LBB0_195
	v_lshl_or_b32 v186, s24, 8, v195
	v_ashrrev_i32_e32 v187, 31, v186
	v_mov_b32_e32 v70, 0
	v_cndmask_b32_e64 v58, 0, 1, s[78:79]
	v_lshl_add_u64 v[138:139], v[186:187], 2, s[12:13]
	v_cmp_ne_u32_e64 s[44:45], 1, v58
	s_andn2_b64 vcc, exec, s[78:79]
	v_mov_b32_e32 v74, 0
	v_mov_b32_e32 v75, v70
	v_mov_b32_e32 v184, 0
	v_mov_b32_e32 v185, v70
	s_cbranch_vccnz .LBB0_198
	global_load_dwordx4 v[74:77], v[138:139], off
	s_waitcnt vmcnt(0)
	v_mov_b32_e32 v184, v76
	v_mov_b32_e32 v185, v77

; #define PG8_STAGE(bufoff, gbase, voff) do { _Pragma("unroll") for (int _i = 0; _i < 2; ++_i) \
;         __builtin_amdgcn_global_load_lds((const unsigned*)((const char*)(gbase) + (voff)[_i]), (LAS unsigned*)(lds + (bufoff) + ldsw + _i * 8192), 16, 0, 0); } while (0)
; #define PG8_LDA(dst, b, h) do { _Pragma("unroll") for (int m = 0; m < 4; ++m) _Pragma("unroll") for (int k = 0; k < 2; ++k) dst[m][k] = *(const LAS bf16x8*)(lds + PG8_SA(b, h) + aoff + m * 2048 + k * 1024); } while (0)
; #define PG8_LDB(dst, b, h) do { _Pragma("unroll") for (int n = 0; n < 2; ++n) _Pragma("unroll") for (int k = 0; k < 2; ++k) dst[n][k] = *(const LAS bf16x8*)(lds + PG8_SB(b, h) + boff + n * 2048 + k * 1024); } while (0)
; #define PG8_MMA(ai, bj, At, Bt) do { __builtin_amdgcn_s_setprio(1); _Pragma("unroll") for (int m = 0; m < 4; ++m) _Pragma("unroll") for (int n = 0; n < 2; ++n) _Pragma("unroll") for (int k = 0; k < 2; ++k) \
;         acc[ai][bj][m][n] = __builtin_amdgcn_mfma_f32_16x16x32_bf16(Bt[n][k], At[m][k], acc[ai][bj][m][n], 0, 0, 0); __builtin_amdgcn_s_setprio(0); } while (0)
; #define PG8_WAIT_V(n) asm volatile("s_waitcnt vmcnt(" #n ")" ::: "memory")
; #define PG8_WAIT_L(n) asm volatile("s_waitcnt lgkmcnt(" #n ")" ::: "memory")
; #define PG8_BAR __builtin_amdgcn_s_barrier()
; #define PG8_SCHED __builtin_amdgcn_sched_barrier(0)
; template <int MODE, class EpiT, class Sched>
; __device__ __forceinline__ void gemm_phase(LAS unsigned char* lds, const Gemm g, const Sched& S, const EpiT& E) {
;     ...
;             PG8_LDB(B0, 0, 0); PG8_SCHED; PG8_LDA(At, 0, 0); PG8_STAGE(PG8_SA(1, 1), a1 + hstep, voffA);
;             PG8_WAIT_L(8); PG8_BAR; PG8_WAIT_L(0); PG8_MMA(0, 0, At, B0); PG8_BAR; PG8_SCHED;
;             PG8_LDB(B1, 0, 1); PG8_STAGE(PG8_SB(0, 0), b2, voffB);
;             PG8_BAR; PG8_WAIT_L(0); PG8_MMA(0, 1, At, B1); PG8_BAR;
;             PG8_LDA(At, 0, 1); PG8_STAGE(PG8_SA(0, 0), a2, voffA);
;             PG8_BAR; PG8_WAIT_L(0); PG8_MMA(1, 0, At, B0); PG8_BAR; PG8_SCHED;
;             PG8_STAGE(PG8_SB(0, 1), b2 + hstep, voffB);
;             PG8_WAIT_V(6); PG8_BAR; PG8_MMA(1, 1, At, B1); PG8_BAR;
;             PG8_LDB(B0, 1, 0); PG8_SCHED; PG8_LDA(At, 1, 0); PG8_STAGE(PG8_SA(0, 1), a2 + hstep, voffA);
;             PG8_WAIT_L(8); PG8_BAR; PG8_WAIT_L(0); PG8_MMA(0, 0, At, B0); PG8_BAR; PG8_SCHED;
.LBB0_280:
	s_add_i32 s68, s46, 2
	s_add_u32 s52, s10, s44
	s_addc_u32 s47, s11, s45
	s_add_u32 s58, s4, s44
	s_addc_u32 s53, s5, s45
	s_add_u32 s100, s10, s44
	s_addc_u32 s101, s11, s45
	s_add_u32 s100, s100, s22
	s_addc_u32 s101, s101, 0
	s_sub_u32 s100, s100, 0x80
	s_subb_u32 s101, s101, 0
	s_add_i32 s59, 0, 0x10000
	ds_read_b128 v[134:137], v250
	ds_read_b128 v[138:141], v250 offset:1024
	ds_read_b128 v[142:145], v250 offset:2048
	ds_read_b128 v[152:155], v250 offset:3072
	s_cmp_eq_u32 s60, s46
	s_cselect_b32 s46, s34, s52
	s_cselect_b32 s47, s35, s47
	s_cselect_b32 s53, s39, s53
	s_cselect_b32 s52, s38, s58
	s_add_i32 m0, s30, 0xc000
	ds_read_b128 v[162:165], v160
	global_load_lds_dwordx4 v0, s[100:101]
	s_add_i32 m0, s30, 0xe000
	ds_read_b128 v[194:197], v160 offset:7168
	global_load_lds_dwordx4 v146, s[100:101]
	ds_read_b128 v[166:169], v160 offset:1024
	ds_read_b128 v[170:173], v160 offset:2048
	ds_read_b128 v[174:177], v160 offset:3072
	ds_read_b128 v[182:185], v160 offset:4096
	ds_read_b128 v[186:189], v160 offset:5120
	ds_read_b128 v[190:193], v160 offset:6144
	s_waitcnt lgkmcnt(8)
	s_barrier
	s_waitcnt lgkmcnt(0)
	v_mfma_f32_16x16x32_bf16 v[126:129], v[134:137], v[162:165], v[126:129]
	v_mfma_f32_16x16x32_bf16 v[122:125], v[142:145], v[162:165], v[122:125]
	v_mfma_f32_16x16x32_bf16 v[118:121], v[134:137], v[170:173], v[118:121]
	v_mfma_f32_16x16x32_bf16 v[114:117], v[142:145], v[170:173], v[114:117]
	v_mfma_f32_16x16x32_bf16 v[110:113], v[134:137], v[182:185], v[110:113]
	v_mfma_f32_16x16x32_bf16 v[106:109], v[142:145], v[182:185], v[106:109]
	v_mfma_f32_16x16x32_bf16 v[102:105], v[134:137], v[190:193], v[102:105]
	v_mfma_f32_16x16x32_bf16 v[98:101], v[142:145], v[190:193], v[98:101]
	v_mfma_f32_16x16x32_bf16 v[126:129], v[138:141], v[166:169], v[126:129]
	v_mfma_f32_16x16x32_bf16 v[122:125], v[152:155], v[166:169], v[122:125]
	v_mfma_f32_16x16x32_bf16 v[118:121], v[138:141], v[174:177], v[118:121]
	v_mfma_f32_16x16x32_bf16 v[114:117], v[152:155], v[174:177], v[114:117]
	v_mfma_f32_16x16x32_bf16 v[110:113], v[138:141], v[186:189], v[110:113]
	v_mfma_f32_16x16x32_bf16 v[106:109], v[152:155], v[186:189], v[106:109]
	v_mfma_f32_16x16x32_bf16 v[102:105], v[138:141], v[194:197], v[102:105]
	v_mfma_f32_16x16x32_bf16 v[98:101], v[152:155], v[194:197], v[98:101]
	s_barrier
	s_add_i32 s58, 0, 0x14000
	s_add_i32 s59, s59, s24
	s_add_u32 s98, s52, 0x80
	s_addc_u32 s99, s53, 0
	s_mov_b32 m0, s59
	ds_read_b128 v[220:223], v250 offset:16384
	global_load_lds_dwordx4 v0, s[52:53]
	s_add_i32 m0, s59, 0x2000
	ds_read_b128 v[232:235], v250 offset:19456
	global_load_lds_dwordx4 v146, s[52:53]
	ds_read_b128 v[224:227], v250 offset:17408
	ds_read_b128 v[228:231], v250 offset:18432
	s_barrier
	s_waitcnt lgkmcnt(0)
	v_mfma_f32_16x16x32_bf16 v[94:97], v[220:223], v[162:165], v[94:97]
	v_mfma_f32_16x16x32_bf16 v[90:93], v[228:231], v[162:165], v[90:93]
	v_mfma_f32_16x16x32_bf16 v[86:89], v[220:223], v[170:173], v[86:89]
	v_mfma_f32_16x16x32_bf16 v[82:85], v[228:231], v[170:173], v[82:85]
	v_mfma_f32_16x16x32_bf16 v[78:81], v[220:223], v[182:185], v[78:81]
	v_mfma_f32_16x16x32_bf16 v[74:77], v[228:231], v[182:185], v[74:77]
	v_mfma_f32_16x16x32_bf16 v[70:73], v[220:223], v[190:193], v[70:73]
	v_mfma_f32_16x16x32_bf16 v[66:69], v[228:231], v[190:193], v[66:69]
	v_mfma_f32_16x16x32_bf16 v[94:97], v[224:227], v[166:169], v[94:97]
	v_mfma_f32_16x16x32_bf16 v[90:93], v[232:235], v[166:169], v[90:93]
	v_mfma_f32_16x16x32_bf16 v[86:89], v[224:227], v[174:177], v[86:89]
	v_mfma_f32_16x16x32_bf16 v[82:85], v[232:235], v[174:177], v[82:85]
	v_mfma_f32_16x16x32_bf16 v[78:81], v[224:227], v[186:189], v[78:81]
	v_mfma_f32_16x16x32_bf16 v[74:77], v[232:235], v[186:189], v[74:77]
	v_mfma_f32_16x16x32_bf16 v[70:73], v[224:227], v[194:197], v[70:73]
	v_mfma_f32_16x16x32_bf16 v[66:69], v[232:235], v[194:197], v[66:69]
	s_barrier
	s_mov_b32 m0, s30
	s_add_u32 s100, s46, 0x80
	s_addc_u32 s101, s47, 0
	ds_read_b128 v[162:165], v160 offset:16384
	global_load_lds_dwordx4 v0, s[46:47]
	s_mov_b32 m0, s50
	ds_read_b128 v[194:197], v160 offset:23552
	global_load_lds_dwordx4 v146, s[46:47]
	ds_read_b128 v[166:169], v160 offset:17408
	ds_read_b128 v[170:173], v160 offset:18432
	ds_read_b128 v[174:177], v160 offset:19456
	ds_read_b128 v[182:185], v160 offset:20480
	ds_read_b128 v[186:189], v160 offset:21504
	ds_read_b128 v[190:193], v160 offset:22528
	s_barrier
	s_waitcnt lgkmcnt(0)
	v_mfma_f32_16x16x32_bf16 v[62:65], v[134:137], v[162:165], v[62:65]
	v_mfma_f32_16x16x32_bf16 v[58:61], v[142:145], v[162:165], v[58:61]
	v_mfma_f32_16x16x32_bf16 v[54:57], v[134:137], v[170:173], v[54:57]
	v_mfma_f32_16x16x32_bf16 v[50:53], v[142:145], v[170:173], v[50:53]
	v_mfma_f32_16x16x32_bf16 v[46:49], v[134:137], v[182:185], v[46:49]
	v_mfma_f32_16x16x32_bf16 v[42:45], v[142:145], v[182:185], v[42:45]
	v_mfma_f32_16x16x32_bf16 v[38:41], v[134:137], v[190:193], v[38:41]
	v_mfma_f32_16x16x32_bf16 v[34:37], v[142:145], v[190:193], v[34:37]
	v_mfma_f32_16x16x32_bf16 v[62:65], v[138:141], v[166:169], v[62:65]
	v_mfma_f32_16x16x32_bf16 v[58:61], v[152:155], v[166:169], v[58:61]
	v_mfma_f32_16x16x32_bf16 v[54:57], v[138:141], v[174:177], v[54:57]
	v_mfma_f32_16x16x32_bf16 v[50:53], v[152:155], v[174:177], v[50:53]
	v_mfma_f32_16x16x32_bf16 v[46:49], v[138:141], v[186:189], v[46:49]
	v_mfma_f32_16x16x32_bf16 v[42:45], v[152:155], v[186:189], v[42:45]
	v_mfma_f32_16x16x32_bf16 v[38:41], v[138:141], v[194:197], v[38:41]
	v_mfma_f32_16x16x32_bf16 v[34:37], v[152:155], v[194:197], v[34:37]
	s_barrier
; #define PG8_STAGE(bufoff, gbase, voff) do { _Pragma("unroll") for (int _i = 0; _i < 2; ++_i) \
;         __builtin_amdgcn_global_load_lds((const unsigned*)((const char*)(gbase) + (voff)[_i]), (LAS unsigned*)(lds + (bufoff) + ldsw + _i * 8192), 16, 0, 0); } while (0)
; #define PG8_LDA(dst, b, h) do { _Pragma("unroll") for (int m = 0; m < 4; ++m) _Pragma("unroll") for (int k = 0; k < 2; ++k) dst[m][k] = *(const LAS bf16x8*)(lds + PG8_SA(b, h) + aoff + m * 2048 + k * 1024); } while (0)
; #define PG8_LDB(dst, b, h) do { _Pragma("unroll") for (int n = 0; n < 2; ++n) _Pragma("unroll") for (int k = 0; k < 2; ++k) dst[n][k] = *(const LAS bf16x8*)(lds + PG8_SB(b, h) + boff + n * 2048 + k * 1024); } while (0)
; #define PG8_MMA(ai, bj, At, Bt) do { __builtin_amdgcn_s_setprio(1); _Pragma("unroll") for (int m = 0; m < 4; ++m) _Pragma("unroll") for (int n = 0; n < 2; ++n) _Pragma("unroll") for (int k = 0; k < 2; ++k) \
;         acc[ai][bj][m][n] = __builtin_amdgcn_mfma_f32_16x16x32_bf16(Bt[n][k], At[m][k], acc[ai][bj][m][n], 0, 0, 0); __builtin_amdgcn_s_setprio(0); } while (0)
; #define PG8_WAIT_V(n) asm volatile("s_waitcnt vmcnt(" #n ")" ::: "memory")
; #define PG8_WAIT_L(n) asm volatile("s_waitcnt lgkmcnt(" #n ")" ::: "memory")
; #define PG8_BAR __builtin_amdgcn_s_barrier()
; #define PG8_SCHED __builtin_amdgcn_sched_barrier(0)
; template <int MODE, class EpiT, class Sched>
; __device__ __forceinline__ void gemm_phase(LAS unsigned char* lds, const Gemm g, const Sched& S, const EpiT& E) {
;     ...
;             PG8_WAIT_V(6); PG8_BAR; PG8_MMA(1, 1, At, B1); PG8_BAR;
;             PG8_LDB(B0, 1, 0); PG8_SCHED; PG8_LDA(At, 1, 0); PG8_STAGE(PG8_SA(0, 1), a2 + hstep, voffA);
;             PG8_WAIT_L(8); PG8_BAR; PG8_WAIT_L(0); PG8_MMA(0, 0, At, B0); PG8_BAR; PG8_SCHED;
;             PG8_LDB(B1, 1, 1); PG8_STAGE(PG8_SB(1, 0), b3, voffB);
;             PG8_BAR; PG8_WAIT_L(0); PG8_MMA(0, 1, At, B1); PG8_BAR;
;             PG8_LDA(At, 1, 1); PG8_STAGE(PG8_SA(1, 0), a3, voffA);
;             PG8_BAR; PG8_WAIT_L(0); PG8_MMA(1, 0, At, B0); PG8_BAR; PG8_SCHED;
	s_add_u32 s52, s52, s22
	s_addc_u32 s53, s53, 0
	s_add_i32 s58, s58, s24
	s_mov_b32 m0, s58
	s_nop 0
	global_load_lds_dwordx4 v0, s[52:53]
	s_add_i32 m0, s58, 0x2000
	s_nop 0
	global_load_lds_dwordx4 v146, s[52:53]
	s_waitcnt vmcnt(6)
	s_barrier
	v_mfma_f32_16x16x32_bf16 v[30:33], v[220:223], v[162:165], v[30:33]
	v_mfma_f32_16x16x32_bf16 v[26:29], v[228:231], v[162:165], v[26:29]
	v_mfma_f32_16x16x32_bf16 v[22:25], v[220:223], v[170:173], v[22:25]
	v_mfma_f32_16x16x32_bf16 v[18:21], v[228:231], v[170:173], v[18:21]
	v_mfma_f32_16x16x32_bf16 v[14:17], v[220:223], v[182:185], v[14:17]
	v_mfma_f32_16x16x32_bf16 v[10:13], v[228:231], v[182:185], v[10:13]
	v_mfma_f32_16x16x32_bf16 v[6:9], v[220:223], v[190:193], v[6:9]
	v_mfma_f32_16x16x32_bf16 v[2:5], v[228:231], v[190:193], v[2:5]
	v_mfma_f32_16x16x32_bf16 v[30:33], v[224:227], v[166:169], v[30:33]
	v_mfma_f32_16x16x32_bf16 v[26:29], v[232:235], v[166:169], v[26:29]
	v_mfma_f32_16x16x32_bf16 v[22:25], v[224:227], v[174:177], v[22:25]
	v_mfma_f32_16x16x32_bf16 v[18:21], v[232:235], v[174:177], v[18:21]
	v_mfma_f32_16x16x32_bf16 v[14:17], v[224:227], v[186:189], v[14:17]
	v_mfma_f32_16x16x32_bf16 v[10:13], v[232:235], v[186:189], v[10:13]
	v_mfma_f32_16x16x32_bf16 v[6:9], v[224:227], v[194:197], v[6:9]
	v_mfma_f32_16x16x32_bf16 v[2:5], v[232:235], v[194:197], v[2:5]
	s_barrier
	s_add_i32 s52, 0, 0x18000
	ds_read_b128 v[134:137], v250 offset:32768
	ds_read_b128 v[138:141], v250 offset:33792
	ds_read_b128 v[142:145], v250 offset:34816
	ds_read_b128 v[152:155], v250 offset:35840
	s_add_u32 s46, s46, s22
	s_addc_u32 s47, s47, 0
	s_mov_b32 m0, s51
	ds_read_b128 v[162:165], v160 offset:32768
	global_load_lds_dwordx4 v0, s[46:47]
	s_mov_b32 m0, s54
	ds_read_b128 v[194:197], v160 offset:39936
	global_load_lds_dwordx4 v146, s[46:47]
	ds_read_b128 v[166:169], v160 offset:33792
	ds_read_b128 v[170:173], v160 offset:34816
	ds_read_b128 v[174:177], v160 offset:35840
	ds_read_b128 v[182:185], v160 offset:36864
	ds_read_b128 v[186:189], v160 offset:37888
	ds_read_b128 v[190:193], v160 offset:38912
	s_waitcnt lgkmcnt(8)
	s_barrier
	s_waitcnt lgkmcnt(0)
	v_mfma_f32_16x16x32_bf16 v[126:129], v[134:137], v[162:165], v[126:129]
	v_mfma_f32_16x16x32_bf16 v[122:125], v[142:145], v[162:165], v[122:125]
	v_mfma_f32_16x16x32_bf16 v[118:121], v[134:137], v[170:173], v[118:121]
	v_mfma_f32_16x16x32_bf16 v[114:117], v[142:145], v[170:173], v[114:117]
	v_mfma_f32_16x16x32_bf16 v[110:113], v[134:137], v[182:185], v[110:113]
	v_mfma_f32_16x16x32_bf16 v[106:109], v[142:145], v[182:185], v[106:109]
	v_mfma_f32_16x16x32_bf16 v[102:105], v[134:137], v[190:193], v[102:105]
	v_mfma_f32_16x16x32_bf16 v[98:101], v[142:145], v[190:193], v[98:101]
	v_mfma_f32_16x16x32_bf16 v[126:129], v[138:141], v[166:169], v[126:129]
	v_mfma_f32_16x16x32_bf16 v[122:125], v[152:155], v[166:169], v[122:125]
	v_mfma_f32_16x16x32_bf16 v[118:121], v[138:141], v[174:177], v[118:121]
	v_mfma_f32_16x16x32_bf16 v[114:117], v[152:155], v[174:177], v[114:117]
	v_mfma_f32_16x16x32_bf16 v[110:113], v[138:141], v[186:189], v[110:113]
	v_mfma_f32_16x16x32_bf16 v[106:109], v[152:155], v[186:189], v[106:109]
	v_mfma_f32_16x16x32_bf16 v[102:105], v[138:141], v[194:197], v[102:105]
	v_mfma_f32_16x16x32_bf16 v[98:101], v[152:155], v[194:197], v[98:101]
	s_barrier
	s_add_i32 s46, 0, 0x1c000
	s_add_i32 s47, s52, s24
	s_mov_b32 m0, s47
	ds_read_b128 v[220:223], v250 offset:49152
	global_load_lds_dwordx4 v0, s[98:99]
	s_add_i32 m0, s47, 0x2000
	ds_read_b128 v[232:235], v250 offset:52224
	global_load_lds_dwordx4 v146, s[98:99]
	ds_read_b128 v[224:227], v250 offset:50176
	ds_read_b128 v[228:231], v250 offset:51200
	s_barrier
; #define PG8_STAGE(bufoff, gbase, voff) do { _Pragma("unroll") for (int _i = 0; _i < 2; ++_i) \
;         __builtin_amdgcn_global_load_lds((const unsigned*)((const char*)(gbase) + (voff)[_i]), (LAS unsigned*)(lds + (bufoff) + ldsw + _i * 8192), 16, 0, 0); } while (0)
; #define PG8_LDA(dst, b, h) do { _Pragma("unroll") for (int m = 0; m < 4; ++m) _Pragma("unroll") for (int k = 0; k < 2; ++k) dst[m][k] = *(const LAS bf16x8*)(lds + PG8_SA(b, h) + aoff + m * 2048 + k * 1024); } while (0)
; #define PG8_MMA(ai, bj, At, Bt) do { __builtin_amdgcn_s_setprio(1); _Pragma("unroll") for (int m = 0; m < 4; ++m) _Pragma("unroll") for (int n = 0; n < 2; ++n) _Pragma("unroll") for (int k = 0; k < 2; ++k) \
;         acc[ai][bj][m][n] = __builtin_amdgcn_mfma_f32_16x16x32_bf16(Bt[n][k], At[m][k], acc[ai][bj][m][n], 0, 0, 0); __builtin_amdgcn_s_setprio(0); } while (0)
; #define PG8_WAIT_V(n) asm volatile("s_waitcnt vmcnt(" #n ")" ::: "memory")
; #define PG8_WAIT_L(n) asm volatile("s_waitcnt lgkmcnt(" #n ")" ::: "memory")
; #define PG8_BAR __builtin_amdgcn_s_barrier()
; #define PG8_SCHED __builtin_amdgcn_sched_barrier(0)
; template <int MODE, class EpiT, class Sched>
; __device__ __forceinline__ void gemm_phase(LAS unsigned char* lds, const Gemm g, const Sched& S, const EpiT& E) {
;     ...
;             PG8_BAR; PG8_WAIT_L(0); PG8_MMA(0, 1, At, B1); PG8_BAR;
;             PG8_LDA(At, 1, 1); PG8_STAGE(PG8_SA(1, 0), a3, voffA);
;             PG8_BAR; PG8_WAIT_L(0); PG8_MMA(1, 0, At, B0); PG8_BAR; PG8_SCHED;
;             PG8_STAGE(PG8_SB(1, 1), b3 + hstep, voffB);
;             PG8_WAIT_V(6); PG8_BAR; PG8_MMA(1, 1, At, B1); PG8_BAR;
;         }
;         E.template run<MODE>(acc, cur, wr, wc, fr, fq, SC + ui * 256);
;         if (!has_next) break;
	s_waitcnt lgkmcnt(0)
	v_mfma_f32_16x16x32_bf16 v[94:97], v[220:223], v[162:165], v[94:97]
	v_mfma_f32_16x16x32_bf16 v[90:93], v[228:231], v[162:165], v[90:93]
	v_mfma_f32_16x16x32_bf16 v[86:89], v[220:223], v[170:173], v[86:89]
	v_mfma_f32_16x16x32_bf16 v[82:85], v[228:231], v[170:173], v[82:85]
	v_mfma_f32_16x16x32_bf16 v[78:81], v[220:223], v[182:185], v[78:81]
	v_mfma_f32_16x16x32_bf16 v[74:77], v[228:231], v[182:185], v[74:77]
	v_mfma_f32_16x16x32_bf16 v[70:73], v[220:223], v[190:193], v[70:73]
	v_mfma_f32_16x16x32_bf16 v[66:69], v[228:231], v[190:193], v[66:69]
	v_mfma_f32_16x16x32_bf16 v[94:97], v[224:227], v[166:169], v[94:97]
	v_mfma_f32_16x16x32_bf16 v[90:93], v[232:235], v[166:169], v[90:93]
	v_mfma_f32_16x16x32_bf16 v[86:89], v[224:227], v[174:177], v[86:89]
	v_mfma_f32_16x16x32_bf16 v[82:85], v[232:235], v[174:177], v[82:85]
	v_mfma_f32_16x16x32_bf16 v[78:81], v[224:227], v[186:189], v[78:81]
	v_mfma_f32_16x16x32_bf16 v[74:77], v[232:235], v[186:189], v[74:77]
	v_mfma_f32_16x16x32_bf16 v[70:73], v[224:227], v[194:197], v[70:73]
	v_mfma_f32_16x16x32_bf16 v[66:69], v[232:235], v[194:197], v[66:69]
	s_barrier
	s_mov_b32 m0, s56
	ds_read_b128 v[162:165], v160 offset:49152
	global_load_lds_dwordx4 v0, s[100:101]
	s_mov_b32 m0, s57
	ds_read_b128 v[194:197], v160 offset:56320
	global_load_lds_dwordx4 v146, s[100:101]
	ds_read_b128 v[166:169], v160 offset:50176
	ds_read_b128 v[170:173], v160 offset:51200
	ds_read_b128 v[174:177], v160 offset:52224
	ds_read_b128 v[182:185], v160 offset:53248
	ds_read_b128 v[186:189], v160 offset:54272
	ds_read_b128 v[190:193], v160 offset:55296
	s_barrier
	s_waitcnt lgkmcnt(0)
	v_mfma_f32_16x16x32_bf16 v[62:65], v[134:137], v[162:165], v[62:65]
	v_mfma_f32_16x16x32_bf16 v[58:61], v[142:145], v[162:165], v[58:61]
	v_mfma_f32_16x16x32_bf16 v[54:57], v[134:137], v[170:173], v[54:57]
	v_mfma_f32_16x16x32_bf16 v[50:53], v[142:145], v[170:173], v[50:53]
	v_mfma_f32_16x16x32_bf16 v[46:49], v[134:137], v[182:185], v[46:49]
	v_mfma_f32_16x16x32_bf16 v[42:45], v[142:145], v[182:185], v[42:45]
	v_mfma_f32_16x16x32_bf16 v[38:41], v[134:137], v[190:193], v[38:41]
	v_mfma_f32_16x16x32_bf16 v[34:37], v[142:145], v[190:193], v[34:37]
	v_mfma_f32_16x16x32_bf16 v[62:65], v[138:141], v[166:169], v[62:65]
	v_mfma_f32_16x16x32_bf16 v[58:61], v[152:155], v[166:169], v[58:61]
	v_mfma_f32_16x16x32_bf16 v[54:57], v[138:141], v[174:177], v[54:57]
	v_mfma_f32_16x16x32_bf16 v[50:53], v[152:155], v[174:177], v[50:53]
	v_mfma_f32_16x16x32_bf16 v[46:49], v[138:141], v[186:189], v[46:49]
	v_mfma_f32_16x16x32_bf16 v[42:45], v[152:155], v[186:189], v[42:45]
	v_mfma_f32_16x16x32_bf16 v[38:41], v[138:141], v[194:197], v[38:41]
	v_mfma_f32_16x16x32_bf16 v[34:37], v[152:155], v[194:197], v[34:37]
	s_barrier
	s_add_i32 s46, s46, s24
	s_add_u32 s98, s98, s22
	s_addc_u32 s99, s99, 0
	s_mov_b32 m0, s46
	s_nop 0
	global_load_lds_dwordx4 v0, s[98:99]
	s_add_i32 m0, s46, 0x2000
	s_nop 0
	global_load_lds_dwordx4 v146, s[98:99]
	s_waitcnt vmcnt(6)
	s_barrier
	v_mfma_f32_16x16x32_bf16 v[30:33], v[220:223], v[162:165], v[30:33]
	v_mfma_f32_16x16x32_bf16 v[26:29], v[228:231], v[162:165], v[26:29]
	v_mfma_f32_16x16x32_bf16 v[22:25], v[220:223], v[170:173], v[22:25]
	v_mfma_f32_16x16x32_bf16 v[18:21], v[228:231], v[170:173], v[18:21]
	v_mfma_f32_16x16x32_bf16 v[14:17], v[220:223], v[182:185], v[14:17]
	v_mfma_f32_16x16x32_bf16 v[10:13], v[228:231], v[182:185], v[10:13]
	v_mfma_f32_16x16x32_bf16 v[6:9], v[220:223], v[190:193], v[6:9]
	v_mfma_f32_16x16x32_bf16 v[2:5], v[228:231], v[190:193], v[2:5]
	v_mfma_f32_16x16x32_bf16 v[30:33], v[224:227], v[166:169], v[30:33]
	v_mfma_f32_16x16x32_bf16 v[26:29], v[232:235], v[166:169], v[26:29]
	v_mfma_f32_16x16x32_bf16 v[22:25], v[224:227], v[174:177], v[22:25]
	v_mfma_f32_16x16x32_bf16 v[18:21], v[232:235], v[174:177], v[18:21]
	v_mfma_f32_16x16x32_bf16 v[14:17], v[224:227], v[186:189], v[14:17]
	v_mfma_f32_16x16x32_bf16 v[10:13], v[232:235], v[186:189], v[10:13]
	v_mfma_f32_16x16x32_bf16 v[6:9], v[224:227], v[194:197], v[6:9]
	v_mfma_f32_16x16x32_bf16 v[2:5], v[232:235], v[194:197], v[2:5]
	s_barrier
	s_add_u32 s44, s44, 0x100
	s_addc_u32 s45, s45, 0
	s_cmp_ge_u32 s68, s55
	s_mov_b32 s46, s68
	s_cbranch_scc0 .LBB0_280
	v_lshl_or_b32 v152, s3, 8, v159
	v_ashrrev_i32_e32 v153, 31, v152
	v_cndmask_b32_e64 v131, 0, 1, s[28:29]
	v_lshl_add_u64 v[154:155], v[152:153], 2, s[12:13]
	v_mov_b32_e32 v130, 0
	v_cmp_ne_u32_e64 s[44:45], 1, v131
	s_andn2_b64 vcc, exec, s[28:29]
	v_mov_b32_e32 v134, 0
	v_mov_b32_e32 v135, 0
	v_mov_b32_e32 v136, 0
	v_mov_b32_e32 v137, 0
	s_cbranch_vccnz .LBB0_283
	global_load_dwordx4 v[134:137], v[154:155], off

; #define PG8_STAGE(bufoff, gbase, voff) do { _Pragma("unroll") for (int _i = 0; _i < 2; ++_i) \
;         __builtin_amdgcn_global_load_lds((const unsigned*)((const char*)(gbase) + (voff)[_i]), (LAS unsigned*)(lds + (bufoff) + ldsw + _i * 8192), 16, 0, 0); } while (0)
; #define PG8_LDA(dst, b, h) do { _Pragma("unroll") for (int m = 0; m < 4; ++m) _Pragma("unroll") for (int k = 0; k < 2; ++k) dst[m][k] = *(const LAS bf16x8*)(lds + PG8_SA(b, h) + aoff + m * 2048 + k * 1024); } while (0)
; #define PG8_LDB(dst, b, h) do { _Pragma("unroll") for (int n = 0; n < 2; ++n) _Pragma("unroll") for (int k = 0; k < 2; ++k) dst[n][k] = *(const LAS bf16x8*)(lds + PG8_SB(b, h) + boff + n * 2048 + k * 1024); } while (0)
; #define PG8_MMA(ai, bj, At, Bt) do { __builtin_amdgcn_s_setprio(1); _Pragma("unroll") for (int m = 0; m < 4; ++m) _Pragma("unroll") for (int n = 0; n < 2; ++n) _Pragma("unroll") for (int k = 0; k < 2; ++k) \
;         acc[ai][bj][m][n] = __builtin_amdgcn_mfma_f32_16x16x32_bf16(Bt[n][k], At[m][k], acc[ai][bj][m][n], 0, 0, 0); __builtin_amdgcn_s_setprio(0); } while (0)
; #define PG8_WAIT_V(n) asm volatile("s_waitcnt vmcnt(" #n ")" ::: "memory")
; #define PG8_WAIT_L(n) asm volatile("s_waitcnt lgkmcnt(" #n ")" ::: "memory")
; #define PG8_BAR __builtin_amdgcn_s_barrier()
; #define PG8_SCHED __builtin_amdgcn_sched_barrier(0)
; template <int MODE, class EpiT, class Sched>
; __device__ __forceinline__ void gemm_phase(LAS unsigned char* lds, const Gemm g, const Sched& S, const EpiT& E) {
;     ...
;             PG8_LDB(B0, 0, 0); PG8_SCHED; PG8_LDA(At, 0, 0); PG8_STAGE(PG8_SA(1, 1), a1 + hstep, voffA);
;             PG8_WAIT_L(8); PG8_BAR; PG8_WAIT_L(0); PG8_MMA(0, 0, At, B0); PG8_BAR; PG8_SCHED;
;             PG8_LDB(B1, 0, 1); PG8_STAGE(PG8_SB(0, 0), b2, voffB);
;             PG8_BAR; PG8_WAIT_L(0); PG8_MMA(0, 1, At, B1); PG8_BAR;
;             PG8_LDA(At, 0, 1); PG8_STAGE(PG8_SA(0, 0), a2, voffA);
;             PG8_BAR; PG8_WAIT_L(0); PG8_MMA(1, 0, At, B0); PG8_BAR; PG8_SCHED;
;             PG8_STAGE(PG8_SB(0, 1), b2 + hstep, voffB);
;             PG8_WAIT_V(6); PG8_BAR; PG8_MMA(1, 1, At, B1); PG8_BAR;
.LBB0_332:
	s_add_i32 s23, s22, 2
	s_add_u32 s30, s12, s4
	s_addc_u32 s38, s13, s5
	s_add_u32 s44, s10, s4
	s_addc_u32 s45, s11, s5
	ds_read_b128 v[146:149], v145
	ds_read_b128 v[150:153], v145 offset:1024
	ds_read_b128 v[154:157], v145 offset:2048
	ds_read_b128 v[158:161], v145 offset:3072
	s_cmp_eq_u32 s55, s22
	s_cselect_b32 s39, s29, s38
	s_cselect_b32 s38, s28, s30
	s_cselect_b32 s45, s35, s45
	s_cselect_b32 s44, s34, s44
	s_add_i32 m0, s47, 0xc000
	ds_read_b128 v[162:165], v144
	global_load_lds_dwordx4 v0, s[100:101]
	s_add_i32 m0, s47, 0xe000
	ds_read_b128 v[194:197], v144 offset:7168
	global_load_lds_dwordx4 v130, s[100:101]
	ds_read_b128 v[166:169], v144 offset:1024
	ds_read_b128 v[170:173], v144 offset:2048
	ds_read_b128 v[174:177], v144 offset:3072
	ds_read_b128 v[182:185], v144 offset:4096
	ds_read_b128 v[186:189], v144 offset:5120
	ds_read_b128 v[190:193], v144 offset:6144
	s_waitcnt lgkmcnt(8)
	s_barrier
	s_waitcnt lgkmcnt(0)
	v_mfma_f32_16x16x32_bf16 v[126:129], v[146:149], v[162:165], v[126:129]
	v_mfma_f32_16x16x32_bf16 v[122:125], v[154:157], v[162:165], v[122:125]
	v_mfma_f32_16x16x32_bf16 v[118:121], v[146:149], v[170:173], v[118:121]
	v_mfma_f32_16x16x32_bf16 v[114:117], v[154:157], v[170:173], v[114:117]
	v_mfma_f32_16x16x32_bf16 v[110:113], v[146:149], v[182:185], v[110:113]
	v_mfma_f32_16x16x32_bf16 v[106:109], v[154:157], v[182:185], v[106:109]
	v_mfma_f32_16x16x32_bf16 v[102:105], v[146:149], v[190:193], v[102:105]
	v_mfma_f32_16x16x32_bf16 v[98:101], v[154:157], v[190:193], v[98:101]
	v_mfma_f32_16x16x32_bf16 v[126:129], v[150:153], v[166:169], v[126:129]
	v_mfma_f32_16x16x32_bf16 v[122:125], v[158:161], v[166:169], v[122:125]
	v_mfma_f32_16x16x32_bf16 v[118:121], v[150:153], v[174:177], v[118:121]
	v_mfma_f32_16x16x32_bf16 v[114:117], v[158:161], v[174:177], v[114:117]
	v_mfma_f32_16x16x32_bf16 v[110:113], v[150:153], v[186:189], v[110:113]
	v_mfma_f32_16x16x32_bf16 v[106:109], v[158:161], v[186:189], v[106:109]
	v_mfma_f32_16x16x32_bf16 v[102:105], v[150:153], v[194:197], v[102:105]
	v_mfma_f32_16x16x32_bf16 v[98:101], v[158:161], v[194:197], v[98:101]
	s_barrier
	s_add_u32 s98, s44, 0x80
	s_addc_u32 s99, s45, 0
	s_add_i32 m0, s46, 0x10000
	ds_read_b128 v[220:223], v145 offset:16384
	global_load_lds_dwordx4 v0, s[44:45]
	s_add_i32 m0, s46, 0x12000
	ds_read_b128 v[232:235], v145 offset:19456
	global_load_lds_dwordx4 v130, s[44:45]
	ds_read_b128 v[224:227], v145 offset:17408
	ds_read_b128 v[228:231], v145 offset:18432
	s_barrier
	s_waitcnt lgkmcnt(0)
	v_mfma_f32_16x16x32_bf16 v[94:97], v[220:223], v[162:165], v[94:97]
	v_mfma_f32_16x16x32_bf16 v[90:93], v[228:231], v[162:165], v[90:93]
	v_mfma_f32_16x16x32_bf16 v[86:89], v[220:223], v[170:173], v[86:89]
	v_mfma_f32_16x16x32_bf16 v[82:85], v[228:231], v[170:173], v[82:85]
	v_mfma_f32_16x16x32_bf16 v[78:81], v[220:223], v[182:185], v[78:81]
	v_mfma_f32_16x16x32_bf16 v[74:77], v[228:231], v[182:185], v[74:77]
	v_mfma_f32_16x16x32_bf16 v[70:73], v[220:223], v[190:193], v[70:73]
	v_mfma_f32_16x16x32_bf16 v[66:69], v[228:231], v[190:193], v[66:69]
	v_mfma_f32_16x16x32_bf16 v[94:97], v[224:227], v[166:169], v[94:97]
	v_mfma_f32_16x16x32_bf16 v[90:93], v[232:235], v[166:169], v[90:93]
	v_mfma_f32_16x16x32_bf16 v[86:89], v[224:227], v[174:177], v[86:89]
	v_mfma_f32_16x16x32_bf16 v[82:85], v[232:235], v[174:177], v[82:85]
	v_mfma_f32_16x16x32_bf16 v[78:81], v[224:227], v[186:189], v[78:81]
	v_mfma_f32_16x16x32_bf16 v[74:77], v[232:235], v[186:189], v[74:77]
	v_mfma_f32_16x16x32_bf16 v[70:73], v[224:227], v[194:197], v[70:73]
	v_mfma_f32_16x16x32_bf16 v[66:69], v[232:235], v[194:197], v[66:69]
	s_barrier
	s_mov_b32 m0, s47
	ds_read_b128 v[162:165], v144 offset:16384
	global_load_lds_dwordx4 v0, s[38:39]
	s_mov_b32 m0, s50
	ds_read_b128 v[194:197], v144 offset:23552
	global_load_lds_dwordx4 v130, s[38:39]
	ds_read_b128 v[166:169], v144 offset:17408
	ds_read_b128 v[170:173], v144 offset:18432
	ds_read_b128 v[174:177], v144 offset:19456
	ds_read_b128 v[182:185], v144 offset:20480
	ds_read_b128 v[186:189], v144 offset:21504
	ds_read_b128 v[190:193], v144 offset:22528
	s_barrier
	s_waitcnt lgkmcnt(0)
	v_mfma_f32_16x16x32_bf16 v[62:65], v[146:149], v[162:165], v[62:65]
	v_mfma_f32_16x16x32_bf16 v[58:61], v[154:157], v[162:165], v[58:61]
	v_mfma_f32_16x16x32_bf16 v[54:57], v[146:149], v[170:173], v[54:57]
	v_mfma_f32_16x16x32_bf16 v[50:53], v[154:157], v[170:173], v[50:53]
	v_mfma_f32_16x16x32_bf16 v[46:49], v[146:149], v[182:185], v[46:49]
	v_mfma_f32_16x16x32_bf16 v[42:45], v[154:157], v[182:185], v[42:45]
	v_mfma_f32_16x16x32_bf16 v[38:41], v[146:149], v[190:193], v[38:41]
	v_mfma_f32_16x16x32_bf16 v[34:37], v[154:157], v[190:193], v[34:37]
	v_mfma_f32_16x16x32_bf16 v[62:65], v[150:153], v[166:169], v[62:65]
	v_mfma_f32_16x16x32_bf16 v[58:61], v[158:161], v[166:169], v[58:61]
	v_mfma_f32_16x16x32_bf16 v[54:57], v[150:153], v[174:177], v[54:57]
	v_mfma_f32_16x16x32_bf16 v[50:53], v[158:161], v[174:177], v[50:53]
	v_mfma_f32_16x16x32_bf16 v[46:49], v[150:153], v[186:189], v[46:49]
	v_mfma_f32_16x16x32_bf16 v[42:45], v[158:161], v[186:189], v[42:45]
	v_mfma_f32_16x16x32_bf16 v[38:41], v[150:153], v[194:197], v[38:41]
	v_mfma_f32_16x16x32_bf16 v[34:37], v[158:161], v[194:197], v[34:37]
	s_barrier
	s_add_u32 s44, s44, s21
	s_addc_u32 s45, s45, 0
	s_add_i32 m0, s46, 0x14000
	s_nop 0
	global_load_lds_dwordx4 v0, s[44:45]
	s_add_i32 m0, s46, 0x16000
	s_nop 0
	global_load_lds_dwordx4 v130, s[44:45]
	s_waitcnt vmcnt(6)
	s_barrier
; #define PG8_STAGE(bufoff, gbase, voff) do { _Pragma("unroll") for (int _i = 0; _i < 2; ++_i) \
;         __builtin_amdgcn_global_load_lds((const unsigned*)((const char*)(gbase) + (voff)[_i]), (LAS unsigned*)(lds + (bufoff) + ldsw + _i * 8192), 16, 0, 0); } while (0)
; #define PG8_LDA(dst, b, h) do { _Pragma("unroll") for (int m = 0; m < 4; ++m) _Pragma("unroll") for (int k = 0; k < 2; ++k) dst[m][k] = *(const LAS bf16x8*)(lds + PG8_SA(b, h) + aoff + m * 2048 + k * 1024); } while (0)
; #define PG8_LDB(dst, b, h) do { _Pragma("unroll") for (int n = 0; n < 2; ++n) _Pragma("unroll") for (int k = 0; k < 2; ++k) dst[n][k] = *(const LAS bf16x8*)(lds + PG8_SB(b, h) + boff + n * 2048 + k * 1024); } while (0)
; #define PG8_MMA(ai, bj, At, Bt) do { __builtin_amdgcn_s_setprio(1); _Pragma("unroll") for (int m = 0; m < 4; ++m) _Pragma("unroll") for (int n = 0; n < 2; ++n) _Pragma("unroll") for (int k = 0; k < 2; ++k) \
;         acc[ai][bj][m][n] = __builtin_amdgcn_mfma_f32_16x16x32_bf16(Bt[n][k], At[m][k], acc[ai][bj][m][n], 0, 0, 0); __builtin_amdgcn_s_setprio(0); } while (0)
; #define PG8_WAIT_V(n) asm volatile("s_waitcnt vmcnt(" #n ")" ::: "memory")
; #define PG8_WAIT_L(n) asm volatile("s_waitcnt lgkmcnt(" #n ")" ::: "memory")
; #define PG8_BAR __builtin_amdgcn_s_barrier()
; #define PG8_SCHED __builtin_amdgcn_sched_barrier(0)
; template <int MODE, class EpiT, class Sched>
; __device__ __forceinline__ void gemm_phase(LAS unsigned char* lds, const Gemm g, const Sched& S, const EpiT& E) {
;     ...
;             PG8_WAIT_V(6); PG8_BAR; PG8_MMA(1, 1, At, B1); PG8_BAR;
;             PG8_LDB(B0, 1, 0); PG8_SCHED; PG8_LDA(At, 1, 0); PG8_STAGE(PG8_SA(0, 1), a2 + hstep, voffA);
;             PG8_WAIT_L(8); PG8_BAR; PG8_WAIT_L(0); PG8_MMA(0, 0, At, B0); PG8_BAR; PG8_SCHED;
;             PG8_LDB(B1, 1, 1); PG8_STAGE(PG8_SB(1, 0), b3, voffB);
;             PG8_BAR; PG8_WAIT_L(0); PG8_MMA(0, 1, At, B1); PG8_BAR;
;             PG8_LDA(At, 1, 1); PG8_STAGE(PG8_SA(1, 0), a3, voffA);
;             PG8_BAR; PG8_WAIT_L(0); PG8_MMA(1, 0, At, B0); PG8_BAR; PG8_SCHED;
	v_mfma_f32_16x16x32_bf16 v[30:33], v[220:223], v[162:165], v[30:33]
	v_mfma_f32_16x16x32_bf16 v[26:29], v[228:231], v[162:165], v[26:29]
	v_mfma_f32_16x16x32_bf16 v[22:25], v[220:223], v[170:173], v[22:25]
	v_mfma_f32_16x16x32_bf16 v[18:21], v[228:231], v[170:173], v[18:21]
	v_mfma_f32_16x16x32_bf16 v[14:17], v[220:223], v[182:185], v[14:17]
	v_mfma_f32_16x16x32_bf16 v[10:13], v[228:231], v[182:185], v[10:13]
	v_mfma_f32_16x16x32_bf16 v[6:9], v[220:223], v[190:193], v[6:9]
	v_mfma_f32_16x16x32_bf16 v[2:5], v[228:231], v[190:193], v[2:5]
	v_mfma_f32_16x16x32_bf16 v[30:33], v[224:227], v[166:169], v[30:33]
	v_mfma_f32_16x16x32_bf16 v[26:29], v[232:235], v[166:169], v[26:29]
	v_mfma_f32_16x16x32_bf16 v[22:25], v[224:227], v[174:177], v[22:25]
	v_mfma_f32_16x16x32_bf16 v[18:21], v[232:235], v[174:177], v[18:21]
	v_mfma_f32_16x16x32_bf16 v[14:17], v[224:227], v[186:189], v[14:17]
	v_mfma_f32_16x16x32_bf16 v[10:13], v[232:235], v[186:189], v[10:13]
	v_mfma_f32_16x16x32_bf16 v[6:9], v[224:227], v[194:197], v[6:9]
	v_mfma_f32_16x16x32_bf16 v[2:5], v[232:235], v[194:197], v[2:5]
	s_barrier
	ds_read_b128 v[146:149], v145 offset:32768
	ds_read_b128 v[150:153], v145 offset:33792
	ds_read_b128 v[154:157], v145 offset:34816
	ds_read_b128 v[158:161], v145 offset:35840
	s_add_u32 s38, s38, s21
	s_addc_u32 s39, s39, 0
	s_mov_b32 m0, s51
	ds_read_b128 v[162:165], v144 offset:32768
	global_load_lds_dwordx4 v0, s[38:39]
	s_mov_b32 m0, s52
	ds_read_b128 v[194:197], v144 offset:39936
	global_load_lds_dwordx4 v130, s[38:39]
	ds_read_b128 v[166:169], v144 offset:33792
	ds_read_b128 v[170:173], v144 offset:34816
	ds_read_b128 v[174:177], v144 offset:35840
	ds_read_b128 v[182:185], v144 offset:36864
	ds_read_b128 v[186:189], v144 offset:37888
	ds_read_b128 v[190:193], v144 offset:38912
	s_waitcnt lgkmcnt(8)
	s_barrier
	s_waitcnt lgkmcnt(0)
	v_mfma_f32_16x16x32_bf16 v[126:129], v[146:149], v[162:165], v[126:129]
	v_mfma_f32_16x16x32_bf16 v[122:125], v[154:157], v[162:165], v[122:125]
	v_mfma_f32_16x16x32_bf16 v[118:121], v[146:149], v[170:173], v[118:121]
	v_mfma_f32_16x16x32_bf16 v[114:117], v[154:157], v[170:173], v[114:117]
	v_mfma_f32_16x16x32_bf16 v[110:113], v[146:149], v[182:185], v[110:113]
	v_mfma_f32_16x16x32_bf16 v[106:109], v[154:157], v[182:185], v[106:109]
	v_mfma_f32_16x16x32_bf16 v[102:105], v[146:149], v[190:193], v[102:105]
	v_mfma_f32_16x16x32_bf16 v[98:101], v[154:157], v[190:193], v[98:101]
	v_mfma_f32_16x16x32_bf16 v[126:129], v[150:153], v[166:169], v[126:129]
	v_mfma_f32_16x16x32_bf16 v[122:125], v[158:161], v[166:169], v[122:125]
	v_mfma_f32_16x16x32_bf16 v[118:121], v[150:153], v[174:177], v[118:121]
	v_mfma_f32_16x16x32_bf16 v[114:117], v[158:161], v[174:177], v[114:117]
	v_mfma_f32_16x16x32_bf16 v[110:113], v[150:153], v[186:189], v[110:113]
	v_mfma_f32_16x16x32_bf16 v[106:109], v[158:161], v[186:189], v[106:109]
	v_mfma_f32_16x16x32_bf16 v[102:105], v[150:153], v[194:197], v[102:105]
	v_mfma_f32_16x16x32_bf16 v[98:101], v[158:161], v[194:197], v[98:101]
	s_barrier
	s_add_i32 m0, s46, 0x18000
	ds_read_b128 v[220:223], v145 offset:49152
	global_load_lds_dwordx4 v0, s[98:99]
	s_add_i32 m0, s46, 0x1a000
	ds_read_b128 v[232:235], v145 offset:52224
	global_load_lds_dwordx4 v130, s[98:99]
	ds_read_b128 v[224:227], v145 offset:50176
	ds_read_b128 v[228:231], v145 offset:51200
	s_barrier
	s_waitcnt lgkmcnt(0)
	v_mfma_f32_16x16x32_bf16 v[94:97], v[220:223], v[162:165], v[94:97]
	v_mfma_f32_16x16x32_bf16 v[90:93], v[228:231], v[162:165], v[90:93]
	v_mfma_f32_16x16x32_bf16 v[86:89], v[220:223], v[170:173], v[86:89]
	v_mfma_f32_16x16x32_bf16 v[82:85], v[228:231], v[170:173], v[82:85]
	v_mfma_f32_16x16x32_bf16 v[78:81], v[220:223], v[182:185], v[78:81]
	v_mfma_f32_16x16x32_bf16 v[74:77], v[228:231], v[182:185], v[74:77]
	v_mfma_f32_16x16x32_bf16 v[70:73], v[220:223], v[190:193], v[70:73]
	v_mfma_f32_16x16x32_bf16 v[66:69], v[228:231], v[190:193], v[66:69]
	v_mfma_f32_16x16x32_bf16 v[94:97], v[224:227], v[166:169], v[94:97]
	v_mfma_f32_16x16x32_bf16 v[90:93], v[232:235], v[166:169], v[90:93]
	v_mfma_f32_16x16x32_bf16 v[86:89], v[224:227], v[174:177], v[86:89]
	v_mfma_f32_16x16x32_bf16 v[82:85], v[232:235], v[174:177], v[82:85]
	v_mfma_f32_16x16x32_bf16 v[78:81], v[224:227], v[186:189], v[78:81]
	v_mfma_f32_16x16x32_bf16 v[74:77], v[232:235], v[186:189], v[74:77]
	v_mfma_f32_16x16x32_bf16 v[70:73], v[224:227], v[194:197], v[70:73]
	v_mfma_f32_16x16x32_bf16 v[66:69], v[232:235], v[194:197], v[66:69]
	s_barrier
	s_mov_b32 m0, s53
	s_sub_u32 s98, s38, s21
	s_subb_u32 s99, s39, 0
	s_add_u32 s98, s98, 0x80
	s_addc_u32 s99, s99, 0
	ds_read_b128 v[162:165], v144 offset:49152
	global_load_lds_dwordx4 v0, s[98:99]
	s_mov_b32 m0, s54
	ds_read_b128 v[194:197], v144 offset:56320
	global_load_lds_dwordx4 v130, s[98:99]
	ds_read_b128 v[166:169], v144 offset:50176
	ds_read_b128 v[170:173], v144 offset:51200
	ds_read_b128 v[174:177], v144 offset:52224
	ds_read_b128 v[182:185], v144 offset:53248
	ds_read_b128 v[186:189], v144 offset:54272
	ds_read_b128 v[190:193], v144 offset:55296
	s_barrier
	s_waitcnt lgkmcnt(0)
	v_mfma_f32_16x16x32_bf16 v[62:65], v[146:149], v[162:165], v[62:65]
	v_mfma_f32_16x16x32_bf16 v[58:61], v[154:157], v[162:165], v[58:61]
	v_mfma_f32_16x16x32_bf16 v[54:57], v[146:149], v[170:173], v[54:57]
	v_mfma_f32_16x16x32_bf16 v[50:53], v[154:157], v[170:173], v[50:53]
	v_mfma_f32_16x16x32_bf16 v[46:49], v[146:149], v[182:185], v[46:49]
	v_mfma_f32_16x16x32_bf16 v[42:45], v[154:157], v[182:185], v[42:45]
	v_mfma_f32_16x16x32_bf16 v[38:41], v[146:149], v[190:193], v[38:41]
	v_mfma_f32_16x16x32_bf16 v[34:37], v[154:157], v[190:193], v[34:37]
	v_mfma_f32_16x16x32_bf16 v[62:65], v[150:153], v[166:169], v[62:65]
	v_mfma_f32_16x16x32_bf16 v[58:61], v[158:161], v[166:169], v[58:61]
	v_mfma_f32_16x16x32_bf16 v[54:57], v[150:153], v[174:177], v[54:57]
	v_mfma_f32_16x16x32_bf16 v[50:53], v[158:161], v[174:177], v[50:53]
	v_mfma_f32_16x16x32_bf16 v[46:49], v[150:153], v[186:189], v[46:49]
	v_mfma_f32_16x16x32_bf16 v[42:45], v[158:161], v[186:189], v[42:45]
	v_mfma_f32_16x16x32_bf16 v[38:41], v[150:153], v[194:197], v[38:41]
	v_mfma_f32_16x16x32_bf16 v[34:37], v[158:161], v[194:197], v[34:37]
	s_barrier
; __device__ __forceinline__ unsigned pk2(float lo, float hi) { unsigned r; asm volatile("v_cvt_pk_bf16_f32 %0, %1, %2" : "=v"(r) : "v"(lo), "v"(hi)); return r; }
; __device__ __forceinline__ float siluf_(float x) { return x * __builtin_amdgcn_rcpf(1.0f + __expf(-x)); }
; #define PG8_STAGE(bufoff, gbase, voff) do { _Pragma("unroll") for (int _i = 0; _i < 2; ++_i) \
;         __builtin_amdgcn_global_load_lds((const unsigned*)((const char*)(gbase) + (voff)[_i]), (LAS unsigned*)(lds + (bufoff) + ldsw + _i * 8192), 16, 0, 0); } while (0)
; #define PG8_WAIT_V(n) asm volatile("s_waitcnt vmcnt(" #n ")" ::: "memory")
; #define PG8_WAIT_L(n) asm volatile("s_waitcnt lgkmcnt(" #n ")" ::: "memory")
; #define PG8_BAR __builtin_amdgcn_s_barrier()
; #define PG8_SCHED __builtin_amdgcn_sched_barrier(0)
;     template <int mode> __device__ __forceinline__ void run(const f32x4 (&acc)[2][2][4][2], const Unit& u, int wr, int wc, int fr, int fq, const LAS float* sc) const {
;     ...
;             const int col0 = u.pn * HALF + wc * 32 + 8 * fq;
; #pragma unroll
;             for (int ai = 0; ai < 2; ++ai)
; #pragma unroll
;                 for (int m = 0; m < 4; ++m) {
;                     const int row = row0 + ai * HALF + m * 16;
;                     const float s = sc[ai * HALF + wr * 64 + m * 16 + fr];
;                     const f32x4 g0 = acc[ai][0][m][0] * s, u0 = acc[ai][1][m][0] * s, g1 = acc[ai][0][m][1] * s, u1 = acc[ai][1][m][1] * s;
;                     u32x4 w;
;                     w.x = pk2(siluf_(g0[0]) * u0[0], siluf_(g0[1]) * u0[1]); w.y = pk2(siluf_(g0[2]) * u0[2], siluf_(g0[3]) * u0[3]);
;                     w.z = pk2(siluf_(g1[0]) * u1[0], siluf_(g1[1]) * u1[1]); w.w = pk2(siluf_(g1[2]) * u1[2], siluf_(g1[3]) * u1[3]);
;                     *(u32x4*)(ob + (size_t)row * FF + col0) = w;
; template <int MODE, class EpiT, class Sched>
; __device__ __forceinline__ void gemm_phase(LAS unsigned char* lds, const Gemm g, const Sched& S, const EpiT& E) {
;     ...
;             PG8_BAR; PG8_WAIT_L(0); PG8_MMA(1, 0, At, B0); PG8_BAR; PG8_SCHED;
;             PG8_STAGE(PG8_SB(1, 1), b3 + hstep, voffB);
;             PG8_WAIT_V(6); PG8_BAR; PG8_MMA(1, 1, At, B1); PG8_BAR;
;         }
;         E.template run<MODE>(acc, cur, wr, wc, fr, fq, SC + ui * 256);
;         if (!has_next) break;
	s_add_u32 s98, s44, 0x80
	s_addc_u32 s99, s45, 0
	s_add_i32 m0, s46, 0x1c000
	s_nop 0
	global_load_lds_dwordx4 v0, s[98:99]
	s_add_i32 m0, s46, 0x1e000
	s_nop 0
	global_load_lds_dwordx4 v130, s[98:99]
	s_waitcnt vmcnt(6)
	s_barrier
	v_mfma_f32_16x16x32_bf16 v[30:33], v[220:223], v[162:165], v[30:33]
	v_mfma_f32_16x16x32_bf16 v[26:29], v[228:231], v[162:165], v[26:29]
	v_mfma_f32_16x16x32_bf16 v[22:25], v[220:223], v[170:173], v[22:25]
	v_mfma_f32_16x16x32_bf16 v[18:21], v[228:231], v[170:173], v[18:21]
	v_mfma_f32_16x16x32_bf16 v[14:17], v[220:223], v[182:185], v[14:17]
	v_mfma_f32_16x16x32_bf16 v[10:13], v[228:231], v[182:185], v[10:13]
	v_mfma_f32_16x16x32_bf16 v[6:9], v[220:223], v[190:193], v[6:9]
	v_mfma_f32_16x16x32_bf16 v[2:5], v[228:231], v[190:193], v[2:5]
	v_mfma_f32_16x16x32_bf16 v[30:33], v[224:227], v[166:169], v[30:33]
	v_mfma_f32_16x16x32_bf16 v[26:29], v[232:235], v[166:169], v[26:29]
	v_mfma_f32_16x16x32_bf16 v[22:25], v[224:227], v[174:177], v[22:25]
	v_mfma_f32_16x16x32_bf16 v[18:21], v[232:235], v[174:177], v[18:21]
	v_mfma_f32_16x16x32_bf16 v[14:17], v[224:227], v[186:189], v[14:17]
	v_mfma_f32_16x16x32_bf16 v[10:13], v[232:235], v[186:189], v[10:13]
	v_mfma_f32_16x16x32_bf16 v[6:9], v[224:227], v[194:197], v[6:9]
	v_mfma_f32_16x16x32_bf16 v[2:5], v[232:235], v[194:197], v[2:5]
	s_barrier
	s_add_u32 s4, s4, 0x100
	s_addc_u32 s5, s5, 0
	s_add_u32 s100, s100, 0x100
	s_addc_u32 s101, s101, 0
	s_cmp_ge_u32 s23, s16
	s_mov_b32 s22, s23
	s_cbranch_scc0 .LBB0_332
	v_lshl_add_u32 v145, s57, 10, v142
	ds_read_b32 v136, v145
	v_lshl_or_b32 v138, s8, 7, v143
	v_lshl_add_u32 v146, s9, 8, v140
	v_ashrrev_i32_e32 v139, 31, v138
	v_lshlrev_b64 v[138:139], 1, v[138:139]
	s_waitcnt lgkmcnt(0)
	v_pk_mul_f32 v[148:149], v[126:127], v[136:137] op_sel_hi:[1,0]
	v_pk_mul_f32 v[154:155], v[94:95], v[136:137] op_sel_hi:[1,0]
	v_mul_f32_e32 v147, 0xbfb8aa3b, v148
	v_exp_f32_e32 v147, v147
	v_pk_mul_f32 v[150:151], v[128:129], v[136:137] op_sel_hi:[1,0]
	v_pk_mul_f32 v[152:153], v[96:97], v[136:137] op_sel_hi:[1,0]
	v_pk_mul_f32 v[158:159], v[122:123], v[136:137] op_sel_hi:[1,0]
	v_add_f32_e32 v147, 1.0, v147
	v_rcp_f32_e32 v147, v147
	v_pk_mul_f32 v[156:157], v[124:125], v[136:137] op_sel_hi:[1,0]
	v_pk_mul_f32 v[160:161], v[92:93], v[136:137] op_sel_hi:[1,0]
	v_pk_mul_f32 v[136:137], v[90:91], v[136:137] op_sel_hi:[1,0]
	v_mul_f32_e32 v147, v148, v147
	v_mul_f32_e32 v148, 0xbfb8aa3b, v149
	v_exp_f32_e32 v148, v148
	v_mul_f32_e32 v147, v154, v147
	s_and_b64 vcc, exec, s[42:43]
	v_add_f32_e32 v148, 1.0, v148
	v_rcp_f32_e32 v148, v148
	s_nop 0
	v_mul_f32_e32 v148, v149, v148
	v_mul_f32_e32 v148, v155, v148
	v_cvt_pk_bf16_f32 v148, v147, v148
	v_mul_f32_e32 v147, 0xbfb8aa3b, v150
	v_mul_f32_e32 v149, 0xbfb8aa3b, v151
	v_exp_f32_e32 v147, v147
	v_exp_f32_e32 v149, v149
	v_add_f32_e32 v147, 1.0, v147
	v_add_f32_e32 v149, 1.0, v149
	v_rcp_f32_e32 v147, v147
	v_rcp_f32_e32 v149, v149
	v_mul_f32_e32 v147, v150, v147
	v_mul_f32_e32 v149, v151, v149
	v_mul_f32_e32 v147, v152, v147
	v_mul_f32_e32 v149, v153, v149
	v_cvt_pk_bf16_f32 v149, v147, v149
	v_mul_f32_e32 v147, 0xbfb8aa3b, v158
	v_exp_f32_e32 v147, v147
	s_nop 0
	v_add_f32_e32 v147, 1.0, v147
	v_rcp_f32_e32 v147, v147
	s_nop 0
	v_mul_f32_e32 v147, v158, v147
	v_mul_f32_e32 v136, v136, v147
	v_mul_f32_e32 v147, 0xbfb8aa3b, v159
	v_exp_f32_e32 v147, v147
	s_nop 0
	v_add_f32_e32 v147, 1.0, v147
	v_rcp_f32_e32 v147, v147
	s_nop 0
	v_mul_f32_e32 v147, v159, v147
	v_mul_f32_e32 v137, v137, v147
	v_cvt_pk_bf16_f32 v150, v136, v137
	v_mul_f32_e32 v136, 0xbfb8aa3b, v156
	v_mul_f32_e32 v137, 0xbfb8aa3b, v157
	v_exp_f32_e32 v136, v136
	v_exp_f32_e32 v137, v137
	v_or_b32_e32 v147, 16, v146
	v_add_f32_e32 v136, 1.0, v136
	v_add_f32_e32 v137, 1.0, v137
	v_rcp_f32_e32 v136, v136
	v_rcp_f32_e32 v137, v137
	v_mul_f32_e32 v136, v156, v136
	v_mul_f32_e32 v137, v157, v137
	v_mul_f32_e32 v136, v160, v136
	v_mul_f32_e32 v137, v161, v137
	v_cvt_pk_bf16_f32 v151, v136, v137
	v_mov_b64_e32 v[136:137], s[6:7]
	v_mad_i64_i32 v[152:153], s[4:5], v146, s33, v[136:137]
	v_lshl_add_u64 v[152:153], v[152:153], 0, v[138:139]
	global_store_dwordx4 v[152:153], v[148:151], off
	ds_read_b32 v148, v145 offset:64
	s_waitcnt lgkmcnt(0)
	v_pk_mul_f32 v[152:153], v[118:119], v[148:149] op_sel_hi:[1,0]
	v_pk_mul_f32 v[150:151], v[120:121], v[148:149] op_sel_hi:[1,0]
	v_pk_mul_f32 v[154:155], v[88:89], v[148:149] op_sel_hi:[1,0]
	v_pk_mul_f32 v[156:157], v[86:87], v[148:149] op_sel_hi:[1,0]
	v_pk_mul_f32 v[158:159], v[116:117], v[148:149] op_sel_hi:[1,0]
	v_pk_mul_f32 v[160:161], v[114:115], v[148:149] op_sel_hi:[1,0]
	v_pk_mul_f32 v[162:163], v[84:85], v[148:149] op_sel_hi:[1,0]
	v_pk_mul_f32 v[164:165], v[82:83], v[148:149] op_sel_hi:[1,0]
	v_mul_f32_e32 v148, 0xbfb8aa3b, v152
	v_mul_f32_e32 v149, 0xbfb8aa3b, v153
	v_exp_f32_e32 v148, v148
	v_exp_f32_e32 v149, v149
	v_add_f32_e32 v148, 1.0, v148
	v_add_f32_e32 v149, 1.0, v149
	v_rcp_f32_e32 v148, v148
	v_rcp_f32_e32 v149, v149
	v_mul_f32_e32 v148, v152, v148
	v_mul_f32_e32 v149, v153, v149
	v_mul_f32_e32 v148, v156, v148
	v_mul_f32_e32 v149, v157, v149
	v_cvt_pk_bf16_f32 v148, v148, v149
	v_mul_f32_e32 v149, 0xbfb8aa3b, v150
	v_exp_f32_e32 v149, v149
	v_mul_f32_e32 v152, 0xbfb8aa3b, v159
	v_exp_f32_e32 v152, v152
	v_add_f32_e32 v149, 1.0, v149
	v_rcp_f32_e32 v149, v149
	v_add_f32_e32 v152, 1.0, v152
	v_rcp_f32_e32 v152, v152
	v_mul_f32_e32 v149, v150, v149
	v_mul_f32_e32 v150, 0xbfb8aa3b, v151
	v_exp_f32_e32 v150, v150
	v_mul_f32_e32 v149, v154, v149
	v_mul_f32_e32 v152, v159, v152
	v_mul_f32_e32 v152, v163, v152
	v_add_f32_e32 v150, 1.0, v150
	v_rcp_f32_e32 v150, v150
	s_nop 0
	v_mul_f32_e32 v150, v151, v150
	v_mul_f32_e32 v150, v155, v150
	v_cvt_pk_bf16_f32 v149, v149, v150
	v_mul_f32_e32 v150, 0xbfb8aa3b, v160
	v_mul_f32_e32 v151, 0xbfb8aa3b, v161
	v_exp_f32_e32 v150, v150
	v_exp_f32_e32 v151, v151
	v_add_f32_e32 v150, 1.0, v150
	v_add_f32_e32 v151, 1.0, v151
	v_rcp_f32_e32 v150, v150
	v_rcp_f32_e32 v151, v151
	v_mul_f32_e32 v150, v160, v150
	v_mul_f32_e32 v151, v161, v151
	v_mul_f32_e32 v150, v164, v150
	v_mul_f32_e32 v151, v165, v151
	v_cvt_pk_bf16_f32 v150, v150, v151
	v_mul_f32_e32 v151, 0xbfb8aa3b, v158
	v_exp_f32_e32 v151, v151
	s_nop 0
	v_add_f32_e32 v151, 1.0, v151
	v_rcp_f32_e32 v151, v151
	s_nop 0
	v_mul_f32_e32 v151, v158, v151
	v_mul_f32_e32 v151, v162, v151
	v_cvt_pk_bf16_f32 v151, v151, v152
	v_mad_i64_i32 v[152:153], s[4:5], v147, s33, v[136:137]
	v_lshl_add_u64 v[152:153], v[152:153], 0, v[138:139]
	global_store_dwordx4 v[152:153], v[148:151], off
	ds_read_b32 v148, v145 offset:128
	v_or_b32_e32 v147, 32, v146
	s_waitcnt lgkmcnt(0)
; __device__ __forceinline__ unsigned pk2(float lo, float hi) { unsigned r; asm volatile("v_cvt_pk_bf16_f32 %0, %1, %2" : "=v"(r) : "v"(lo), "v"(hi)); return r; }
; __device__ __forceinline__ float siluf_(float x) { return x * __builtin_amdgcn_rcpf(1.0f + __expf(-x)); }
;     template <int mode> __device__ __forceinline__ void run(const f32x4 (&acc)[2][2][4][2], const Unit& u, int wr, int wc, int fr, int fq, const LAS float* sc) const {
;     ...
;             const int col0 = u.pn * HALF + wc * 32 + 8 * fq;
; #pragma unroll
;             for (int ai = 0; ai < 2; ++ai)
; #pragma unroll
;                 for (int m = 0; m < 4; ++m) {
;                     const int row = row0 + ai * HALF + m * 16;
;                     const float s = sc[ai * HALF + wr * 64 + m * 16 + fr];
;                     const f32x4 g0 = acc[ai][0][m][0] * s, u0 = acc[ai][1][m][0] * s, g1 = acc[ai][0][m][1] * s, u1 = acc[ai][1][m][1] * s;
;                     u32x4 w;
;                     w.x = pk2(siluf_(g0[0]) * u0[0], siluf_(g0[1]) * u0[1]); w.y = pk2(siluf_(g0[2]) * u0[2], siluf_(g0[3]) * u0[3]);
;                     w.z = pk2(siluf_(g1[0]) * u1[0], siluf_(g1[1]) * u1[1]); w.w = pk2(siluf_(g1[2]) * u1[2], siluf_(g1[3]) * u1[3]);
;                     *(u32x4*)(ob + (size_t)row * FF + col0) = w;
	v_pk_mul_f32 v[152:153], v[110:111], v[148:149] op_sel_hi:[1,0]
	v_pk_mul_f32 v[150:151], v[112:113], v[148:149] op_sel_hi:[1,0]
	v_pk_mul_f32 v[154:155], v[80:81], v[148:149] op_sel_hi:[1,0]
	v_pk_mul_f32 v[156:157], v[78:79], v[148:149] op_sel_hi:[1,0]
	v_pk_mul_f32 v[158:159], v[108:109], v[148:149] op_sel_hi:[1,0]
	v_pk_mul_f32 v[160:161], v[106:107], v[148:149] op_sel_hi:[1,0]
	v_pk_mul_f32 v[162:163], v[76:77], v[148:149] op_sel_hi:[1,0]
	v_pk_mul_f32 v[164:165], v[74:75], v[148:149] op_sel_hi:[1,0]
	v_mul_f32_e32 v148, 0xbfb8aa3b, v152
	v_mul_f32_e32 v149, 0xbfb8aa3b, v153
	v_exp_f32_e32 v148, v148
	v_exp_f32_e32 v149, v149
	v_add_f32_e32 v148, 1.0, v148
	v_add_f32_e32 v149, 1.0, v149
	v_rcp_f32_e32 v148, v148
	v_rcp_f32_e32 v149, v149
	v_mul_f32_e32 v148, v152, v148
	v_mul_f32_e32 v149, v153, v149
	v_mul_f32_e32 v148, v156, v148
	v_mul_f32_e32 v149, v157, v149
	v_cvt_pk_bf16_f32 v148, v148, v149
	v_mul_f32_e32 v149, 0xbfb8aa3b, v150
	v_exp_f32_e32 v149, v149
	v_mul_f32_e32 v152, 0xbfb8aa3b, v159
	v_exp_f32_e32 v152, v152
	v_add_f32_e32 v149, 1.0, v149
	v_rcp_f32_e32 v149, v149
	v_add_f32_e32 v152, 1.0, v152
	v_rcp_f32_e32 v152, v152
	v_mul_f32_e32 v149, v150, v149
	v_mul_f32_e32 v150, 0xbfb8aa3b, v151
	v_exp_f32_e32 v150, v150
	v_mul_f32_e32 v149, v154, v149
	v_mul_f32_e32 v152, v159, v152
	v_mul_f32_e32 v152, v163, v152
	v_add_f32_e32 v150, 1.0, v150
	v_rcp_f32_e32 v150, v150
	s_nop 0
	v_mul_f32_e32 v150, v151, v150
	v_mul_f32_e32 v150, v155, v150
	v_cvt_pk_bf16_f32 v149, v149, v150
	v_mul_f32_e32 v150, 0xbfb8aa3b, v160
	v_mul_f32_e32 v151, 0xbfb8aa3b, v161
	v_exp_f32_e32 v150, v150
	v_exp_f32_e32 v151, v151
	v_add_f32_e32 v150, 1.0, v150
	v_add_f32_e32 v151, 1.0, v151
	v_rcp_f32_e32 v150, v150
	v_rcp_f32_e32 v151, v151
	v_mul_f32_e32 v150, v160, v150
	v_mul_f32_e32 v151, v161, v151
	v_mul_f32_e32 v150, v164, v150
	v_mul_f32_e32 v151, v165, v151
	v_cvt_pk_bf16_f32 v150, v150, v151
	v_mul_f32_e32 v151, 0xbfb8aa3b, v158
	v_exp_f32_e32 v151, v151
	s_nop 0
	v_add_f32_e32 v151, 1.0, v151
	v_rcp_f32_e32 v151, v151
	s_nop 0
	v_mul_f32_e32 v151, v158, v151
	v_mul_f32_e32 v151, v162, v151
	v_cvt_pk_bf16_f32 v151, v151, v152
	v_mad_i64_i32 v[152:153], s[4:5], v147, s33, v[136:137]
	v_lshl_add_u64 v[152:153], v[152:153], 0, v[138:139]
	global_store_dwordx4 v[152:153], v[148:151], off
	ds_read_b32 v148, v145 offset:192
	v_or_b32_e32 v147, 48, v146
	s_waitcnt lgkmcnt(0)
	v_pk_mul_f32 v[152:153], v[102:103], v[148:149] op_sel_hi:[1,0]
	v_pk_mul_f32 v[150:151], v[104:105], v[148:149] op_sel_hi:[1,0]
	v_pk_mul_f32 v[154:155], v[72:73], v[148:149] op_sel_hi:[1,0]
	v_pk_mul_f32 v[156:157], v[70:71], v[148:149] op_sel_hi:[1,0]
	v_pk_mul_f32 v[158:159], v[100:101], v[148:149] op_sel_hi:[1,0]
	v_pk_mul_f32 v[160:161], v[98:99], v[148:149] op_sel_hi:[1,0]
	v_pk_mul_f32 v[162:163], v[68:69], v[148:149] op_sel_hi:[1,0]
	v_pk_mul_f32 v[164:165], v[66:67], v[148:149] op_sel_hi:[1,0]
	v_mul_f32_e32 v148, 0xbfb8aa3b, v152
	v_mul_f32_e32 v149, 0xbfb8aa3b, v153
	v_exp_f32_e32 v148, v148
	v_exp_f32_e32 v149, v149
	v_add_f32_e32 v148, 1.0, v148
	v_add_f32_e32 v149, 1.0, v149
	v_rcp_f32_e32 v148, v148
	v_rcp_f32_e32 v149, v149
	v_mul_f32_e32 v148, v152, v148
	v_mul_f32_e32 v149, v153, v149
	v_mul_f32_e32 v148, v156, v148
	v_mul_f32_e32 v149, v157, v149
	v_cvt_pk_bf16_f32 v148, v148, v149
	v_mul_f32_e32 v149, 0xbfb8aa3b, v150
	v_exp_f32_e32 v149, v149
	v_mul_f32_e32 v152, 0xbfb8aa3b, v159
	v_exp_f32_e32 v152, v152
	v_add_f32_e32 v149, 1.0, v149
	v_rcp_f32_e32 v149, v149
	v_add_f32_e32 v152, 1.0, v152
	v_rcp_f32_e32 v152, v152
	v_mul_f32_e32 v149, v150, v149
	v_mul_f32_e32 v150, 0xbfb8aa3b, v151
	v_exp_f32_e32 v150, v150
	v_mul_f32_e32 v149, v154, v149
	v_mul_f32_e32 v152, v159, v152
	v_mul_f32_e32 v152, v163, v152
	v_add_f32_e32 v150, 1.0, v150
	v_rcp_f32_e32 v150, v150
	s_nop 0
	v_mul_f32_e32 v150, v151, v150
	v_mul_f32_e32 v150, v155, v150
	v_cvt_pk_bf16_f32 v149, v149, v150
	v_mul_f32_e32 v150, 0xbfb8aa3b, v160
	v_mul_f32_e32 v151, 0xbfb8aa3b, v161
	v_exp_f32_e32 v150, v150
	v_exp_f32_e32 v151, v151
	v_add_f32_e32 v150, 1.0, v150
	v_add_f32_e32 v151, 1.0, v151
	v_rcp_f32_e32 v150, v150
	v_rcp_f32_e32 v151, v151
	v_mul_f32_e32 v150, v160, v150
	v_mul_f32_e32 v151, v161, v151
	v_mul_f32_e32 v150, v164, v150
	v_mul_f32_e32 v151, v165, v151
	v_cvt_pk_bf16_f32 v150, v150, v151
	v_mul_f32_e32 v151, 0xbfb8aa3b, v158
	v_exp_f32_e32 v151, v151
	s_nop 0
	v_add_f32_e32 v151, 1.0, v151
	v_rcp_f32_e32 v151, v151
	s_nop 0
	v_mul_f32_e32 v151, v158, v151
	v_mul_f32_e32 v151, v162, v151
	v_cvt_pk_bf16_f32 v151, v151, v152
	v_mad_i64_i32 v[152:153], s[4:5], v147, s33, v[136:137]
	v_lshl_add_u64 v[152:153], v[152:153], 0, v[138:139]
	global_store_dwordx4 v[152:153], v[148:151], off
	ds_read_b32 v148, v145 offset:512
	v_add_u32_e32 v147, 0x80, v146
	s_waitcnt lgkmcnt(0)
; __device__ __forceinline__ unsigned pk2(float lo, float hi) { unsigned r; asm volatile("v_cvt_pk_bf16_f32 %0, %1, %2" : "=v"(r) : "v"(lo), "v"(hi)); return r; }
; __device__ __forceinline__ float siluf_(float x) { return x * __builtin_amdgcn_rcpf(1.0f + __expf(-x)); }
;     template <int mode> __device__ __forceinline__ void run(const f32x4 (&acc)[2][2][4][2], const Unit& u, int wr, int wc, int fr, int fq, const LAS float* sc) const {
;     ...
;             const int col0 = u.pn * HALF + wc * 32 + 8 * fq;
; #pragma unroll
;             for (int ai = 0; ai < 2; ++ai)
; #pragma unroll
;                 for (int m = 0; m < 4; ++m) {
;                     const int row = row0 + ai * HALF + m * 16;
;                     const float s = sc[ai * HALF + wr * 64 + m * 16 + fr];
;                     const f32x4 g0 = acc[ai][0][m][0] * s, u0 = acc[ai][1][m][0] * s, g1 = acc[ai][0][m][1] * s, u1 = acc[ai][1][m][1] * s;
;                     u32x4 w;
;                     w.x = pk2(siluf_(g0[0]) * u0[0], siluf_(g0[1]) * u0[1]); w.y = pk2(siluf_(g0[2]) * u0[2], siluf_(g0[3]) * u0[3]);
;                     w.z = pk2(siluf_(g1[0]) * u1[0], siluf_(g1[1]) * u1[1]); w.w = pk2(siluf_(g1[2]) * u1[2], siluf_(g1[3]) * u1[3]);
;                     *(u32x4*)(ob + (size_t)row * FF + col0) = w;
	v_pk_mul_f32 v[152:153], v[62:63], v[148:149] op_sel_hi:[1,0]
	v_pk_mul_f32 v[150:151], v[64:65], v[148:149] op_sel_hi:[1,0]
	v_pk_mul_f32 v[154:155], v[32:33], v[148:149] op_sel_hi:[1,0]
	v_pk_mul_f32 v[156:157], v[30:31], v[148:149] op_sel_hi:[1,0]
	v_pk_mul_f32 v[158:159], v[60:61], v[148:149] op_sel_hi:[1,0]
	v_pk_mul_f32 v[160:161], v[58:59], v[148:149] op_sel_hi:[1,0]
	v_pk_mul_f32 v[162:163], v[28:29], v[148:149] op_sel_hi:[1,0]
	v_pk_mul_f32 v[164:165], v[26:27], v[148:149] op_sel_hi:[1,0]
	v_mul_f32_e32 v148, 0xbfb8aa3b, v152
	v_mul_f32_e32 v149, 0xbfb8aa3b, v153
	v_exp_f32_e32 v148, v148
	v_exp_f32_e32 v149, v149
	v_add_f32_e32 v148, 1.0, v148
	v_add_f32_e32 v149, 1.0, v149
	v_rcp_f32_e32 v148, v148
	v_rcp_f32_e32 v149, v149
	v_mul_f32_e32 v148, v152, v148
	v_mul_f32_e32 v149, v153, v149
	v_mul_f32_e32 v148, v156, v148
	v_mul_f32_e32 v149, v157, v149
	v_cvt_pk_bf16_f32 v148, v148, v149
	v_mul_f32_e32 v149, 0xbfb8aa3b, v150
	v_exp_f32_e32 v149, v149
	v_mul_f32_e32 v152, 0xbfb8aa3b, v159
	v_exp_f32_e32 v152, v152
	v_add_f32_e32 v149, 1.0, v149
	v_rcp_f32_e32 v149, v149
	v_add_f32_e32 v152, 1.0, v152
	v_rcp_f32_e32 v152, v152
	v_mul_f32_e32 v149, v150, v149
	v_mul_f32_e32 v150, 0xbfb8aa3b, v151
	v_exp_f32_e32 v150, v150
	v_mul_f32_e32 v149, v154, v149
	v_mul_f32_e32 v152, v159, v152
	v_mul_f32_e32 v152, v163, v152
	v_add_f32_e32 v150, 1.0, v150
	v_rcp_f32_e32 v150, v150
	s_nop 0
	v_mul_f32_e32 v150, v151, v150
	v_mul_f32_e32 v150, v155, v150
	v_cvt_pk_bf16_f32 v149, v149, v150
	v_mul_f32_e32 v150, 0xbfb8aa3b, v160
	v_mul_f32_e32 v151, 0xbfb8aa3b, v161
	v_exp_f32_e32 v150, v150
	v_exp_f32_e32 v151, v151
	v_add_f32_e32 v150, 1.0, v150
	v_add_f32_e32 v151, 1.0, v151
	v_rcp_f32_e32 v150, v150
	v_rcp_f32_e32 v151, v151
	v_mul_f32_e32 v150, v160, v150
	v_mul_f32_e32 v151, v161, v151
	v_mul_f32_e32 v150, v164, v150
	v_mul_f32_e32 v151, v165, v151
	v_cvt_pk_bf16_f32 v150, v150, v151
	v_mul_f32_e32 v151, 0xbfb8aa3b, v158
	v_exp_f32_e32 v151, v151
	s_nop 0
	v_add_f32_e32 v151, 1.0, v151
	v_rcp_f32_e32 v151, v151
	s_nop 0
	v_mul_f32_e32 v151, v158, v151
	v_mul_f32_e32 v151, v162, v151
	v_cvt_pk_bf16_f32 v151, v151, v152
	v_mad_i64_i32 v[152:153], s[4:5], v147, s33, v[136:137]
	v_lshl_add_u64 v[152:153], v[152:153], 0, v[138:139]
	global_store_dwordx4 v[152:153], v[148:151], off
	ds_read_b32 v148, v145 offset:576
	v_add_u32_e32 v147, 0x90, v146
	s_waitcnt lgkmcnt(0)
	v_pk_mul_f32 v[152:153], v[54:55], v[148:149] op_sel_hi:[1,0]
	v_pk_mul_f32 v[150:151], v[56:57], v[148:149] op_sel_hi:[1,0]
	v_pk_mul_f32 v[154:155], v[24:25], v[148:149] op_sel_hi:[1,0]
	v_pk_mul_f32 v[156:157], v[22:23], v[148:149] op_sel_hi:[1,0]
	v_pk_mul_f32 v[158:159], v[52:53], v[148:149] op_sel_hi:[1,0]
	v_pk_mul_f32 v[160:161], v[50:51], v[148:149] op_sel_hi:[1,0]
	v_pk_mul_f32 v[162:163], v[20:21], v[148:149] op_sel_hi:[1,0]
	v_pk_mul_f32 v[164:165], v[18:19], v[148:149] op_sel_hi:[1,0]
	v_mul_f32_e32 v148, 0xbfb8aa3b, v152
	v_mul_f32_e32 v149, 0xbfb8aa3b, v153
	v_exp_f32_e32 v148, v148
	v_exp_f32_e32 v149, v149
	v_add_f32_e32 v148, 1.0, v148
	v_add_f32_e32 v149, 1.0, v149
	v_rcp_f32_e32 v148, v148
	v_rcp_f32_e32 v149, v149
	v_mul_f32_e32 v148, v152, v148
	v_mul_f32_e32 v149, v153, v149
	v_mul_f32_e32 v148, v156, v148
	v_mul_f32_e32 v149, v157, v149
	v_cvt_pk_bf16_f32 v148, v148, v149
	v_mul_f32_e32 v149, 0xbfb8aa3b, v150
	v_exp_f32_e32 v149, v149
	v_mul_f32_e32 v152, 0xbfb8aa3b, v159
	v_exp_f32_e32 v152, v152
	v_add_f32_e32 v149, 1.0, v149
	v_rcp_f32_e32 v149, v149
	v_add_f32_e32 v152, 1.0, v152
	v_rcp_f32_e32 v152, v152
	v_mul_f32_e32 v149, v150, v149
	v_mul_f32_e32 v150, 0xbfb8aa3b, v151
	v_exp_f32_e32 v150, v150
	v_mul_f32_e32 v149, v154, v149
	v_mul_f32_e32 v152, v159, v152
	v_mul_f32_e32 v152, v163, v152
	v_add_f32_e32 v150, 1.0, v150
	v_rcp_f32_e32 v150, v150
	s_nop 0
	v_mul_f32_e32 v150, v151, v150
	v_mul_f32_e32 v150, v155, v150
	v_cvt_pk_bf16_f32 v149, v149, v150
	v_mul_f32_e32 v150, 0xbfb8aa3b, v160
	v_mul_f32_e32 v151, 0xbfb8aa3b, v161
	v_exp_f32_e32 v150, v150
	v_exp_f32_e32 v151, v151
	v_add_f32_e32 v150, 1.0, v150
	v_add_f32_e32 v151, 1.0, v151
	v_rcp_f32_e32 v150, v150
	v_rcp_f32_e32 v151, v151
	v_mul_f32_e32 v150, v160, v150
	v_mul_f32_e32 v151, v161, v151
	v_mul_f32_e32 v150, v164, v150
	v_mul_f32_e32 v151, v165, v151
	v_cvt_pk_bf16_f32 v150, v150, v151
	v_mul_f32_e32 v151, 0xbfb8aa3b, v158
	v_exp_f32_e32 v151, v151
	s_nop 0
	v_add_f32_e32 v151, 1.0, v151
	v_rcp_f32_e32 v151, v151
	s_nop 0
	v_mul_f32_e32 v151, v158, v151
	v_mul_f32_e32 v151, v162, v151
	v_cvt_pk_bf16_f32 v151, v151, v152
	v_mad_i64_i32 v[152:153], s[4:5], v147, s33, v[136:137]
	v_lshl_add_u64 v[152:153], v[152:153], 0, v[138:139]
	global_store_dwordx4 v[152:153], v[148:151], off
	ds_read_b32 v148, v145 offset:640
	v_add_u32_e32 v147, 0xa0, v146
	s_waitcnt lgkmcnt(0)
; __device__ __forceinline__ unsigned pk2(float lo, float hi) { unsigned r; asm volatile("v_cvt_pk_bf16_f32 %0, %1, %2" : "=v"(r) : "v"(lo), "v"(hi)); return r; }
; __device__ __forceinline__ float siluf_(float x) { return x * __builtin_amdgcn_rcpf(1.0f + __expf(-x)); }
;     template <int mode> __device__ __forceinline__ void run(const f32x4 (&acc)[2][2][4][2], const Unit& u, int wr, int wc, int fr, int fq, const LAS float* sc) const {
;     ...
;             const int col0 = u.pn * HALF + wc * 32 + 8 * fq;
; #pragma unroll
;             for (int ai = 0; ai < 2; ++ai)
; #pragma unroll
;                 for (int m = 0; m < 4; ++m) {
;                     const int row = row0 + ai * HALF + m * 16;
;                     const float s = sc[ai * HALF + wr * 64 + m * 16 + fr];
;                     const f32x4 g0 = acc[ai][0][m][0] * s, u0 = acc[ai][1][m][0] * s, g1 = acc[ai][0][m][1] * s, u1 = acc[ai][1][m][1] * s;
;                     u32x4 w;
;                     w.x = pk2(siluf_(g0[0]) * u0[0], siluf_(g0[1]) * u0[1]); w.y = pk2(siluf_(g0[2]) * u0[2], siluf_(g0[3]) * u0[3]);
;                     w.z = pk2(siluf_(g1[0]) * u1[0], siluf_(g1[1]) * u1[1]); w.w = pk2(siluf_(g1[2]) * u1[2], siluf_(g1[3]) * u1[3]);
;                     *(u32x4*)(ob + (size_t)row * FF + col0) = w;
	v_pk_mul_f32 v[152:153], v[46:47], v[148:149] op_sel_hi:[1,0]
	v_pk_mul_f32 v[150:151], v[48:49], v[148:149] op_sel_hi:[1,0]
	v_pk_mul_f32 v[154:155], v[16:17], v[148:149] op_sel_hi:[1,0]
	v_pk_mul_f32 v[156:157], v[14:15], v[148:149] op_sel_hi:[1,0]
	v_pk_mul_f32 v[158:159], v[44:45], v[148:149] op_sel_hi:[1,0]
	v_pk_mul_f32 v[160:161], v[42:43], v[148:149] op_sel_hi:[1,0]
	v_pk_mul_f32 v[162:163], v[12:13], v[148:149] op_sel_hi:[1,0]
	v_pk_mul_f32 v[164:165], v[10:11], v[148:149] op_sel_hi:[1,0]
	v_mul_f32_e32 v148, 0xbfb8aa3b, v152
	v_mul_f32_e32 v149, 0xbfb8aa3b, v153
	v_exp_f32_e32 v148, v148
	v_exp_f32_e32 v149, v149
	v_add_f32_e32 v148, 1.0, v148
	v_add_f32_e32 v149, 1.0, v149
	v_rcp_f32_e32 v148, v148
	v_rcp_f32_e32 v149, v149
	v_mul_f32_e32 v148, v152, v148
	v_mul_f32_e32 v149, v153, v149
	v_mul_f32_e32 v148, v156, v148
	v_mul_f32_e32 v149, v157, v149
	v_cvt_pk_bf16_f32 v148, v148, v149
	v_mul_f32_e32 v149, 0xbfb8aa3b, v150
	v_exp_f32_e32 v149, v149
	v_mul_f32_e32 v152, 0xbfb8aa3b, v159
	v_exp_f32_e32 v152, v152
	v_add_f32_e32 v149, 1.0, v149
	v_rcp_f32_e32 v149, v149
	v_add_f32_e32 v152, 1.0, v152
	v_rcp_f32_e32 v152, v152
	v_mul_f32_e32 v149, v150, v149
	v_mul_f32_e32 v150, 0xbfb8aa3b, v151
	v_exp_f32_e32 v150, v150
	v_mul_f32_e32 v149, v154, v149
	v_mul_f32_e32 v152, v159, v152
	v_mul_f32_e32 v152, v163, v152
	v_add_f32_e32 v150, 1.0, v150
	v_rcp_f32_e32 v150, v150
	s_nop 0
	v_mul_f32_e32 v150, v151, v150
	v_mul_f32_e32 v150, v155, v150
	v_cvt_pk_bf16_f32 v149, v149, v150
	v_mul_f32_e32 v150, 0xbfb8aa3b, v160
	v_mul_f32_e32 v151, 0xbfb8aa3b, v161
	v_exp_f32_e32 v150, v150
	v_exp_f32_e32 v151, v151
	v_add_f32_e32 v150, 1.0, v150
	v_add_f32_e32 v151, 1.0, v151
	v_rcp_f32_e32 v150, v150
	v_rcp_f32_e32 v151, v151
	v_mul_f32_e32 v150, v160, v150
	v_mul_f32_e32 v151, v161, v151
	v_mul_f32_e32 v150, v164, v150
	v_mul_f32_e32 v151, v165, v151
	v_cvt_pk_bf16_f32 v150, v150, v151
	v_mul_f32_e32 v151, 0xbfb8aa3b, v158
	v_exp_f32_e32 v151, v151
	v_add_u32_e32 v164, 0xb0, v146
	v_add_f32_e32 v151, 1.0, v151
	v_rcp_f32_e32 v151, v151
	s_nop 0
	v_mul_f32_e32 v151, v158, v151
	v_mul_f32_e32 v151, v162, v151
	v_cvt_pk_bf16_f32 v151, v151, v152
	ds_read_b32 v146, v145 offset:704
	v_mad_i64_i32 v[152:153], s[4:5], v147, s33, v[136:137]
	v_lshl_add_u64 v[152:153], v[152:153], 0, v[138:139]
	global_store_dwordx4 v[152:153], v[148:151], off
	s_waitcnt lgkmcnt(0)
	v_pk_mul_f32 v[152:153], v[8:9], v[146:147] op_sel_hi:[1,0]
	v_pk_mul_f32 v[154:155], v[6:7], v[146:147] op_sel_hi:[1,0]
	v_pk_mul_f32 v[150:151], v[38:39], v[146:147] op_sel_hi:[1,0]
	v_pk_mul_f32 v[148:149], v[40:41], v[146:147] op_sel_hi:[1,0]
	v_pk_mul_f32 v[156:157], v[36:37], v[146:147] op_sel_hi:[1,0]
	v_pk_mul_f32 v[158:159], v[34:35], v[146:147] op_sel_hi:[1,0]
	v_pk_mul_f32 v[160:161], v[4:5], v[146:147] op_sel_hi:[1,0]
	v_pk_mul_f32 v[162:163], v[2:3], v[146:147] op_sel_hi:[1,0]
	v_mul_f32_e32 v145, 0xbfb8aa3b, v150
	v_mul_f32_e32 v146, 0xbfb8aa3b, v151
	v_exp_f32_e32 v145, v145
	v_exp_f32_e32 v146, v146
	v_mul_f32_e32 v147, 0xbfb8aa3b, v149
	v_exp_f32_e32 v147, v147
	v_add_f32_e32 v145, 1.0, v145
	v_add_f32_e32 v146, 1.0, v146
	v_rcp_f32_e32 v145, v145
	v_rcp_f32_e32 v146, v146
	v_add_f32_e32 v147, 1.0, v147
	v_rcp_f32_e32 v147, v147
	v_mul_f32_e32 v145, v150, v145
	v_mul_f32_e32 v146, v151, v146
	v_mul_f32_e32 v145, v154, v145
	v_mul_f32_e32 v146, v155, v146
	v_cvt_pk_bf16_f32 v146, v145, v146
	v_mul_f32_e32 v145, 0xbfb8aa3b, v148
	v_exp_f32_e32 v145, v145
	v_mul_f32_e32 v147, v149, v147
	v_mul_f32_e32 v147, v153, v147
	v_mul_f32_e32 v149, 0xbfb8aa3b, v157
	v_add_f32_e32 v145, 1.0, v145
	v_rcp_f32_e32 v145, v145
	v_exp_f32_e32 v149, v149
	v_mad_i64_i32 v[136:137], s[4:5], v164, s33, v[136:137]
	v_mul_f32_e32 v145, v148, v145
	v_mul_f32_e32 v145, v152, v145
	v_cvt_pk_bf16_f32 v147, v145, v147
	v_mul_f32_e32 v145, 0xbfb8aa3b, v158
	v_mul_f32_e32 v148, 0xbfb8aa3b, v159
	v_exp_f32_e32 v145, v145
	v_exp_f32_e32 v148, v148
	v_add_f32_e32 v149, 1.0, v149
	v_rcp_f32_e32 v149, v149
	v_add_f32_e32 v145, 1.0, v145
	v_add_f32_e32 v148, 1.0, v148
	v_rcp_f32_e32 v145, v145
	v_rcp_f32_e32 v148, v148
	v_mul_f32_e32 v149, v157, v149
	v_mul_f32_e32 v149, v161, v149
	v_mul_f32_e32 v145, v158, v145
	v_mul_f32_e32 v148, v159, v148
	v_mul_f32_e32 v145, v162, v145
	v_mul_f32_e32 v148, v163, v148
	v_cvt_pk_bf16_f32 v148, v145, v148
	v_mul_f32_e32 v145, 0xbfb8aa3b, v156
	v_exp_f32_e32 v145, v145
	v_lshl_add_u64 v[136:137], v[136:137], 0, v[138:139]
	v_add_f32_e32 v145, 1.0, v145
	v_rcp_f32_e32 v145, v145
	s_nop 0
	v_mul_f32_e32 v145, v156, v145
	v_mul_f32_e32 v145, v160, v145
	v_cvt_pk_bf16_f32 v149, v145, v149
	global_store_dwordx4 v[136:137], v[146:149], off
	s_cbranch_vccnz .LBB0_324
; template <int MODE, class EpiT, class Sched>
; __device__ __forceinline__ void gemm_phase(LAS unsigned char* lds, const Gemm g, const Sched& S, const EpiT& E) {
;     ...
; #pragma unroll
;         for (int a = 0; a < 2; ++a)
; #pragma unroll
;             for (int b = 0; b < 2; ++b)
; #pragma unroll
;                 for (int m = 0; m < 4; ++m)
; #pragma unroll
;                     for (int n = 0; n < 2; ++n) acc[a][b][m][n] = (f32x4){0.f, 0.f, 0.f, 0.f};
;         cur = nxt; cA = nA; cB = nB; ++ui;
	v_mov_b32_e32 v2, 0
	s_mov_b32 s9, s61
	s_mov_b32 s8, s60
	s_mov_b64 s[12:13], s[28:29]
	s_mov_b64 s[10:11], s[34:35]
	s_mov_b32 s57, s2
	v_mov_b32_e32 v3, v2
	v_mov_b32_e32 v4, v2
	v_mov_b32_e32 v5, v2
	v_mov_b32_e32 v6, v2
	v_mov_b32_e32 v7, v2
	v_mov_b32_e32 v8, v2
	v_mov_b32_e32 v9, v2
	v_mov_b32_e32 v10, v2
	v_mov_b32_e32 v11, v2
	v_mov_b32_e32 v12, v2
	v_mov_b32_e32 v13, v2
	v_mov_b32_e32 v14, v2
	v_mov_b32_e32 v15, v2
	v_mov_b32_e32 v16, v2
	v_mov_b32_e32 v17, v2
	v_mov_b32_e32 v18, v2
	v_mov_b32_e32 v19, v2
	v_mov_b32_e32 v20, v2
	v_mov_b32_e32 v21, v2
	v_mov_b32_e32 v22, v2
	v_mov_b32_e32 v23, v2
	v_mov_b32_e32 v24, v2
	v_mov_b32_e32 v25, v2
	v_mov_b32_e32 v26, v2
	v_mov_b32_e32 v27, v2
	v_mov_b32_e32 v28, v2
	v_mov_b32_e32 v29, v2
	v_mov_b32_e32 v30, v2
	v_mov_b32_e32 v31, v2
	v_mov_b32_e32 v32, v2
	v_mov_b32_e32 v33, v2
	v_mov_b32_e32 v34, v2
	v_mov_b32_e32 v35, v2
	v_mov_b32_e32 v36, v2
	v_mov_b32_e32 v37, v2
	v_mov_b32_e32 v38, v2
	v_mov_b32_e32 v39, v2
	v_mov_b32_e32 v40, v2
	v_mov_b32_e32 v41, v2
	v_mov_b32_e32 v42, v2
	v_mov_b32_e32 v43, v2
	v_mov_b32_e32 v44, v2
	v_mov_b32_e32 v45, v2
	v_mov_b32_e32 v46, v2
	v_mov_b32_e32 v47, v2
	v_mov_b32_e32 v48, v2
	v_mov_b32_e32 v49, v2
	v_mov_b32_e32 v50, v2
	v_mov_b32_e32 v51, v2
	v_mov_b32_e32 v52, v2
	v_mov_b32_e32 v53, v2
	v_mov_b32_e32 v54, v2
	v_mov_b32_e32 v55, v2
	v_mov_b32_e32 v56, v2
	v_mov_b32_e32 v57, v2
	v_mov_b32_e32 v58, v2
	v_mov_b32_e32 v59, v2
	v_mov_b32_e32 v60, v2
	v_mov_b32_e32 v61, v2
	v_mov_b32_e32 v62, v2
	v_mov_b32_e32 v63, v2
	v_mov_b32_e32 v64, v2
	v_mov_b32_e32 v65, v2
	v_mov_b32_e32 v66, v2
	v_mov_b32_e32 v67, v2
	v_mov_b32_e32 v68, v2
	v_mov_b32_e32 v69, v2
	v_mov_b32_e32 v70, v2
	v_mov_b32_e32 v71, v2
	v_mov_b32_e32 v72, v2
	v_mov_b32_e32 v73, v2
	v_mov_b32_e32 v74, v2
	v_mov_b32_e32 v75, v2
	v_mov_b32_e32 v76, v2
	v_mov_b32_e32 v77, v2
	v_mov_b32_e32 v78, v2
	v_mov_b32_e32 v79, v2
	v_mov_b32_e32 v80, v2
	v_mov_b32_e32 v81, v2
	v_mov_b32_e32 v82, v2
	v_mov_b32_e32 v83, v2
	v_mov_b32_e32 v84, v2
	v_mov_b32_e32 v85, v2
	v_mov_b32_e32 v86, v2
	v_mov_b32_e32 v87, v2
	v_mov_b32_e32 v88, v2
	v_mov_b32_e32 v89, v2
	v_mov_b32_e32 v90, v2
	v_mov_b32_e32 v91, v2
	v_mov_b32_e32 v92, v2
	v_mov_b32_e32 v93, v2
	v_mov_b32_e32 v94, v2
	v_mov_b32_e32 v95, v2
	v_mov_b32_e32 v96, v2
	v_mov_b32_e32 v97, v2
	v_mov_b32_e32 v98, v2
	v_mov_b32_e32 v99, v2
	v_mov_b32_e32 v100, v2
	v_mov_b32_e32 v101, v2
	v_mov_b32_e32 v102, v2
	v_mov_b32_e32 v103, v2
	v_mov_b32_e32 v104, v2
	v_mov_b32_e32 v105, v2
	v_mov_b32_e32 v106, v2
	v_mov_b32_e32 v107, v2
	v_mov_b32_e32 v108, v2
	v_mov_b32_e32 v109, v2
	v_mov_b32_e32 v110, v2
	v_mov_b32_e32 v111, v2
	v_mov_b32_e32 v112, v2
	v_mov_b32_e32 v113, v2
	v_mov_b32_e32 v114, v2
	v_mov_b32_e32 v115, v2
	v_mov_b32_e32 v116, v2
	v_mov_b32_e32 v117, v2
	v_mov_b32_e32 v118, v2
	v_mov_b32_e32 v119, v2
	v_mov_b32_e32 v120, v2
	v_mov_b32_e32 v121, v2
	v_mov_b32_e32 v122, v2
	v_mov_b32_e32 v123, v2
	v_mov_b32_e32 v124, v2
	v_mov_b32_e32 v125, v2
	v_mov_b32_e32 v126, v2
	v_mov_b32_e32 v127, v2
	v_mov_b32_e32 v128, v2
	v_mov_b32_e32 v129, v2
	s_branch .LBB0_324
